# up epilogue trimmed (conv taps staged by LDS-DMA, packed gelu), first k-step uses C=0, s_setprio 1 around each k-step MFMA block
# speedup vs baseline: 1.0642x; 1.0126x over previous
.Lgy_nn_a:
	s_waitcnt vmcnt(6) lgkmcnt(0)
	s_barrier
	v_add_u32_e32 v240, s61, v238
	v_add_u32_e32 v241, s61, v239
	s_setprio 1
	s_add_i32 m0, s60, s62
	v_mfma_f32_16x16x32_bf16 v[2:5], v[162:165], v[130:133], 0
	global_load_lds_dwordx4 v226, s[54:55]
	v_mfma_f32_16x16x32_bf16 v[6:9], v[166:169], v[130:133], 0
	global_load_lds_dwordx4 v226, s[54:55] offset:1024
	v_mfma_f32_16x16x32_bf16 v[10:13], v[170:173], v[130:133], 0
	global_load_lds_dwordx4 v226, s[54:55] offset:2048
	v_mfma_f32_16x16x32_bf16 v[14:17], v[174:177], v[130:133], 0
	global_load_lds_dwordx4 v226, s[54:55] offset:3072
	s_add_i32 m0, s60, s63
	v_mfma_f32_16x16x32_bf16 v[18:21], v[162:165], v[134:137], 0
	global_load_lds_dwordx4 v230, s[56:57]
	v_mfma_f32_16x16x32_bf16 v[22:25], v[166:169], v[134:137], 0
	global_load_lds_dwordx4 v231, s[56:57] offset:1024
	v_mfma_f32_16x16x32_bf16 v[26:29], v[170:173], v[134:137], 0
	v_mfma_f32_16x16x32_bf16 v[30:33], v[174:177], v[134:137], 0
	v_mfma_f32_16x16x32_bf16 v[34:37], v[162:165], v[138:141], 0
	ds_read_b128 v[210:213], v241 offset:0
	v_mfma_f32_16x16x32_bf16 v[38:41], v[166:169], v[138:141], 0
	ds_read_b128 v[214:217], v241 offset:256
	v_mfma_f32_16x16x32_bf16 v[42:45], v[170:173], v[138:141], 0
	ds_read_b128 v[218:221], v241 offset:512
	v_mfma_f32_16x16x32_bf16 v[46:49], v[174:177], v[138:141], 0
	ds_read_b128 v[222:225], v241 offset:768
	v_mfma_f32_16x16x32_bf16 v[50:53], v[162:165], v[142:145], 0
	ds_read_b128 v[178:181], v240 offset:0
	v_mfma_f32_16x16x32_bf16 v[54:57], v[166:169], v[142:145], 0
	ds_read_b128 v[182:185], v240 offset:1024
	v_mfma_f32_16x16x32_bf16 v[58:61], v[170:173], v[142:145], 0
	ds_read_b128 v[186:189], v240 offset:2048
	v_mfma_f32_16x16x32_bf16 v[62:65], v[174:177], v[142:145], 0
	ds_read_b128 v[190:193], v240 offset:3072
	v_mfma_f32_16x16x32_bf16 v[66:69], v[162:165], v[146:149], 0
	ds_read_b128 v[194:197], v240 offset:4096
	v_mfma_f32_16x16x32_bf16 v[70:73], v[166:169], v[146:149], 0
	ds_read_b128 v[198:201], v240 offset:5120
	v_mfma_f32_16x16x32_bf16 v[74:77], v[170:173], v[146:149], 0
	ds_read_b128 v[202:205], v240 offset:6144
	v_mfma_f32_16x16x32_bf16 v[78:81], v[174:177], v[146:149], 0
	ds_read_b128 v[206:209], v240 offset:7168
	v_mfma_f32_16x16x32_bf16 v[82:85], v[162:165], v[150:153], 0
	v_mfma_f32_16x16x32_bf16 v[86:89], v[166:169], v[150:153], 0
	v_mfma_f32_16x16x32_bf16 v[90:93], v[170:173], v[150:153], 0
	v_mfma_f32_16x16x32_bf16 v[94:97], v[174:177], v[150:153], 0
	v_mfma_f32_16x16x32_bf16 v[98:101], v[162:165], v[154:157], 0
	v_mfma_f32_16x16x32_bf16 v[102:105], v[166:169], v[154:157], 0
	v_mfma_f32_16x16x32_bf16 v[106:109], v[170:173], v[154:157], 0
	v_mfma_f32_16x16x32_bf16 v[110:113], v[174:177], v[154:157], 0
	v_mfma_f32_16x16x32_bf16 v[114:117], v[162:165], v[158:161], 0
	v_mfma_f32_16x16x32_bf16 v[118:121], v[166:169], v[158:161], 0
	v_mfma_f32_16x16x32_bf16 v[122:125], v[170:173], v[158:161], 0
	v_mfma_f32_16x16x32_bf16 v[126:129], v[174:177], v[158:161], 0
	s_setprio 0
	s_add_i32 s60, s60, 0x6000
	s_cmp_eq_u32 s60, 0x12000
	s_cselect_b32 s60, 0, s60
	s_add_u32 s54, s54, s72
	s_addc_u32 s55, s55, 0
	s_add_u32 s56, s56, s73
	s_addc_u32 s57, s57, 0
	s_add_i32 s61, s61, 0x6000
	s_cmp_eq_u32 s61, 0x12000
	s_cselect_b32 s61, 0, s61
	s_waitcnt vmcnt(6) lgkmcnt(0)
	s_barrier
	v_add_u32_e32 v240, s61, v238
	v_add_u32_e32 v241, s61, v239
	s_setprio 1
	s_add_i32 m0, s60, s62
	v_mfma_f32_16x16x32_bf16 v[2:5], v[210:213], v[178:181], v[2:5]
	global_load_lds_dwordx4 v226, s[54:55]
	v_mfma_f32_16x16x32_bf16 v[6:9], v[214:217], v[178:181], v[6:9]
	global_load_lds_dwordx4 v226, s[54:55] offset:1024
	v_mfma_f32_16x16x32_bf16 v[10:13], v[218:221], v[178:181], v[10:13]
	global_load_lds_dwordx4 v226, s[54:55] offset:2048
	v_mfma_f32_16x16x32_bf16 v[14:17], v[222:225], v[178:181], v[14:17]
	global_load_lds_dwordx4 v226, s[54:55] offset:3072
	s_add_i32 m0, s60, s63
	v_mfma_f32_16x16x32_bf16 v[18:21], v[210:213], v[182:185], v[18:21]
	global_load_lds_dwordx4 v230, s[56:57]
	v_mfma_f32_16x16x32_bf16 v[22:25], v[214:217], v[182:185], v[22:25]
	global_load_lds_dwordx4 v231, s[56:57] offset:1024
	v_mfma_f32_16x16x32_bf16 v[26:29], v[218:221], v[182:185], v[26:29]
	v_mfma_f32_16x16x32_bf16 v[30:33], v[222:225], v[182:185], v[30:33]
	v_mfma_f32_16x16x32_bf16 v[34:37], v[210:213], v[186:189], v[34:37]
	ds_read_b128 v[162:165], v241 offset:0
	v_mfma_f32_16x16x32_bf16 v[38:41], v[214:217], v[186:189], v[38:41]
	ds_read_b128 v[166:169], v241 offset:256
	v_mfma_f32_16x16x32_bf16 v[42:45], v[218:221], v[186:189], v[42:45]
	ds_read_b128 v[170:173], v241 offset:512
	v_mfma_f32_16x16x32_bf16 v[46:49], v[222:225], v[186:189], v[46:49]
	ds_read_b128 v[174:177], v241 offset:768
	v_mfma_f32_16x16x32_bf16 v[50:53], v[210:213], v[190:193], v[50:53]
	ds_read_b128 v[130:133], v240 offset:0
	v_mfma_f32_16x16x32_bf16 v[54:57], v[214:217], v[190:193], v[54:57]
	ds_read_b128 v[134:137], v240 offset:1024
	v_mfma_f32_16x16x32_bf16 v[58:61], v[218:221], v[190:193], v[58:61]
	ds_read_b128 v[138:141], v240 offset:2048
	v_mfma_f32_16x16x32_bf16 v[62:65], v[222:225], v[190:193], v[62:65]
	ds_read_b128 v[142:145], v240 offset:3072
	v_mfma_f32_16x16x32_bf16 v[66:69], v[210:213], v[194:197], v[66:69]
	ds_read_b128 v[146:149], v240 offset:4096
	v_mfma_f32_16x16x32_bf16 v[70:73], v[214:217], v[194:197], v[70:73]
	ds_read_b128 v[150:153], v240 offset:5120
	v_mfma_f32_16x16x32_bf16 v[74:77], v[218:221], v[194:197], v[74:77]
	ds_read_b128 v[154:157], v240 offset:6144
	v_mfma_f32_16x16x32_bf16 v[78:81], v[222:225], v[194:197], v[78:81]
	ds_read_b128 v[158:161], v240 offset:7168
	v_mfma_f32_16x16x32_bf16 v[82:85], v[210:213], v[198:201], v[82:85]
	v_mfma_f32_16x16x32_bf16 v[86:89], v[214:217], v[198:201], v[86:89]
	v_mfma_f32_16x16x32_bf16 v[90:93], v[218:221], v[198:201], v[90:93]
	v_mfma_f32_16x16x32_bf16 v[94:97], v[222:225], v[198:201], v[94:97]
	v_mfma_f32_16x16x32_bf16 v[98:101], v[210:213], v[202:205], v[98:101]
	v_mfma_f32_16x16x32_bf16 v[102:105], v[214:217], v[202:205], v[102:105]
	v_mfma_f32_16x16x32_bf16 v[106:109], v[218:221], v[202:205], v[106:109]
	v_mfma_f32_16x16x32_bf16 v[110:113], v[222:225], v[202:205], v[110:113]
	v_mfma_f32_16x16x32_bf16 v[114:117], v[210:213], v[206:209], v[114:117]
	v_mfma_f32_16x16x32_bf16 v[118:121], v[214:217], v[206:209], v[118:121]
	v_mfma_f32_16x16x32_bf16 v[122:125], v[218:221], v[206:209], v[122:125]
	v_mfma_f32_16x16x32_bf16 v[126:129], v[222:225], v[206:209], v[126:129]
	s_setprio 0
	s_add_i32 s60, s60, 0x6000
	s_cmp_eq_u32 s60, 0x12000
	s_cselect_b32 s60, 0, s60
	s_add_u32 s54, s54, s72
	s_addc_u32 s55, s55, 0
	s_add_u32 s56, s56, s73
	s_addc_u32 s57, s57, 0
	s_add_i32 s61, s61, 0x6000
	s_cmp_eq_u32 s61, 0x12000
	s_cselect_b32 s61, 0, s61
	s_branch .Lgy_main

.Lgy_nn_b:
	s_waitcnt vmcnt(22) lgkmcnt(0)
	s_barrier
	v_add_u32_e32 v240, s61, v238
	v_add_u32_e32 v241, s61, v239
	s_setprio 1
	s_add_i32 m0, s60, s62
	v_mfma_f32_16x16x32_bf16 v[2:5], v[162:165], v[130:133], 0
	global_load_lds_dwordx4 v226, s[54:55]
	v_mfma_f32_16x16x32_bf16 v[6:9], v[166:169], v[130:133], 0
	global_load_lds_dwordx4 v226, s[54:55] offset:1024
	v_mfma_f32_16x16x32_bf16 v[10:13], v[170:173], v[130:133], 0
	global_load_lds_dwordx4 v226, s[54:55] offset:2048
	v_mfma_f32_16x16x32_bf16 v[14:17], v[174:177], v[130:133], 0
	global_load_lds_dwordx4 v226, s[54:55] offset:3072
	s_add_i32 m0, s60, s63
	v_mfma_f32_16x16x32_bf16 v[18:21], v[162:165], v[134:137], 0
	global_load_lds_dwordx4 v230, s[56:57]
	v_mfma_f32_16x16x32_bf16 v[22:25], v[166:169], v[134:137], 0
	global_load_lds_dwordx4 v231, s[56:57] offset:1024
	v_mfma_f32_16x16x32_bf16 v[26:29], v[170:173], v[134:137], 0
	v_mfma_f32_16x16x32_bf16 v[30:33], v[174:177], v[134:137], 0
	v_mfma_f32_16x16x32_bf16 v[34:37], v[162:165], v[138:141], 0
	ds_read_b128 v[210:213], v241 offset:0
	v_mfma_f32_16x16x32_bf16 v[38:41], v[166:169], v[138:141], 0
	ds_read_b128 v[214:217], v241 offset:256
	v_mfma_f32_16x16x32_bf16 v[42:45], v[170:173], v[138:141], 0
	ds_read_b128 v[218:221], v241 offset:512
	v_mfma_f32_16x16x32_bf16 v[46:49], v[174:177], v[138:141], 0
	ds_read_b128 v[222:225], v241 offset:768
	v_mfma_f32_16x16x32_bf16 v[50:53], v[162:165], v[142:145], 0
	ds_read_b128 v[178:181], v240 offset:0
	v_mfma_f32_16x16x32_bf16 v[54:57], v[166:169], v[142:145], 0
	ds_read_b128 v[182:185], v240 offset:1024
	v_mfma_f32_16x16x32_bf16 v[58:61], v[170:173], v[142:145], 0
	ds_read_b128 v[186:189], v240 offset:2048
	v_mfma_f32_16x16x32_bf16 v[62:65], v[174:177], v[142:145], 0
	ds_read_b128 v[190:193], v240 offset:3072
	v_mfma_f32_16x16x32_bf16 v[66:69], v[162:165], v[146:149], 0
	ds_read_b128 v[194:197], v240 offset:4096
	v_mfma_f32_16x16x32_bf16 v[70:73], v[166:169], v[146:149], 0
	ds_read_b128 v[198:201], v240 offset:5120
	v_mfma_f32_16x16x32_bf16 v[74:77], v[170:173], v[146:149], 0
	ds_read_b128 v[202:205], v240 offset:6144
	v_mfma_f32_16x16x32_bf16 v[78:81], v[174:177], v[146:149], 0
	ds_read_b128 v[206:209], v240 offset:7168
	v_mfma_f32_16x16x32_bf16 v[82:85], v[162:165], v[150:153], 0
	v_mfma_f32_16x16x32_bf16 v[86:89], v[166:169], v[150:153], 0
	v_mfma_f32_16x16x32_bf16 v[90:93], v[170:173], v[150:153], 0
	v_mfma_f32_16x16x32_bf16 v[94:97], v[174:177], v[150:153], 0
	v_mfma_f32_16x16x32_bf16 v[98:101], v[162:165], v[154:157], 0
	v_mfma_f32_16x16x32_bf16 v[102:105], v[166:169], v[154:157], 0
	v_mfma_f32_16x16x32_bf16 v[106:109], v[170:173], v[154:157], 0
	v_mfma_f32_16x16x32_bf16 v[110:113], v[174:177], v[154:157], 0
	v_mfma_f32_16x16x32_bf16 v[114:117], v[162:165], v[158:161], 0
	v_mfma_f32_16x16x32_bf16 v[118:121], v[166:169], v[158:161], 0
	v_mfma_f32_16x16x32_bf16 v[122:125], v[170:173], v[158:161], 0
	v_mfma_f32_16x16x32_bf16 v[126:129], v[174:177], v[158:161], 0
	s_setprio 0
	s_add_i32 s60, s60, 0x6000
	s_cmp_eq_u32 s60, 0x12000
	s_cselect_b32 s60, 0, s60
	s_add_u32 s54, s54, s72
	s_addc_u32 s55, s55, 0
	s_add_u32 s56, s56, s73
	s_addc_u32 s57, s57, 0
	s_add_i32 s61, s61, 0x6000
	s_cmp_eq_u32 s61, 0x12000
	s_cselect_b32 s61, 0, s61
	s_waitcnt vmcnt(22) lgkmcnt(0)
	s_barrier
	v_add_u32_e32 v240, s61, v238
	v_add_u32_e32 v241, s61, v239
	s_setprio 1
	s_add_i32 m0, s60, s62
	v_mfma_f32_16x16x32_bf16 v[2:5], v[210:213], v[178:181], v[2:5]
	global_load_lds_dwordx4 v226, s[54:55]
	v_mfma_f32_16x16x32_bf16 v[6:9], v[214:217], v[178:181], v[6:9]
	global_load_lds_dwordx4 v226, s[54:55] offset:1024
	v_mfma_f32_16x16x32_bf16 v[10:13], v[218:221], v[178:181], v[10:13]
	global_load_lds_dwordx4 v226, s[54:55] offset:2048
	v_mfma_f32_16x16x32_bf16 v[14:17], v[222:225], v[178:181], v[14:17]
	global_load_lds_dwordx4 v226, s[54:55] offset:3072
	s_add_i32 m0, s60, s63
	v_mfma_f32_16x16x32_bf16 v[18:21], v[210:213], v[182:185], v[18:21]
	global_load_lds_dwordx4 v230, s[56:57]
	v_mfma_f32_16x16x32_bf16 v[22:25], v[214:217], v[182:185], v[22:25]
	global_load_lds_dwordx4 v231, s[56:57] offset:1024
	v_mfma_f32_16x16x32_bf16 v[26:29], v[218:221], v[182:185], v[26:29]
	v_mfma_f32_16x16x32_bf16 v[30:33], v[222:225], v[182:185], v[30:33]
	v_mfma_f32_16x16x32_bf16 v[34:37], v[210:213], v[186:189], v[34:37]
	ds_read_b128 v[162:165], v241 offset:0
	v_mfma_f32_16x16x32_bf16 v[38:41], v[214:217], v[186:189], v[38:41]
	ds_read_b128 v[166:169], v241 offset:256
	v_mfma_f32_16x16x32_bf16 v[42:45], v[218:221], v[186:189], v[42:45]
	ds_read_b128 v[170:173], v241 offset:512
	v_mfma_f32_16x16x32_bf16 v[46:49], v[222:225], v[186:189], v[46:49]
	ds_read_b128 v[174:177], v241 offset:768
	v_mfma_f32_16x16x32_bf16 v[50:53], v[210:213], v[190:193], v[50:53]
	ds_read_b128 v[130:133], v240 offset:0
	v_mfma_f32_16x16x32_bf16 v[54:57], v[214:217], v[190:193], v[54:57]
	ds_read_b128 v[134:137], v240 offset:1024
	v_mfma_f32_16x16x32_bf16 v[58:61], v[218:221], v[190:193], v[58:61]
	ds_read_b128 v[138:141], v240 offset:2048
	v_mfma_f32_16x16x32_bf16 v[62:65], v[222:225], v[190:193], v[62:65]
	ds_read_b128 v[142:145], v240 offset:3072
	v_mfma_f32_16x16x32_bf16 v[66:69], v[210:213], v[194:197], v[66:69]
	ds_read_b128 v[146:149], v240 offset:4096
	v_mfma_f32_16x16x32_bf16 v[70:73], v[214:217], v[194:197], v[70:73]
	ds_read_b128 v[150:153], v240 offset:5120
	v_mfma_f32_16x16x32_bf16 v[74:77], v[218:221], v[194:197], v[74:77]
	ds_read_b128 v[154:157], v240 offset:6144
	v_mfma_f32_16x16x32_bf16 v[78:81], v[222:225], v[194:197], v[78:81]
	ds_read_b128 v[158:161], v240 offset:7168
	v_mfma_f32_16x16x32_bf16 v[82:85], v[210:213], v[198:201], v[82:85]
	v_mfma_f32_16x16x32_bf16 v[86:89], v[214:217], v[198:201], v[86:89]
	v_mfma_f32_16x16x32_bf16 v[90:93], v[218:221], v[198:201], v[90:93]
	v_mfma_f32_16x16x32_bf16 v[94:97], v[222:225], v[198:201], v[94:97]
	v_mfma_f32_16x16x32_bf16 v[98:101], v[210:213], v[202:205], v[98:101]
	v_mfma_f32_16x16x32_bf16 v[102:105], v[214:217], v[202:205], v[102:105]
	v_mfma_f32_16x16x32_bf16 v[106:109], v[218:221], v[202:205], v[106:109]
	v_mfma_f32_16x16x32_bf16 v[110:113], v[222:225], v[202:205], v[110:113]
	v_mfma_f32_16x16x32_bf16 v[114:117], v[210:213], v[206:209], v[114:117]
	v_mfma_f32_16x16x32_bf16 v[118:121], v[214:217], v[206:209], v[118:121]
	v_mfma_f32_16x16x32_bf16 v[122:125], v[218:221], v[206:209], v[122:125]
	v_mfma_f32_16x16x32_bf16 v[126:129], v[222:225], v[206:209], v[126:129]
	s_setprio 0
	s_add_i32 s60, s60, 0x6000
	s_cmp_eq_u32 s60, 0x12000
	s_cselect_b32 s60, 0, s60
	s_add_u32 s54, s54, s72
	s_addc_u32 s55, s55, 0
	s_add_u32 s56, s56, s73
	s_addc_u32 s57, s57, 0
	s_add_i32 s61, s61, 0x6000
	s_cmp_eq_u32 s61, 0x12000
	s_cselect_b32 s61, 0, s61

.Lgy_kloop:
	s_waitcnt vmcnt(6) lgkmcnt(0)
	s_barrier
	v_add_u32_e32 v240, s61, v238
	v_add_u32_e32 v241, s61, v239
	s_setprio 1
	s_add_i32 m0, s60, s62
	v_mfma_f32_16x16x32_bf16 v[2:5], v[162:165], v[130:133], v[2:5]
	global_load_lds_dwordx4 v226, s[54:55]
	v_mfma_f32_16x16x32_bf16 v[6:9], v[166:169], v[130:133], v[6:9]
	global_load_lds_dwordx4 v226, s[54:55] offset:1024
	v_mfma_f32_16x16x32_bf16 v[10:13], v[170:173], v[130:133], v[10:13]
	global_load_lds_dwordx4 v226, s[54:55] offset:2048
	v_mfma_f32_16x16x32_bf16 v[14:17], v[174:177], v[130:133], v[14:17]
	global_load_lds_dwordx4 v226, s[54:55] offset:3072
	s_add_i32 m0, s60, s63
	v_mfma_f32_16x16x32_bf16 v[18:21], v[162:165], v[134:137], v[18:21]
	global_load_lds_dwordx4 v230, s[56:57]
	v_mfma_f32_16x16x32_bf16 v[22:25], v[166:169], v[134:137], v[22:25]
	global_load_lds_dwordx4 v231, s[56:57] offset:1024
	v_mfma_f32_16x16x32_bf16 v[26:29], v[170:173], v[134:137], v[26:29]
	v_mfma_f32_16x16x32_bf16 v[30:33], v[174:177], v[134:137], v[30:33]
	v_mfma_f32_16x16x32_bf16 v[34:37], v[162:165], v[138:141], v[34:37]
	ds_read_b128 v[210:213], v241 offset:0
	v_mfma_f32_16x16x32_bf16 v[38:41], v[166:169], v[138:141], v[38:41]
	ds_read_b128 v[214:217], v241 offset:256
	v_mfma_f32_16x16x32_bf16 v[42:45], v[170:173], v[138:141], v[42:45]
	ds_read_b128 v[218:221], v241 offset:512
	v_mfma_f32_16x16x32_bf16 v[46:49], v[174:177], v[138:141], v[46:49]
	ds_read_b128 v[222:225], v241 offset:768
	v_mfma_f32_16x16x32_bf16 v[50:53], v[162:165], v[142:145], v[50:53]
	ds_read_b128 v[178:181], v240 offset:0
	v_mfma_f32_16x16x32_bf16 v[54:57], v[166:169], v[142:145], v[54:57]
	ds_read_b128 v[182:185], v240 offset:1024
	v_mfma_f32_16x16x32_bf16 v[58:61], v[170:173], v[142:145], v[58:61]
	ds_read_b128 v[186:189], v240 offset:2048
	v_mfma_f32_16x16x32_bf16 v[62:65], v[174:177], v[142:145], v[62:65]
	ds_read_b128 v[190:193], v240 offset:3072
	v_mfma_f32_16x16x32_bf16 v[66:69], v[162:165], v[146:149], v[66:69]
	ds_read_b128 v[194:197], v240 offset:4096
	v_mfma_f32_16x16x32_bf16 v[70:73], v[166:169], v[146:149], v[70:73]
	ds_read_b128 v[198:201], v240 offset:5120
	v_mfma_f32_16x16x32_bf16 v[74:77], v[170:173], v[146:149], v[74:77]
	ds_read_b128 v[202:205], v240 offset:6144
	v_mfma_f32_16x16x32_bf16 v[78:81], v[174:177], v[146:149], v[78:81]
	ds_read_b128 v[206:209], v240 offset:7168
	v_mfma_f32_16x16x32_bf16 v[82:85], v[162:165], v[150:153], v[82:85]
	v_mfma_f32_16x16x32_bf16 v[86:89], v[166:169], v[150:153], v[86:89]
	v_mfma_f32_16x16x32_bf16 v[90:93], v[170:173], v[150:153], v[90:93]
	v_mfma_f32_16x16x32_bf16 v[94:97], v[174:177], v[150:153], v[94:97]
	v_mfma_f32_16x16x32_bf16 v[98:101], v[162:165], v[154:157], v[98:101]
	v_mfma_f32_16x16x32_bf16 v[102:105], v[166:169], v[154:157], v[102:105]
	v_mfma_f32_16x16x32_bf16 v[106:109], v[170:173], v[154:157], v[106:109]
	v_mfma_f32_16x16x32_bf16 v[110:113], v[174:177], v[154:157], v[110:113]
	v_mfma_f32_16x16x32_bf16 v[114:117], v[162:165], v[158:161], v[114:117]
	v_mfma_f32_16x16x32_bf16 v[118:121], v[166:169], v[158:161], v[118:121]
	v_mfma_f32_16x16x32_bf16 v[122:125], v[170:173], v[158:161], v[122:125]
	v_mfma_f32_16x16x32_bf16 v[126:129], v[174:177], v[158:161], v[126:129]
	s_setprio 0
	s_add_i32 s60, s60, 0x6000
	s_cmp_eq_u32 s60, 0x12000
	s_cselect_b32 s60, 0, s60
	s_add_u32 s54, s54, s72
	s_addc_u32 s55, s55, 0
	s_add_u32 s56, s56, s73
	s_addc_u32 s57, s57, 0
	s_add_i32 s61, s61, 0x6000
	s_cmp_eq_u32 s61, 0x12000
	s_cselect_b32 s61, 0, s61
	s_waitcnt vmcnt(6) lgkmcnt(0)
	s_barrier
	v_add_u32_e32 v240, s61, v238
	v_add_u32_e32 v241, s61, v239
	s_setprio 1
	s_add_i32 m0, s60, s62
	v_mfma_f32_16x16x32_bf16 v[2:5], v[210:213], v[178:181], v[2:5]
	global_load_lds_dwordx4 v226, s[54:55]
	v_mfma_f32_16x16x32_bf16 v[6:9], v[214:217], v[178:181], v[6:9]
	global_load_lds_dwordx4 v226, s[54:55] offset:1024
	v_mfma_f32_16x16x32_bf16 v[10:13], v[218:221], v[178:181], v[10:13]
	global_load_lds_dwordx4 v226, s[54:55] offset:2048
	v_mfma_f32_16x16x32_bf16 v[14:17], v[222:225], v[178:181], v[14:17]
	global_load_lds_dwordx4 v226, s[54:55] offset:3072
	s_add_i32 m0, s60, s63
	v_mfma_f32_16x16x32_bf16 v[18:21], v[210:213], v[182:185], v[18:21]
	global_load_lds_dwordx4 v230, s[56:57]
	v_mfma_f32_16x16x32_bf16 v[22:25], v[214:217], v[182:185], v[22:25]
	global_load_lds_dwordx4 v231, s[56:57] offset:1024
	v_mfma_f32_16x16x32_bf16 v[26:29], v[218:221], v[182:185], v[26:29]
	v_mfma_f32_16x16x32_bf16 v[30:33], v[222:225], v[182:185], v[30:33]
	v_mfma_f32_16x16x32_bf16 v[34:37], v[210:213], v[186:189], v[34:37]
	ds_read_b128 v[162:165], v241 offset:0
	v_mfma_f32_16x16x32_bf16 v[38:41], v[214:217], v[186:189], v[38:41]
	ds_read_b128 v[166:169], v241 offset:256
	v_mfma_f32_16x16x32_bf16 v[42:45], v[218:221], v[186:189], v[42:45]
	ds_read_b128 v[170:173], v241 offset:512
	v_mfma_f32_16x16x32_bf16 v[46:49], v[222:225], v[186:189], v[46:49]
	ds_read_b128 v[174:177], v241 offset:768
	v_mfma_f32_16x16x32_bf16 v[50:53], v[210:213], v[190:193], v[50:53]
	ds_read_b128 v[130:133], v240 offset:0
	v_mfma_f32_16x16x32_bf16 v[54:57], v[214:217], v[190:193], v[54:57]
	ds_read_b128 v[134:137], v240 offset:1024
	v_mfma_f32_16x16x32_bf16 v[58:61], v[218:221], v[190:193], v[58:61]
	ds_read_b128 v[138:141], v240 offset:2048
	v_mfma_f32_16x16x32_bf16 v[62:65], v[222:225], v[190:193], v[62:65]
	ds_read_b128 v[142:145], v240 offset:3072
	v_mfma_f32_16x16x32_bf16 v[66:69], v[210:213], v[194:197], v[66:69]
	ds_read_b128 v[146:149], v240 offset:4096
	v_mfma_f32_16x16x32_bf16 v[70:73], v[214:217], v[194:197], v[70:73]
	ds_read_b128 v[150:153], v240 offset:5120
	v_mfma_f32_16x16x32_bf16 v[74:77], v[218:221], v[194:197], v[74:77]
	ds_read_b128 v[154:157], v240 offset:6144
	v_mfma_f32_16x16x32_bf16 v[78:81], v[222:225], v[194:197], v[78:81]
	ds_read_b128 v[158:161], v240 offset:7168
	v_mfma_f32_16x16x32_bf16 v[82:85], v[210:213], v[198:201], v[82:85]
	v_mfma_f32_16x16x32_bf16 v[86:89], v[214:217], v[198:201], v[86:89]
	v_mfma_f32_16x16x32_bf16 v[90:93], v[218:221], v[198:201], v[90:93]
	v_mfma_f32_16x16x32_bf16 v[94:97], v[222:225], v[198:201], v[94:97]
	v_mfma_f32_16x16x32_bf16 v[98:101], v[210:213], v[202:205], v[98:101]
	v_mfma_f32_16x16x32_bf16 v[102:105], v[214:217], v[202:205], v[102:105]
	v_mfma_f32_16x16x32_bf16 v[106:109], v[218:221], v[202:205], v[106:109]
	v_mfma_f32_16x16x32_bf16 v[110:113], v[222:225], v[202:205], v[110:113]
	v_mfma_f32_16x16x32_bf16 v[114:117], v[210:213], v[206:209], v[114:117]
	v_mfma_f32_16x16x32_bf16 v[118:121], v[214:217], v[206:209], v[118:121]
	v_mfma_f32_16x16x32_bf16 v[122:125], v[218:221], v[206:209], v[122:125]
	v_mfma_f32_16x16x32_bf16 v[126:129], v[222:225], v[206:209], v[126:129]
	s_setprio 0
	s_add_i32 s60, s60, 0x6000
	s_cmp_eq_u32 s60, 0x12000
	s_cselect_b32 s60, 0, s60
	s_add_u32 s54, s54, s72
	s_addc_u32 s55, s55, 0
	s_add_u32 s56, s56, s73
	s_addc_u32 s57, s57, 0
	s_add_i32 s61, s61, 0x6000
	s_cmp_eq_u32 s61, 0x12000
	s_cselect_b32 s61, 0, s61
	s_add_i32 s40, s40, -1
	s_cmp_lg_u32 s40, 0
	s_cbranch_scc1 .Lgy_kloop
	s_cmp_eq_u32 s37, 0
	s_cbranch_scc1 .Lgy_tail_last
	s_waitcnt vmcnt(6) lgkmcnt(0)
	s_barrier
	v_add_u32_e32 v240, s61, v238
	v_add_u32_e32 v241, s61, v239
	s_setprio 1
	s_add_i32 m0, s60, s62
	v_mfma_f32_16x16x32_bf16 v[2:5], v[162:165], v[130:133], v[2:5]
	global_load_lds_dwordx4 v226, s[54:55]
	v_mfma_f32_16x16x32_bf16 v[6:9], v[166:169], v[130:133], v[6:9]
	global_load_lds_dwordx4 v226, s[54:55] offset:1024
	v_mfma_f32_16x16x32_bf16 v[10:13], v[170:173], v[130:133], v[10:13]
	global_load_lds_dwordx4 v226, s[54:55] offset:2048
	v_mfma_f32_16x16x32_bf16 v[14:17], v[174:177], v[130:133], v[14:17]
	global_load_lds_dwordx4 v226, s[54:55] offset:3072
	s_add_i32 m0, s60, s63
	v_mfma_f32_16x16x32_bf16 v[18:21], v[162:165], v[134:137], v[18:21]
	global_load_lds_dwordx4 v230, s[56:57]
	v_mfma_f32_16x16x32_bf16 v[22:25], v[166:169], v[134:137], v[22:25]
	global_load_lds_dwordx4 v231, s[56:57] offset:1024
	v_mfma_f32_16x16x32_bf16 v[26:29], v[170:173], v[134:137], v[26:29]
	v_mfma_f32_16x16x32_bf16 v[30:33], v[174:177], v[134:137], v[30:33]
	v_mfma_f32_16x16x32_bf16 v[34:37], v[162:165], v[138:141], v[34:37]
	ds_read_b128 v[210:213], v241 offset:0
	v_mfma_f32_16x16x32_bf16 v[38:41], v[166:169], v[138:141], v[38:41]
	ds_read_b128 v[214:217], v241 offset:256
	v_mfma_f32_16x16x32_bf16 v[42:45], v[170:173], v[138:141], v[42:45]
	ds_read_b128 v[218:221], v241 offset:512
	v_mfma_f32_16x16x32_bf16 v[46:49], v[174:177], v[138:141], v[46:49]
	ds_read_b128 v[222:225], v241 offset:768
	v_mfma_f32_16x16x32_bf16 v[50:53], v[162:165], v[142:145], v[50:53]
	ds_read_b128 v[178:181], v240 offset:0
	v_mfma_f32_16x16x32_bf16 v[54:57], v[166:169], v[142:145], v[54:57]
	ds_read_b128 v[182:185], v240 offset:1024
	v_mfma_f32_16x16x32_bf16 v[58:61], v[170:173], v[142:145], v[58:61]
	ds_read_b128 v[186:189], v240 offset:2048
	v_mfma_f32_16x16x32_bf16 v[62:65], v[174:177], v[142:145], v[62:65]
	ds_read_b128 v[190:193], v240 offset:3072
	v_mfma_f32_16x16x32_bf16 v[66:69], v[162:165], v[146:149], v[66:69]
	ds_read_b128 v[194:197], v240 offset:4096
	v_mfma_f32_16x16x32_bf16 v[70:73], v[166:169], v[146:149], v[70:73]
	ds_read_b128 v[198:201], v240 offset:5120
	v_mfma_f32_16x16x32_bf16 v[74:77], v[170:173], v[146:149], v[74:77]
	ds_read_b128 v[202:205], v240 offset:6144
	v_mfma_f32_16x16x32_bf16 v[78:81], v[174:177], v[146:149], v[78:81]
	ds_read_b128 v[206:209], v240 offset:7168
	v_mfma_f32_16x16x32_bf16 v[82:85], v[162:165], v[150:153], v[82:85]
	v_mfma_f32_16x16x32_bf16 v[86:89], v[166:169], v[150:153], v[86:89]
	v_mfma_f32_16x16x32_bf16 v[90:93], v[170:173], v[150:153], v[90:93]
	v_mfma_f32_16x16x32_bf16 v[94:97], v[174:177], v[150:153], v[94:97]
	v_mfma_f32_16x16x32_bf16 v[98:101], v[162:165], v[154:157], v[98:101]
	v_mfma_f32_16x16x32_bf16 v[102:105], v[166:169], v[154:157], v[102:105]
	v_mfma_f32_16x16x32_bf16 v[106:109], v[170:173], v[154:157], v[106:109]
	v_mfma_f32_16x16x32_bf16 v[110:113], v[174:177], v[154:157], v[110:113]
	v_mfma_f32_16x16x32_bf16 v[114:117], v[162:165], v[158:161], v[114:117]
	v_mfma_f32_16x16x32_bf16 v[118:121], v[166:169], v[158:161], v[118:121]
	v_mfma_f32_16x16x32_bf16 v[122:125], v[170:173], v[158:161], v[122:125]
	v_mfma_f32_16x16x32_bf16 v[126:129], v[174:177], v[158:161], v[126:129]
	s_setprio 0
	s_add_i32 s60, s60, 0x6000
	s_cmp_eq_u32 s60, 0x12000
	s_cselect_b32 s60, 0, s60
	s_add_u32 s54, s54, s72
	s_addc_u32 s55, s55, 0
	s_add_u32 s56, s56, s73
	s_addc_u32 s57, s57, 0
	s_add_i32 s61, s61, 0x6000
	s_cmp_eq_u32 s61, 0x12000
	s_cselect_b32 s61, 0, s61
	v_mov_b32_e32 v226, v232
	v_mov_b32_e32 v230, v236
	v_mov_b32_e32 v231, v237
	s_mov_b64 s[54:55], s[48:49]
	s_mov_b64 s[56:57], s[50:51]
	s_waitcnt vmcnt(6) lgkmcnt(0)
	s_barrier
	v_add_u32_e32 v240, s61, v238
	v_add_u32_e32 v241, s61, v239
	s_setprio 1
	s_add_i32 m0, s60, s62
	v_mfma_f32_16x16x32_bf16 v[2:5], v[210:213], v[178:181], v[2:5]
	global_load_lds_dwordx4 v226, s[54:55]
	v_mfma_f32_16x16x32_bf16 v[6:9], v[214:217], v[178:181], v[6:9]
	global_load_lds_dwordx4 v226, s[54:55] offset:1024
	v_mfma_f32_16x16x32_bf16 v[10:13], v[218:221], v[178:181], v[10:13]
	global_load_lds_dwordx4 v226, s[54:55] offset:2048
	v_mfma_f32_16x16x32_bf16 v[14:17], v[222:225], v[178:181], v[14:17]
	global_load_lds_dwordx4 v226, s[54:55] offset:3072
	s_add_i32 m0, s60, s63
	v_mfma_f32_16x16x32_bf16 v[18:21], v[210:213], v[182:185], v[18:21]
	global_load_lds_dwordx4 v230, s[56:57]
	v_mfma_f32_16x16x32_bf16 v[22:25], v[214:217], v[182:185], v[22:25]
	global_load_lds_dwordx4 v231, s[56:57] offset:1024
	v_mfma_f32_16x16x32_bf16 v[26:29], v[218:221], v[182:185], v[26:29]
	v_mfma_f32_16x16x32_bf16 v[30:33], v[222:225], v[182:185], v[30:33]
	v_mfma_f32_16x16x32_bf16 v[34:37], v[210:213], v[186:189], v[34:37]
	ds_read_b128 v[162:165], v241 offset:0
	v_mfma_f32_16x16x32_bf16 v[38:41], v[214:217], v[186:189], v[38:41]
	ds_read_b128 v[166:169], v241 offset:256
	v_mfma_f32_16x16x32_bf16 v[42:45], v[218:221], v[186:189], v[42:45]
	ds_read_b128 v[170:173], v241 offset:512
	v_mfma_f32_16x16x32_bf16 v[46:49], v[222:225], v[186:189], v[46:49]
	ds_read_b128 v[174:177], v241 offset:768
	v_mfma_f32_16x16x32_bf16 v[50:53], v[210:213], v[190:193], v[50:53]
	ds_read_b128 v[130:133], v240 offset:0
	v_mfma_f32_16x16x32_bf16 v[54:57], v[214:217], v[190:193], v[54:57]
	ds_read_b128 v[134:137], v240 offset:1024
	v_mfma_f32_16x16x32_bf16 v[58:61], v[218:221], v[190:193], v[58:61]
	ds_read_b128 v[138:141], v240 offset:2048
	v_mfma_f32_16x16x32_bf16 v[62:65], v[222:225], v[190:193], v[62:65]
	ds_read_b128 v[142:145], v240 offset:3072
	v_mfma_f32_16x16x32_bf16 v[66:69], v[210:213], v[194:197], v[66:69]
	ds_read_b128 v[146:149], v240 offset:4096
	v_mfma_f32_16x16x32_bf16 v[70:73], v[214:217], v[194:197], v[70:73]
	ds_read_b128 v[150:153], v240 offset:5120
	v_mfma_f32_16x16x32_bf16 v[74:77], v[218:221], v[194:197], v[74:77]
	ds_read_b128 v[154:157], v240 offset:6144
	v_mfma_f32_16x16x32_bf16 v[78:81], v[222:225], v[194:197], v[78:81]
	ds_read_b128 v[158:161], v240 offset:7168
	v_mfma_f32_16x16x32_bf16 v[82:85], v[210:213], v[198:201], v[82:85]
	v_mfma_f32_16x16x32_bf16 v[86:89], v[214:217], v[198:201], v[86:89]
	v_mfma_f32_16x16x32_bf16 v[90:93], v[218:221], v[198:201], v[90:93]
	v_mfma_f32_16x16x32_bf16 v[94:97], v[222:225], v[198:201], v[94:97]
	v_mfma_f32_16x16x32_bf16 v[98:101], v[210:213], v[202:205], v[98:101]
	v_mfma_f32_16x16x32_bf16 v[102:105], v[214:217], v[202:205], v[102:105]
	v_mfma_f32_16x16x32_bf16 v[106:109], v[218:221], v[202:205], v[106:109]
	v_mfma_f32_16x16x32_bf16 v[110:113], v[222:225], v[202:205], v[110:113]
	v_mfma_f32_16x16x32_bf16 v[114:117], v[210:213], v[206:209], v[114:117]
	v_mfma_f32_16x16x32_bf16 v[118:121], v[214:217], v[206:209], v[118:121]
	v_mfma_f32_16x16x32_bf16 v[122:125], v[218:221], v[206:209], v[122:125]
	v_mfma_f32_16x16x32_bf16 v[126:129], v[222:225], v[206:209], v[126:129]
	s_setprio 0
	s_add_i32 s60, s60, 0x6000
	s_cmp_eq_u32 s60, 0x12000
	s_cselect_b32 s60, 0, s60
	s_add_u32 s54, s54, s72
	s_addc_u32 s55, s55, 0
	s_add_u32 s56, s56, s73
	s_addc_u32 s57, s57, 0
	s_add_i32 s61, s61, 0x6000
	s_cmp_eq_u32 s61, 0x12000
	s_cselect_b32 s61, 0, s61
	s_waitcnt vmcnt(6) lgkmcnt(0)
	s_barrier
	v_add_u32_e32 v240, s61, v238
	v_add_u32_e32 v241, s61, v239
	s_setprio 1
	s_add_i32 m0, s60, s62
	v_mfma_f32_16x16x32_bf16 v[2:5], v[162:165], v[130:133], v[2:5]
	global_load_lds_dwordx4 v226, s[54:55]
	v_mfma_f32_16x16x32_bf16 v[6:9], v[166:169], v[130:133], v[6:9]
	global_load_lds_dwordx4 v226, s[54:55] offset:1024
	v_mfma_f32_16x16x32_bf16 v[10:13], v[170:173], v[130:133], v[10:13]
	global_load_lds_dwordx4 v226, s[54:55] offset:2048
	v_mfma_f32_16x16x32_bf16 v[14:17], v[174:177], v[130:133], v[14:17]
	global_load_lds_dwordx4 v226, s[54:55] offset:3072
	s_add_i32 m0, s60, s63
	v_mfma_f32_16x16x32_bf16 v[18:21], v[162:165], v[134:137], v[18:21]
	global_load_lds_dwordx4 v230, s[56:57]
	v_mfma_f32_16x16x32_bf16 v[22:25], v[166:169], v[134:137], v[22:25]
	global_load_lds_dwordx4 v231, s[56:57] offset:1024
	v_mfma_f32_16x16x32_bf16 v[26:29], v[170:173], v[134:137], v[26:29]
	v_mfma_f32_16x16x32_bf16 v[30:33], v[174:177], v[134:137], v[30:33]
	v_mfma_f32_16x16x32_bf16 v[34:37], v[162:165], v[138:141], v[34:37]
	ds_read_b128 v[210:213], v241 offset:0
	v_mfma_f32_16x16x32_bf16 v[38:41], v[166:169], v[138:141], v[38:41]
	ds_read_b128 v[214:217], v241 offset:256
	v_mfma_f32_16x16x32_bf16 v[42:45], v[170:173], v[138:141], v[42:45]
	ds_read_b128 v[218:221], v241 offset:512
	v_mfma_f32_16x16x32_bf16 v[46:49], v[174:177], v[138:141], v[46:49]
	ds_read_b128 v[222:225], v241 offset:768
	v_mfma_f32_16x16x32_bf16 v[50:53], v[162:165], v[142:145], v[50:53]
	ds_read_b128 v[178:181], v240 offset:0
	v_mfma_f32_16x16x32_bf16 v[54:57], v[166:169], v[142:145], v[54:57]
	ds_read_b128 v[182:185], v240 offset:1024
	v_mfma_f32_16x16x32_bf16 v[58:61], v[170:173], v[142:145], v[58:61]
	ds_read_b128 v[186:189], v240 offset:2048
	v_mfma_f32_16x16x32_bf16 v[62:65], v[174:177], v[142:145], v[62:65]
	ds_read_b128 v[190:193], v240 offset:3072
	v_mfma_f32_16x16x32_bf16 v[66:69], v[162:165], v[146:149], v[66:69]
	ds_read_b128 v[194:197], v240 offset:4096
	v_mfma_f32_16x16x32_bf16 v[70:73], v[166:169], v[146:149], v[70:73]
	ds_read_b128 v[198:201], v240 offset:5120
	v_mfma_f32_16x16x32_bf16 v[74:77], v[170:173], v[146:149], v[74:77]
	ds_read_b128 v[202:205], v240 offset:6144
	v_mfma_f32_16x16x32_bf16 v[78:81], v[174:177], v[146:149], v[78:81]
	ds_read_b128 v[206:209], v240 offset:7168
	v_mfma_f32_16x16x32_bf16 v[82:85], v[162:165], v[150:153], v[82:85]
	v_mfma_f32_16x16x32_bf16 v[86:89], v[166:169], v[150:153], v[86:89]
	v_mfma_f32_16x16x32_bf16 v[90:93], v[170:173], v[150:153], v[90:93]
	v_mfma_f32_16x16x32_bf16 v[94:97], v[174:177], v[150:153], v[94:97]
	v_mfma_f32_16x16x32_bf16 v[98:101], v[162:165], v[154:157], v[98:101]
	v_mfma_f32_16x16x32_bf16 v[102:105], v[166:169], v[154:157], v[102:105]
	v_mfma_f32_16x16x32_bf16 v[106:109], v[170:173], v[154:157], v[106:109]
	v_mfma_f32_16x16x32_bf16 v[110:113], v[174:177], v[154:157], v[110:113]
	v_mfma_f32_16x16x32_bf16 v[114:117], v[162:165], v[158:161], v[114:117]
	v_mfma_f32_16x16x32_bf16 v[118:121], v[166:169], v[158:161], v[118:121]
	v_mfma_f32_16x16x32_bf16 v[122:125], v[170:173], v[158:161], v[122:125]
	v_mfma_f32_16x16x32_bf16 v[126:129], v[174:177], v[158:161], v[126:129]
	s_setprio 0
	s_add_i32 s60, s60, 0x6000
	s_cmp_eq_u32 s60, 0x12000
	s_cselect_b32 s60, 0, s60
	s_add_u32 s54, s54, s72
	s_addc_u32 s55, s55, 0
	s_add_u32 s56, s56, s73
	s_addc_u32 s57, s57, 0
	s_add_i32 s61, s61, 0x6000
	s_cmp_eq_u32 s61, 0x12000
	s_cselect_b32 s61, 0, s61
	s_waitcnt vmcnt(6) lgkmcnt(0)
	s_barrier
	v_add_u32_e32 v240, s61, v238
	v_add_u32_e32 v241, s61, v239
	s_setprio 1
	s_add_i32 m0, s60, s62
	v_mfma_f32_16x16x32_bf16 v[2:5], v[210:213], v[178:181], v[2:5]
	global_load_lds_dwordx4 v226, s[54:55]
	v_mfma_f32_16x16x32_bf16 v[6:9], v[214:217], v[178:181], v[6:9]
	global_load_lds_dwordx4 v226, s[54:55] offset:1024
	v_mfma_f32_16x16x32_bf16 v[10:13], v[218:221], v[178:181], v[10:13]
	global_load_lds_dwordx4 v226, s[54:55] offset:2048
	v_mfma_f32_16x16x32_bf16 v[14:17], v[222:225], v[178:181], v[14:17]
	global_load_lds_dwordx4 v226, s[54:55] offset:3072
	s_add_i32 m0, s60, s63
	v_mfma_f32_16x16x32_bf16 v[18:21], v[210:213], v[182:185], v[18:21]
	global_load_lds_dwordx4 v230, s[56:57]
	v_mfma_f32_16x16x32_bf16 v[22:25], v[214:217], v[182:185], v[22:25]
	global_load_lds_dwordx4 v231, s[56:57] offset:1024
	v_mfma_f32_16x16x32_bf16 v[26:29], v[218:221], v[182:185], v[26:29]
	v_mfma_f32_16x16x32_bf16 v[30:33], v[222:225], v[182:185], v[30:33]
	v_mfma_f32_16x16x32_bf16 v[34:37], v[210:213], v[186:189], v[34:37]
	ds_read_b128 v[162:165], v241 offset:0
	v_mfma_f32_16x16x32_bf16 v[38:41], v[214:217], v[186:189], v[38:41]
	ds_read_b128 v[166:169], v241 offset:256
	v_mfma_f32_16x16x32_bf16 v[42:45], v[218:221], v[186:189], v[42:45]
	ds_read_b128 v[170:173], v241 offset:512
	v_mfma_f32_16x16x32_bf16 v[46:49], v[222:225], v[186:189], v[46:49]
	ds_read_b128 v[174:177], v241 offset:768
	v_mfma_f32_16x16x32_bf16 v[50:53], v[210:213], v[190:193], v[50:53]
	ds_read_b128 v[130:133], v240 offset:0
	v_mfma_f32_16x16x32_bf16 v[54:57], v[214:217], v[190:193], v[54:57]
	ds_read_b128 v[134:137], v240 offset:1024
	v_mfma_f32_16x16x32_bf16 v[58:61], v[218:221], v[190:193], v[58:61]
	ds_read_b128 v[138:141], v240 offset:2048
	v_mfma_f32_16x16x32_bf16 v[62:65], v[222:225], v[190:193], v[62:65]
	ds_read_b128 v[142:145], v240 offset:3072
	v_mfma_f32_16x16x32_bf16 v[66:69], v[210:213], v[194:197], v[66:69]
	ds_read_b128 v[146:149], v240 offset:4096
	v_mfma_f32_16x16x32_bf16 v[70:73], v[214:217], v[194:197], v[70:73]
	ds_read_b128 v[150:153], v240 offset:5120
	v_mfma_f32_16x16x32_bf16 v[74:77], v[218:221], v[194:197], v[74:77]
	ds_read_b128 v[154:157], v240 offset:6144
	v_mfma_f32_16x16x32_bf16 v[78:81], v[222:225], v[194:197], v[78:81]
	ds_read_b128 v[158:161], v240 offset:7168
	v_mfma_f32_16x16x32_bf16 v[82:85], v[210:213], v[198:201], v[82:85]
	v_mfma_f32_16x16x32_bf16 v[86:89], v[214:217], v[198:201], v[86:89]
	v_mfma_f32_16x16x32_bf16 v[90:93], v[218:221], v[198:201], v[90:93]
	v_mfma_f32_16x16x32_bf16 v[94:97], v[222:225], v[198:201], v[94:97]
	v_mfma_f32_16x16x32_bf16 v[98:101], v[210:213], v[202:205], v[98:101]
	v_mfma_f32_16x16x32_bf16 v[102:105], v[214:217], v[202:205], v[102:105]
	v_mfma_f32_16x16x32_bf16 v[106:109], v[218:221], v[202:205], v[106:109]
	v_mfma_f32_16x16x32_bf16 v[110:113], v[222:225], v[202:205], v[110:113]
	v_mfma_f32_16x16x32_bf16 v[114:117], v[210:213], v[206:209], v[114:117]
	v_mfma_f32_16x16x32_bf16 v[118:121], v[214:217], v[206:209], v[118:121]
	v_mfma_f32_16x16x32_bf16 v[122:125], v[218:221], v[206:209], v[122:125]
	v_mfma_f32_16x16x32_bf16 v[126:129], v[222:225], v[206:209], v[126:129]
	s_setprio 0
	s_add_i32 s60, s60, 0x6000
	s_cmp_eq_u32 s60, 0x12000
	s_cselect_b32 s60, 0, s60
	s_add_u32 s54, s54, s72
	s_addc_u32 s55, s55, 0
	s_add_u32 s56, s56, s73
	s_addc_u32 s57, s57, 0
	s_add_i32 s61, s61, 0x6000
	s_cmp_eq_u32 s61, 0x12000
	s_cselect_b32 s61, 0, s61
	s_nop 7
	s_nop 1
	s_lshl_b32 s26, s35, 11
	s_lshl_b32 s27, s36, 1
	s_add_i32 s26, s26, s27
	s_add_u32 s18, s52, s26
	s_addc_u32 s19, s53, 0
	v_cvt_pk_bf16_f32 v2, v2, v3
	v_cvt_pk_bf16_f32 v3, v4, v5
	v_cvt_pk_bf16_f32 v4, v6, v7
	v_cvt_pk_bf16_f32 v5, v8, v9
	v_cvt_pk_bf16_f32 v6, v10, v11
	v_cvt_pk_bf16_f32 v7, v12, v13
	v_cvt_pk_bf16_f32 v8, v14, v15
	v_cvt_pk_bf16_f32 v9, v16, v17
	global_store_dwordx4 v242, v[2:5], s[18:19]
	global_store_dwordx4 v242, v[6:9], s[18:19] offset:16
	s_add_u32 s18, s18, 0x8000
	s_addc_u32 s19, s19, 0
	v_cvt_pk_bf16_f32 v18, v18, v19
	v_cvt_pk_bf16_f32 v19, v20, v21
	v_cvt_pk_bf16_f32 v20, v22, v23
	v_cvt_pk_bf16_f32 v21, v24, v25
	v_cvt_pk_bf16_f32 v22, v26, v27
	v_cvt_pk_bf16_f32 v23, v28, v29
	v_cvt_pk_bf16_f32 v24, v30, v31
	v_cvt_pk_bf16_f32 v25, v32, v33
	global_store_dwordx4 v242, v[18:21], s[18:19]
	global_store_dwordx4 v242, v[22:25], s[18:19] offset:16
	s_add_u32 s18, s18, 0x8000
	s_addc_u32 s19, s19, 0
	v_cvt_pk_bf16_f32 v34, v34, v35
	v_cvt_pk_bf16_f32 v35, v36, v37
	v_cvt_pk_bf16_f32 v36, v38, v39
	v_cvt_pk_bf16_f32 v37, v40, v41
	v_cvt_pk_bf16_f32 v38, v42, v43
	v_cvt_pk_bf16_f32 v39, v44, v45
	v_cvt_pk_bf16_f32 v40, v46, v47
	v_cvt_pk_bf16_f32 v41, v48, v49
	global_store_dwordx4 v242, v[34:37], s[18:19]
	global_store_dwordx4 v242, v[38:41], s[18:19] offset:16
	s_add_u32 s18, s18, 0x8000
	s_addc_u32 s19, s19, 0
	v_cvt_pk_bf16_f32 v50, v50, v51
	v_cvt_pk_bf16_f32 v51, v52, v53
	v_cvt_pk_bf16_f32 v52, v54, v55
	v_cvt_pk_bf16_f32 v53, v56, v57
	v_cvt_pk_bf16_f32 v54, v58, v59
	v_cvt_pk_bf16_f32 v55, v60, v61
	v_cvt_pk_bf16_f32 v56, v62, v63
	v_cvt_pk_bf16_f32 v57, v64, v65
	global_store_dwordx4 v242, v[50:53], s[18:19]
	global_store_dwordx4 v242, v[54:57], s[18:19] offset:16
	s_add_u32 s18, s18, 0x8000
	s_addc_u32 s19, s19, 0
	v_cvt_pk_bf16_f32 v66, v66, v67
	v_cvt_pk_bf16_f32 v67, v68, v69
	v_cvt_pk_bf16_f32 v68, v70, v71
	v_cvt_pk_bf16_f32 v69, v72, v73
	v_cvt_pk_bf16_f32 v70, v74, v75
	v_cvt_pk_bf16_f32 v71, v76, v77
	v_cvt_pk_bf16_f32 v72, v78, v79
	v_cvt_pk_bf16_f32 v73, v80, v81
	global_store_dwordx4 v242, v[66:69], s[18:19]
	global_store_dwordx4 v242, v[70:73], s[18:19] offset:16
	s_add_u32 s18, s18, 0x8000
	s_addc_u32 s19, s19, 0
	v_cvt_pk_bf16_f32 v82, v82, v83
	v_cvt_pk_bf16_f32 v83, v84, v85
	v_cvt_pk_bf16_f32 v84, v86, v87
	v_cvt_pk_bf16_f32 v85, v88, v89
	v_cvt_pk_bf16_f32 v86, v90, v91
	v_cvt_pk_bf16_f32 v87, v92, v93
	v_cvt_pk_bf16_f32 v88, v94, v95
	v_cvt_pk_bf16_f32 v89, v96, v97
	global_store_dwordx4 v242, v[82:85], s[18:19]
	global_store_dwordx4 v242, v[86:89], s[18:19] offset:16
	s_add_u32 s18, s18, 0x8000
	s_addc_u32 s19, s19, 0
	v_cvt_pk_bf16_f32 v98, v98, v99
	v_cvt_pk_bf16_f32 v99, v100, v101
	v_cvt_pk_bf16_f32 v100, v102, v103
	v_cvt_pk_bf16_f32 v101, v104, v105
	v_cvt_pk_bf16_f32 v102, v106, v107
	v_cvt_pk_bf16_f32 v103, v108, v109
	v_cvt_pk_bf16_f32 v104, v110, v111
	v_cvt_pk_bf16_f32 v105, v112, v113
	global_store_dwordx4 v242, v[98:101], s[18:19]
	global_store_dwordx4 v242, v[102:105], s[18:19] offset:16
	s_add_u32 s18, s18, 0x8000
	s_addc_u32 s19, s19, 0
	v_cvt_pk_bf16_f32 v114, v114, v115
	v_cvt_pk_bf16_f32 v115, v116, v117
	v_cvt_pk_bf16_f32 v116, v118, v119
	v_cvt_pk_bf16_f32 v117, v120, v121
	v_cvt_pk_bf16_f32 v118, v122, v123
	v_cvt_pk_bf16_f32 v119, v124, v125
	v_cvt_pk_bf16_f32 v120, v126, v127
	v_cvt_pk_bf16_f32 v121, v128, v129
	global_store_dwordx4 v242, v[114:117], s[18:19]
	global_store_dwordx4 v242, v[118:121], s[18:19] offset:16
	s_mov_b32 s34, s38
	s_mov_b32 s35, s30
	s_mov_b32 s36, s31
	s_branch .Lgy_tile
.Lgy_tail_last:
	s_waitcnt vmcnt(6) lgkmcnt(0)
	s_barrier
	v_add_u32_e32 v240, s61, v238
	v_add_u32_e32 v241, s61, v239
	s_setprio 1
	s_add_i32 m0, s60, s62
	v_mfma_f32_16x16x32_bf16 v[2:5], v[162:165], v[130:133], v[2:5]
	global_load_lds_dwordx4 v226, s[54:55]
	v_mfma_f32_16x16x32_bf16 v[6:9], v[166:169], v[130:133], v[6:9]
	global_load_lds_dwordx4 v226, s[54:55] offset:1024
	v_mfma_f32_16x16x32_bf16 v[10:13], v[170:173], v[130:133], v[10:13]
	global_load_lds_dwordx4 v226, s[54:55] offset:2048
	v_mfma_f32_16x16x32_bf16 v[14:17], v[174:177], v[130:133], v[14:17]
	global_load_lds_dwordx4 v226, s[54:55] offset:3072
	s_add_i32 m0, s60, s63
	v_mfma_f32_16x16x32_bf16 v[18:21], v[162:165], v[134:137], v[18:21]
	global_load_lds_dwordx4 v230, s[56:57]
	v_mfma_f32_16x16x32_bf16 v[22:25], v[166:169], v[134:137], v[22:25]
	global_load_lds_dwordx4 v231, s[56:57] offset:1024
	v_mfma_f32_16x16x32_bf16 v[26:29], v[170:173], v[134:137], v[26:29]
	v_mfma_f32_16x16x32_bf16 v[30:33], v[174:177], v[134:137], v[30:33]
	v_mfma_f32_16x16x32_bf16 v[34:37], v[162:165], v[138:141], v[34:37]
	ds_read_b128 v[210:213], v241 offset:0
	v_mfma_f32_16x16x32_bf16 v[38:41], v[166:169], v[138:141], v[38:41]
	ds_read_b128 v[214:217], v241 offset:256
	v_mfma_f32_16x16x32_bf16 v[42:45], v[170:173], v[138:141], v[42:45]
	ds_read_b128 v[218:221], v241 offset:512
	v_mfma_f32_16x16x32_bf16 v[46:49], v[174:177], v[138:141], v[46:49]
	ds_read_b128 v[222:225], v241 offset:768
	v_mfma_f32_16x16x32_bf16 v[50:53], v[162:165], v[142:145], v[50:53]
	ds_read_b128 v[178:181], v240 offset:0
	v_mfma_f32_16x16x32_bf16 v[54:57], v[166:169], v[142:145], v[54:57]
	ds_read_b128 v[182:185], v240 offset:1024
	v_mfma_f32_16x16x32_bf16 v[58:61], v[170:173], v[142:145], v[58:61]
	ds_read_b128 v[186:189], v240 offset:2048
	v_mfma_f32_16x16x32_bf16 v[62:65], v[174:177], v[142:145], v[62:65]
	ds_read_b128 v[190:193], v240 offset:3072
	v_mfma_f32_16x16x32_bf16 v[66:69], v[162:165], v[146:149], v[66:69]
	ds_read_b128 v[194:197], v240 offset:4096
	v_mfma_f32_16x16x32_bf16 v[70:73], v[166:169], v[146:149], v[70:73]
	ds_read_b128 v[198:201], v240 offset:5120
	v_mfma_f32_16x16x32_bf16 v[74:77], v[170:173], v[146:149], v[74:77]
	ds_read_b128 v[202:205], v240 offset:6144
	v_mfma_f32_16x16x32_bf16 v[78:81], v[174:177], v[146:149], v[78:81]
	ds_read_b128 v[206:209], v240 offset:7168
	v_mfma_f32_16x16x32_bf16 v[82:85], v[162:165], v[150:153], v[82:85]
	v_mfma_f32_16x16x32_bf16 v[86:89], v[166:169], v[150:153], v[86:89]
	v_mfma_f32_16x16x32_bf16 v[90:93], v[170:173], v[150:153], v[90:93]
	v_mfma_f32_16x16x32_bf16 v[94:97], v[174:177], v[150:153], v[94:97]
	v_mfma_f32_16x16x32_bf16 v[98:101], v[162:165], v[154:157], v[98:101]
	v_mfma_f32_16x16x32_bf16 v[102:105], v[166:169], v[154:157], v[102:105]
	v_mfma_f32_16x16x32_bf16 v[106:109], v[170:173], v[154:157], v[106:109]
	v_mfma_f32_16x16x32_bf16 v[110:113], v[174:177], v[154:157], v[110:113]
	v_mfma_f32_16x16x32_bf16 v[114:117], v[162:165], v[158:161], v[114:117]
	v_mfma_f32_16x16x32_bf16 v[118:121], v[166:169], v[158:161], v[118:121]
	v_mfma_f32_16x16x32_bf16 v[122:125], v[170:173], v[158:161], v[122:125]
	v_mfma_f32_16x16x32_bf16 v[126:129], v[174:177], v[158:161], v[126:129]
	s_setprio 0
	s_add_i32 s60, s60, 0x6000
	s_cmp_eq_u32 s60, 0x12000
	s_cselect_b32 s60, 0, s60
	s_add_u32 s54, s54, s72
	s_addc_u32 s55, s55, 0
	s_add_u32 s56, s56, s73
	s_addc_u32 s57, s57, 0
	s_add_i32 s61, s61, 0x6000
	s_cmp_eq_u32 s61, 0x12000
	s_cselect_b32 s61, 0, s61
	s_waitcnt vmcnt(6) lgkmcnt(0)
	s_barrier
	v_add_u32_e32 v240, s61, v238
	v_add_u32_e32 v241, s61, v239
	s_setprio 1
	v_mfma_f32_16x16x32_bf16 v[2:5], v[210:213], v[178:181], v[2:5]
	v_mfma_f32_16x16x32_bf16 v[6:9], v[214:217], v[178:181], v[6:9]
	v_mfma_f32_16x16x32_bf16 v[10:13], v[218:221], v[178:181], v[10:13]
	v_mfma_f32_16x16x32_bf16 v[14:17], v[222:225], v[178:181], v[14:17]
	v_mfma_f32_16x16x32_bf16 v[18:21], v[210:213], v[182:185], v[18:21]
	v_mfma_f32_16x16x32_bf16 v[22:25], v[214:217], v[182:185], v[22:25]
	v_mfma_f32_16x16x32_bf16 v[26:29], v[218:221], v[182:185], v[26:29]
	v_mfma_f32_16x16x32_bf16 v[30:33], v[222:225], v[182:185], v[30:33]
	v_mfma_f32_16x16x32_bf16 v[34:37], v[210:213], v[186:189], v[34:37]
	ds_read_b128 v[162:165], v241 offset:0
	v_mfma_f32_16x16x32_bf16 v[38:41], v[214:217], v[186:189], v[38:41]
	ds_read_b128 v[166:169], v241 offset:256
	v_mfma_f32_16x16x32_bf16 v[42:45], v[218:221], v[186:189], v[42:45]
	ds_read_b128 v[170:173], v241 offset:512
	v_mfma_f32_16x16x32_bf16 v[46:49], v[222:225], v[186:189], v[46:49]
	ds_read_b128 v[174:177], v241 offset:768
	v_mfma_f32_16x16x32_bf16 v[50:53], v[210:213], v[190:193], v[50:53]
	ds_read_b128 v[130:133], v240 offset:0
	v_mfma_f32_16x16x32_bf16 v[54:57], v[214:217], v[190:193], v[54:57]
	ds_read_b128 v[134:137], v240 offset:1024
	v_mfma_f32_16x16x32_bf16 v[58:61], v[218:221], v[190:193], v[58:61]
	ds_read_b128 v[138:141], v240 offset:2048
	v_mfma_f32_16x16x32_bf16 v[62:65], v[222:225], v[190:193], v[62:65]
	ds_read_b128 v[142:145], v240 offset:3072
	v_mfma_f32_16x16x32_bf16 v[66:69], v[210:213], v[194:197], v[66:69]
	ds_read_b128 v[146:149], v240 offset:4096
	v_mfma_f32_16x16x32_bf16 v[70:73], v[214:217], v[194:197], v[70:73]
	ds_read_b128 v[150:153], v240 offset:5120
	v_mfma_f32_16x16x32_bf16 v[74:77], v[218:221], v[194:197], v[74:77]
	ds_read_b128 v[154:157], v240 offset:6144
	v_mfma_f32_16x16x32_bf16 v[78:81], v[222:225], v[194:197], v[78:81]
	ds_read_b128 v[158:161], v240 offset:7168
	v_mfma_f32_16x16x32_bf16 v[82:85], v[210:213], v[198:201], v[82:85]
	v_mfma_f32_16x16x32_bf16 v[86:89], v[214:217], v[198:201], v[86:89]
	v_mfma_f32_16x16x32_bf16 v[90:93], v[218:221], v[198:201], v[90:93]
	v_mfma_f32_16x16x32_bf16 v[94:97], v[222:225], v[198:201], v[94:97]
	v_mfma_f32_16x16x32_bf16 v[98:101], v[210:213], v[202:205], v[98:101]
	v_mfma_f32_16x16x32_bf16 v[102:105], v[214:217], v[202:205], v[102:105]
	v_mfma_f32_16x16x32_bf16 v[106:109], v[218:221], v[202:205], v[106:109]
	v_mfma_f32_16x16x32_bf16 v[110:113], v[222:225], v[202:205], v[110:113]
	v_mfma_f32_16x16x32_bf16 v[114:117], v[210:213], v[206:209], v[114:117]
	v_mfma_f32_16x16x32_bf16 v[118:121], v[214:217], v[206:209], v[118:121]
	v_mfma_f32_16x16x32_bf16 v[122:125], v[218:221], v[206:209], v[122:125]
	v_mfma_f32_16x16x32_bf16 v[126:129], v[222:225], v[206:209], v[126:129]
	s_setprio 0
	s_add_i32 s61, s61, 0x6000
	s_cmp_eq_u32 s61, 0x12000
	s_cselect_b32 s61, 0, s61
	s_waitcnt vmcnt(0) lgkmcnt(0)
	s_barrier
	v_add_u32_e32 v240, s61, v238
	v_add_u32_e32 v241, s61, v239
	s_setprio 1
	v_mfma_f32_16x16x32_bf16 v[2:5], v[162:165], v[130:133], v[2:5]
	v_mfma_f32_16x16x32_bf16 v[6:9], v[166:169], v[130:133], v[6:9]
	v_mfma_f32_16x16x32_bf16 v[10:13], v[170:173], v[130:133], v[10:13]
	v_mfma_f32_16x16x32_bf16 v[14:17], v[174:177], v[130:133], v[14:17]
	v_mfma_f32_16x16x32_bf16 v[18:21], v[162:165], v[134:137], v[18:21]
	v_mfma_f32_16x16x32_bf16 v[22:25], v[166:169], v[134:137], v[22:25]
	v_mfma_f32_16x16x32_bf16 v[26:29], v[170:173], v[134:137], v[26:29]
	v_mfma_f32_16x16x32_bf16 v[30:33], v[174:177], v[134:137], v[30:33]
	v_mfma_f32_16x16x32_bf16 v[34:37], v[162:165], v[138:141], v[34:37]
	ds_read_b128 v[210:213], v241 offset:0
	v_mfma_f32_16x16x32_bf16 v[38:41], v[166:169], v[138:141], v[38:41]
	ds_read_b128 v[214:217], v241 offset:256
	v_mfma_f32_16x16x32_bf16 v[42:45], v[170:173], v[138:141], v[42:45]
	ds_read_b128 v[218:221], v241 offset:512
	v_mfma_f32_16x16x32_bf16 v[46:49], v[174:177], v[138:141], v[46:49]
	ds_read_b128 v[222:225], v241 offset:768
	v_mfma_f32_16x16x32_bf16 v[50:53], v[162:165], v[142:145], v[50:53]
	ds_read_b128 v[178:181], v240 offset:0
	v_mfma_f32_16x16x32_bf16 v[54:57], v[166:169], v[142:145], v[54:57]
	ds_read_b128 v[182:185], v240 offset:1024
	v_mfma_f32_16x16x32_bf16 v[58:61], v[170:173], v[142:145], v[58:61]
	ds_read_b128 v[186:189], v240 offset:2048
	v_mfma_f32_16x16x32_bf16 v[62:65], v[174:177], v[142:145], v[62:65]
	ds_read_b128 v[190:193], v240 offset:3072
	v_mfma_f32_16x16x32_bf16 v[66:69], v[162:165], v[146:149], v[66:69]
	ds_read_b128 v[194:197], v240 offset:4096
	v_mfma_f32_16x16x32_bf16 v[70:73], v[166:169], v[146:149], v[70:73]
	ds_read_b128 v[198:201], v240 offset:5120
	v_mfma_f32_16x16x32_bf16 v[74:77], v[170:173], v[146:149], v[74:77]
	ds_read_b128 v[202:205], v240 offset:6144
	v_mfma_f32_16x16x32_bf16 v[78:81], v[174:177], v[146:149], v[78:81]
	ds_read_b128 v[206:209], v240 offset:7168
	v_mfma_f32_16x16x32_bf16 v[82:85], v[162:165], v[150:153], v[82:85]
	v_mfma_f32_16x16x32_bf16 v[86:89], v[166:169], v[150:153], v[86:89]
	v_mfma_f32_16x16x32_bf16 v[90:93], v[170:173], v[150:153], v[90:93]
	v_mfma_f32_16x16x32_bf16 v[94:97], v[174:177], v[150:153], v[94:97]
	v_mfma_f32_16x16x32_bf16 v[98:101], v[162:165], v[154:157], v[98:101]
	v_mfma_f32_16x16x32_bf16 v[102:105], v[166:169], v[154:157], v[102:105]
	v_mfma_f32_16x16x32_bf16 v[106:109], v[170:173], v[154:157], v[106:109]
	v_mfma_f32_16x16x32_bf16 v[110:113], v[174:177], v[154:157], v[110:113]
	v_mfma_f32_16x16x32_bf16 v[114:117], v[162:165], v[158:161], v[114:117]
	v_mfma_f32_16x16x32_bf16 v[118:121], v[166:169], v[158:161], v[118:121]
	v_mfma_f32_16x16x32_bf16 v[122:125], v[170:173], v[158:161], v[122:125]
	v_mfma_f32_16x16x32_bf16 v[126:129], v[174:177], v[158:161], v[126:129]
	s_setprio 0
	s_add_i32 s61, s61, 0x6000
	s_cmp_eq_u32 s61, 0x12000
	s_cselect_b32 s61, 0, s61
	s_waitcnt lgkmcnt(0)
	s_barrier
	s_setprio 1
	v_mfma_f32_16x16x32_bf16 v[2:5], v[210:213], v[178:181], v[2:5]
	v_mfma_f32_16x16x32_bf16 v[6:9], v[214:217], v[178:181], v[6:9]
	v_mfma_f32_16x16x32_bf16 v[10:13], v[218:221], v[178:181], v[10:13]
	v_mfma_f32_16x16x32_bf16 v[14:17], v[222:225], v[178:181], v[14:17]
	v_mfma_f32_16x16x32_bf16 v[18:21], v[210:213], v[182:185], v[18:21]
	v_mfma_f32_16x16x32_bf16 v[22:25], v[214:217], v[182:185], v[22:25]
	v_mfma_f32_16x16x32_bf16 v[26:29], v[218:221], v[182:185], v[26:29]
	v_mfma_f32_16x16x32_bf16 v[30:33], v[222:225], v[182:185], v[30:33]
	v_mfma_f32_16x16x32_bf16 v[34:37], v[210:213], v[186:189], v[34:37]
	v_mfma_f32_16x16x32_bf16 v[38:41], v[214:217], v[186:189], v[38:41]
	v_mfma_f32_16x16x32_bf16 v[42:45], v[218:221], v[186:189], v[42:45]
	v_mfma_f32_16x16x32_bf16 v[46:49], v[222:225], v[186:189], v[46:49]
	v_mfma_f32_16x16x32_bf16 v[50:53], v[210:213], v[190:193], v[50:53]
	v_mfma_f32_16x16x32_bf16 v[54:57], v[214:217], v[190:193], v[54:57]
	v_mfma_f32_16x16x32_bf16 v[58:61], v[218:221], v[190:193], v[58:61]
	v_mfma_f32_16x16x32_bf16 v[62:65], v[222:225], v[190:193], v[62:65]
	v_mfma_f32_16x16x32_bf16 v[66:69], v[210:213], v[194:197], v[66:69]
	v_mfma_f32_16x16x32_bf16 v[70:73], v[214:217], v[194:197], v[70:73]
	v_mfma_f32_16x16x32_bf16 v[74:77], v[218:221], v[194:197], v[74:77]
	v_mfma_f32_16x16x32_bf16 v[78:81], v[222:225], v[194:197], v[78:81]
	v_mfma_f32_16x16x32_bf16 v[82:85], v[210:213], v[198:201], v[82:85]
	v_mfma_f32_16x16x32_bf16 v[86:89], v[214:217], v[198:201], v[86:89]
	v_mfma_f32_16x16x32_bf16 v[90:93], v[218:221], v[198:201], v[90:93]
	v_mfma_f32_16x16x32_bf16 v[94:97], v[222:225], v[198:201], v[94:97]
	v_mfma_f32_16x16x32_bf16 v[98:101], v[210:213], v[202:205], v[98:101]
	v_mfma_f32_16x16x32_bf16 v[102:105], v[214:217], v[202:205], v[102:105]
	v_mfma_f32_16x16x32_bf16 v[106:109], v[218:221], v[202:205], v[106:109]
	v_mfma_f32_16x16x32_bf16 v[110:113], v[222:225], v[202:205], v[110:113]
	v_mfma_f32_16x16x32_bf16 v[114:117], v[210:213], v[206:209], v[114:117]
	v_mfma_f32_16x16x32_bf16 v[118:121], v[214:217], v[206:209], v[118:121]
	v_mfma_f32_16x16x32_bf16 v[122:125], v[218:221], v[206:209], v[122:125]
	v_mfma_f32_16x16x32_bf16 v[126:129], v[222:225], v[206:209], v[126:129]
	s_setprio 0
	s_nop 7
	s_nop 1
	s_lshl_b32 s26, s35, 11
	s_lshl_b32 s27, s36, 1
	s_add_i32 s26, s26, s27
	s_add_u32 s18, s52, s26
	s_addc_u32 s19, s53, 0
	v_cvt_pk_bf16_f32 v2, v2, v3
	v_cvt_pk_bf16_f32 v3, v4, v5
	v_cvt_pk_bf16_f32 v4, v6, v7
	v_cvt_pk_bf16_f32 v5, v8, v9
	v_cvt_pk_bf16_f32 v6, v10, v11
	v_cvt_pk_bf16_f32 v7, v12, v13
	v_cvt_pk_bf16_f32 v8, v14, v15
	v_cvt_pk_bf16_f32 v9, v16, v17
	global_store_dwordx4 v242, v[2:5], s[18:19]
	global_store_dwordx4 v242, v[6:9], s[18:19] offset:16
	s_add_u32 s18, s18, 0x8000
	s_addc_u32 s19, s19, 0
	v_cvt_pk_bf16_f32 v18, v18, v19
	v_cvt_pk_bf16_f32 v19, v20, v21
	v_cvt_pk_bf16_f32 v20, v22, v23
	v_cvt_pk_bf16_f32 v21, v24, v25
	v_cvt_pk_bf16_f32 v22, v26, v27
	v_cvt_pk_bf16_f32 v23, v28, v29
	v_cvt_pk_bf16_f32 v24, v30, v31
	v_cvt_pk_bf16_f32 v25, v32, v33
	global_store_dwordx4 v242, v[18:21], s[18:19]
	global_store_dwordx4 v242, v[22:25], s[18:19] offset:16
	s_add_u32 s18, s18, 0x8000
	s_addc_u32 s19, s19, 0
	v_cvt_pk_bf16_f32 v34, v34, v35
	v_cvt_pk_bf16_f32 v35, v36, v37
	v_cvt_pk_bf16_f32 v36, v38, v39
	v_cvt_pk_bf16_f32 v37, v40, v41
	v_cvt_pk_bf16_f32 v38, v42, v43
	v_cvt_pk_bf16_f32 v39, v44, v45
	v_cvt_pk_bf16_f32 v40, v46, v47
	v_cvt_pk_bf16_f32 v41, v48, v49
	global_store_dwordx4 v242, v[34:37], s[18:19]
	global_store_dwordx4 v242, v[38:41], s[18:19] offset:16
	s_add_u32 s18, s18, 0x8000
	s_addc_u32 s19, s19, 0
	v_cvt_pk_bf16_f32 v50, v50, v51
	v_cvt_pk_bf16_f32 v51, v52, v53
	v_cvt_pk_bf16_f32 v52, v54, v55
	v_cvt_pk_bf16_f32 v53, v56, v57
	v_cvt_pk_bf16_f32 v54, v58, v59
	v_cvt_pk_bf16_f32 v55, v60, v61
	v_cvt_pk_bf16_f32 v56, v62, v63
	v_cvt_pk_bf16_f32 v57, v64, v65
	global_store_dwordx4 v242, v[50:53], s[18:19]
	global_store_dwordx4 v242, v[54:57], s[18:19] offset:16
	s_add_u32 s18, s18, 0x8000
	s_addc_u32 s19, s19, 0
	v_cvt_pk_bf16_f32 v66, v66, v67
	v_cvt_pk_bf16_f32 v67, v68, v69
	v_cvt_pk_bf16_f32 v68, v70, v71
	v_cvt_pk_bf16_f32 v69, v72, v73
	v_cvt_pk_bf16_f32 v70, v74, v75
	v_cvt_pk_bf16_f32 v71, v76, v77
	v_cvt_pk_bf16_f32 v72, v78, v79
	v_cvt_pk_bf16_f32 v73, v80, v81
	global_store_dwordx4 v242, v[66:69], s[18:19]
	global_store_dwordx4 v242, v[70:73], s[18:19] offset:16
	s_add_u32 s18, s18, 0x8000
	s_addc_u32 s19, s19, 0
	v_cvt_pk_bf16_f32 v82, v82, v83
	v_cvt_pk_bf16_f32 v83, v84, v85
	v_cvt_pk_bf16_f32 v84, v86, v87
	v_cvt_pk_bf16_f32 v85, v88, v89
	v_cvt_pk_bf16_f32 v86, v90, v91
	v_cvt_pk_bf16_f32 v87, v92, v93
	v_cvt_pk_bf16_f32 v88, v94, v95
	v_cvt_pk_bf16_f32 v89, v96, v97
	global_store_dwordx4 v242, v[82:85], s[18:19]
	global_store_dwordx4 v242, v[86:89], s[18:19] offset:16
	s_add_u32 s18, s18, 0x8000
	s_addc_u32 s19, s19, 0
	v_cvt_pk_bf16_f32 v98, v98, v99
	v_cvt_pk_bf16_f32 v99, v100, v101
	v_cvt_pk_bf16_f32 v100, v102, v103
	v_cvt_pk_bf16_f32 v101, v104, v105
	v_cvt_pk_bf16_f32 v102, v106, v107
	v_cvt_pk_bf16_f32 v103, v108, v109
	v_cvt_pk_bf16_f32 v104, v110, v111
	v_cvt_pk_bf16_f32 v105, v112, v113
	global_store_dwordx4 v242, v[98:101], s[18:19]
	global_store_dwordx4 v242, v[102:105], s[18:19] offset:16
	s_add_u32 s18, s18, 0x8000
	s_addc_u32 s19, s19, 0
	v_cvt_pk_bf16_f32 v114, v114, v115
	v_cvt_pk_bf16_f32 v115, v116, v117
	v_cvt_pk_bf16_f32 v116, v118, v119
	v_cvt_pk_bf16_f32 v117, v120, v121
	v_cvt_pk_bf16_f32 v118, v122, v123
	v_cvt_pk_bf16_f32 v119, v124, v125
	v_cvt_pk_bf16_f32 v120, v126, v127
	v_cvt_pk_bf16_f32 v121, v128, v129
	global_store_dwordx4 v242, v[114:117], s[18:19]
	global_store_dwordx4 v242, v[118:121], s[18:19] offset:16

.Lup_b_f:
	s_mulk_i32 s35, 254
	s_add_i32 s35, s35, s26
	s_lshl_b32 s36, s36, 7
	s_lshl_b32 s26, s41, 6
	s_add_i32 s26, s26, s35
	v_add_u32_e32 v0, s26, v243
	v_lshl_add_u32 v226, v0, 6, v245
	s_lshl_b32 s26, s41, 5
	s_add_i32 s26, s26, s36
	v_add_u32_e32 v0, s26, v243
	v_lshl_add_u32 v230, v0, 6, v246
	v_lshl_add_u32 v231, v0, 6, v247
	s_mov_b32 s60, 0
	s_mov_b32 s61, 0
	s_waitcnt lgkmcnt(0)
	s_sub_u32 s48, s48, 0x80
	s_subb_u32 s49, s49, 0
	s_and_b64 s[26:27], s[22:23], exec
	s_cselect_b32 s26, 0x8400, 0
	s_cselect_b32 s27, 0x2c00, 0
	s_cmp_eq_u32 s41, 3
	s_cbranch_scc1 .Lup_wb
	s_mul_i32 s27, s41, 0x2c00
	s_add_i32 s26, s26, s27
	s_add_u32 s82, s82, s26
	s_addc_u32 s83, s83, 0
	s_branch .Lup_wd
.Lup_wb:
	s_add_u32 s82, s28, s27
	s_addc_u32 s83, s29, 0
.Lup_wd:
	s_mov_b32 s92, 0x3d372713
	s_mov_b32 s93, 0x3d372713
	s_mov_b32 s96, 0x3f4c422a
	s_mov_b32 s97, 0x3f4c422a
	s_mov_b32 s28, 0xc038aa3b
	s_mov_b32 s29, 0xc038aa3b
	s_mov_b64 s[54:55], s[48:49]
	s_mov_b64 s[56:57], s[50:51]
	s_add_i32 m0, s60, s62
	s_nop 0
	global_load_lds_dwordx4 v226, s[54:55]
	global_load_lds_dwordx4 v226, s[54:55] offset:1024
	global_load_lds_dwordx4 v226, s[54:55] offset:2048
	global_load_lds_dwordx4 v226, s[54:55] offset:3072
	s_add_i32 m0, s60, s63
	s_nop 0
	global_load_lds_dwordx4 v230, s[56:57]
	global_load_lds_dwordx4 v231, s[56:57] offset:1024
	s_add_i32 s60, s60, 0x6000
	s_cmp_eq_u32 s60, 0x12000
	s_cselect_b32 s60, 0, s60
	s_add_u32 s54, s54, s72
	s_addc_u32 s55, s55, 0
	s_add_u32 s56, s56, s73
	s_addc_u32 s57, s57, 0
	s_add_i32 m0, s60, s62
	s_nop 0
	global_load_lds_dwordx4 v226, s[54:55]
	global_load_lds_dwordx4 v226, s[54:55] offset:1024
	global_load_lds_dwordx4 v226, s[54:55] offset:2048
	global_load_lds_dwordx4 v226, s[54:55] offset:3072
	s_add_i32 m0, s60, s63
	s_nop 0
	global_load_lds_dwordx4 v230, s[56:57]
	global_load_lds_dwordx4 v231, s[56:57] offset:1024
	s_add_i32 s60, s60, 0x6000
	s_cmp_eq_u32 s60, 0x12000
	s_cselect_b32 s60, 0, s60
	s_add_u32 s54, s54, s72
	s_addc_u32 s55, s55, 0
	s_add_u32 s56, s56, s73
	s_addc_u32 s57, s57, 0
	s_add_i32 m0, s60, s62
	s_nop 0
	global_load_lds_dwordx4 v226, s[54:55]
	global_load_lds_dwordx4 v226, s[54:55] offset:1024
	global_load_lds_dwordx4 v226, s[54:55] offset:2048
	global_load_lds_dwordx4 v226, s[54:55] offset:3072
	s_add_i32 m0, s60, s63
	s_nop 0
	global_load_lds_dwordx4 v230, s[56:57]
	global_load_lds_dwordx4 v231, s[56:57] offset:1024
	s_add_i32 s60, s60, 0x6000
	s_cmp_eq_u32 s60, 0x12000
	s_cselect_b32 s60, 0, s60
	s_add_u32 s54, s54, s72
	s_addc_u32 s55, s55, 0
	s_add_u32 s56, s56, s73
	s_addc_u32 s57, s57, 0
	s_waitcnt vmcnt(12)
	s_barrier
	v_add_u32_e32 v240, s61, v238
	v_add_u32_e32 v241, s61, v239
	ds_read_b128 v[162:165], v241 offset:0
	ds_read_b128 v[166:169], v241 offset:256
	ds_read_b128 v[170:173], v241 offset:2048
	ds_read_b128 v[174:177], v241 offset:2304
	ds_read_b128 v[130:133], v240 offset:0
	ds_read_b128 v[134:137], v240 offset:1024
	ds_read_b128 v[138:141], v240 offset:2048
	ds_read_b128 v[142:145], v240 offset:3072
	ds_read_b128 v[146:149], v240 offset:4096
	ds_read_b128 v[150:153], v240 offset:5120
	ds_read_b128 v[154:157], v240 offset:6144
	ds_read_b128 v[158:161], v240 offset:7168
	s_add_i32 s61, s61, 0x6000
	s_cmp_eq_u32 s61, 0x12000
	s_cselect_b32 s61, 0, s61
	s_add_i32 s38, s34, s71
	s_cmp_lt_i32 s38, s32
	s_cselect_b32 s37, 1, 0
	s_cbranch_scc0 .Lup_nn_a
	s_cmpk_lt_i32 s38, 0xb00
	s_cbranch_scc0 .Lup_lo_a
	s_and_b32 s26, s38, 7
	s_lshr_b32 s27, s38, 3
	s_lshr_b32 s31, s27, 3
	s_and_b32 s27, s27, 7
	s_lshl_b32 s27, s27, 3
	s_add_i32 s30, s27, s26
	s_branch .Lup_go_a

.Lup_nn_a:
	s_waitcnt vmcnt(6) lgkmcnt(0)
	s_barrier
	v_add_u32_e32 v240, s61, v238
	v_add_u32_e32 v241, s61, v239
	s_setprio 1
	s_add_i32 m0, s60, s62
	v_mfma_f32_16x16x32_bf16 v[2:5], v[162:165], v[130:133], 0
	global_load_lds_dwordx4 v226, s[54:55]
	v_mfma_f32_16x16x32_bf16 v[6:9], v[166:169], v[130:133], 0
	global_load_lds_dwordx4 v226, s[54:55] offset:1024
	v_mfma_f32_16x16x32_bf16 v[10:13], v[170:173], v[130:133], 0
	global_load_lds_dwordx4 v226, s[54:55] offset:2048
	v_mfma_f32_16x16x32_bf16 v[14:17], v[174:177], v[130:133], 0
	global_load_lds_dwordx4 v226, s[54:55] offset:3072
	s_add_i32 m0, s60, s63
	v_mfma_f32_16x16x32_bf16 v[18:21], v[162:165], v[134:137], 0
	global_load_lds_dwordx4 v230, s[56:57]
	v_mfma_f32_16x16x32_bf16 v[22:25], v[166:169], v[134:137], 0
	global_load_lds_dwordx4 v231, s[56:57] offset:1024
	v_mfma_f32_16x16x32_bf16 v[26:29], v[170:173], v[134:137], 0
	v_mfma_f32_16x16x32_bf16 v[30:33], v[174:177], v[134:137], 0
	v_mfma_f32_16x16x32_bf16 v[34:37], v[162:165], v[138:141], 0
	ds_read_b128 v[210:213], v241 offset:0
	v_mfma_f32_16x16x32_bf16 v[38:41], v[166:169], v[138:141], 0
	ds_read_b128 v[214:217], v241 offset:256
	v_mfma_f32_16x16x32_bf16 v[42:45], v[170:173], v[138:141], 0
	ds_read_b128 v[218:221], v241 offset:2048
	v_mfma_f32_16x16x32_bf16 v[46:49], v[174:177], v[138:141], 0
	ds_read_b128 v[222:225], v241 offset:2304
	v_mfma_f32_16x16x32_bf16 v[50:53], v[162:165], v[142:145], 0
	ds_read_b128 v[178:181], v240 offset:0
	v_mfma_f32_16x16x32_bf16 v[54:57], v[166:169], v[142:145], 0
	ds_read_b128 v[182:185], v240 offset:1024
	v_mfma_f32_16x16x32_bf16 v[58:61], v[170:173], v[142:145], 0
	ds_read_b128 v[186:189], v240 offset:2048
	v_mfma_f32_16x16x32_bf16 v[62:65], v[174:177], v[142:145], 0
	ds_read_b128 v[190:193], v240 offset:3072
	v_mfma_f32_16x16x32_bf16 v[66:69], v[162:165], v[146:149], 0
	ds_read_b128 v[194:197], v240 offset:4096
	v_mfma_f32_16x16x32_bf16 v[70:73], v[166:169], v[146:149], 0
	ds_read_b128 v[198:201], v240 offset:5120
	v_mfma_f32_16x16x32_bf16 v[74:77], v[170:173], v[146:149], 0
	ds_read_b128 v[202:205], v240 offset:6144
	v_mfma_f32_16x16x32_bf16 v[78:81], v[174:177], v[146:149], 0
	ds_read_b128 v[206:209], v240 offset:7168
	v_mfma_f32_16x16x32_bf16 v[82:85], v[162:165], v[150:153], 0
	v_mfma_f32_16x16x32_bf16 v[86:89], v[166:169], v[150:153], 0
	v_mfma_f32_16x16x32_bf16 v[90:93], v[170:173], v[150:153], 0
	v_mfma_f32_16x16x32_bf16 v[94:97], v[174:177], v[150:153], 0
	v_mfma_f32_16x16x32_bf16 v[98:101], v[162:165], v[154:157], 0
	v_mfma_f32_16x16x32_bf16 v[102:105], v[166:169], v[154:157], 0
	v_mfma_f32_16x16x32_bf16 v[106:109], v[170:173], v[154:157], 0
	v_mfma_f32_16x16x32_bf16 v[110:113], v[174:177], v[154:157], 0
	v_mfma_f32_16x16x32_bf16 v[114:117], v[162:165], v[158:161], 0
	v_mfma_f32_16x16x32_bf16 v[118:121], v[166:169], v[158:161], 0
	v_mfma_f32_16x16x32_bf16 v[122:125], v[170:173], v[158:161], 0
	v_mfma_f32_16x16x32_bf16 v[126:129], v[174:177], v[158:161], 0
	s_setprio 0
	s_add_i32 s60, s60, 0x6000
	s_cmp_eq_u32 s60, 0x12000
	s_cselect_b32 s60, 0, s60
	s_add_u32 s54, s54, s72
	s_addc_u32 s55, s55, 0
	s_add_u32 s56, s56, s73
	s_addc_u32 s57, s57, 0
	s_add_i32 s61, s61, 0x6000
	s_cmp_eq_u32 s61, 0x12000
	s_cselect_b32 s61, 0, s61
	v_mbcnt_lo_u32_b32 v0, -1, 0
	v_lshlrev_b32_e32 v0, 4, v0
	s_lshl_b32 s26, s36, 1
	v_add_u32_e32 v0, s26, v0
	s_lshl_b32 s26, s41, 8
	s_add_i32 m0, s26, 0x13010
	s_mov_b64 exec, 0xffff
	global_load_lds_dwordx4 v0, s[82:83]
	s_mov_b64 exec, -1
	s_waitcnt vmcnt(6) lgkmcnt(0)
	s_barrier
	v_add_u32_e32 v240, s61, v238
	v_add_u32_e32 v241, s61, v239
	s_setprio 1
	s_add_i32 m0, s60, s62
	v_mfma_f32_16x16x32_bf16 v[2:5], v[210:213], v[178:181], v[2:5]
	global_load_lds_dwordx4 v226, s[54:55]
	v_mfma_f32_16x16x32_bf16 v[6:9], v[214:217], v[178:181], v[6:9]
	global_load_lds_dwordx4 v226, s[54:55] offset:1024
	v_mfma_f32_16x16x32_bf16 v[10:13], v[218:221], v[178:181], v[10:13]
	global_load_lds_dwordx4 v226, s[54:55] offset:2048
	v_mfma_f32_16x16x32_bf16 v[14:17], v[222:225], v[178:181], v[14:17]
	global_load_lds_dwordx4 v226, s[54:55] offset:3072
	s_add_i32 m0, s60, s63
	v_mfma_f32_16x16x32_bf16 v[18:21], v[210:213], v[182:185], v[18:21]
	global_load_lds_dwordx4 v230, s[56:57]
	v_mfma_f32_16x16x32_bf16 v[22:25], v[214:217], v[182:185], v[22:25]
	global_load_lds_dwordx4 v231, s[56:57] offset:1024
	v_mfma_f32_16x16x32_bf16 v[26:29], v[218:221], v[182:185], v[26:29]
	v_mfma_f32_16x16x32_bf16 v[30:33], v[222:225], v[182:185], v[30:33]
	v_mfma_f32_16x16x32_bf16 v[34:37], v[210:213], v[186:189], v[34:37]
	ds_read_b128 v[162:165], v241 offset:0
	v_mfma_f32_16x16x32_bf16 v[38:41], v[214:217], v[186:189], v[38:41]
	ds_read_b128 v[166:169], v241 offset:256
	v_mfma_f32_16x16x32_bf16 v[42:45], v[218:221], v[186:189], v[42:45]
	ds_read_b128 v[170:173], v241 offset:2048
	v_mfma_f32_16x16x32_bf16 v[46:49], v[222:225], v[186:189], v[46:49]
	ds_read_b128 v[174:177], v241 offset:2304
	v_mfma_f32_16x16x32_bf16 v[50:53], v[210:213], v[190:193], v[50:53]
	ds_read_b128 v[130:133], v240 offset:0
	v_mfma_f32_16x16x32_bf16 v[54:57], v[214:217], v[190:193], v[54:57]
	ds_read_b128 v[134:137], v240 offset:1024
	v_mfma_f32_16x16x32_bf16 v[58:61], v[218:221], v[190:193], v[58:61]
	ds_read_b128 v[138:141], v240 offset:2048
	v_mfma_f32_16x16x32_bf16 v[62:65], v[222:225], v[190:193], v[62:65]
	ds_read_b128 v[142:145], v240 offset:3072
	v_mfma_f32_16x16x32_bf16 v[66:69], v[210:213], v[194:197], v[66:69]
	ds_read_b128 v[146:149], v240 offset:4096
	v_mfma_f32_16x16x32_bf16 v[70:73], v[214:217], v[194:197], v[70:73]
	ds_read_b128 v[150:153], v240 offset:5120
	v_mfma_f32_16x16x32_bf16 v[74:77], v[218:221], v[194:197], v[74:77]
	ds_read_b128 v[154:157], v240 offset:6144
	v_mfma_f32_16x16x32_bf16 v[78:81], v[222:225], v[194:197], v[78:81]
	ds_read_b128 v[158:161], v240 offset:7168
	v_mfma_f32_16x16x32_bf16 v[82:85], v[210:213], v[198:201], v[82:85]
	v_mfma_f32_16x16x32_bf16 v[86:89], v[214:217], v[198:201], v[86:89]
	v_mfma_f32_16x16x32_bf16 v[90:93], v[218:221], v[198:201], v[90:93]
	v_mfma_f32_16x16x32_bf16 v[94:97], v[222:225], v[198:201], v[94:97]
	v_mfma_f32_16x16x32_bf16 v[98:101], v[210:213], v[202:205], v[98:101]
	v_mfma_f32_16x16x32_bf16 v[102:105], v[214:217], v[202:205], v[102:105]
	v_mfma_f32_16x16x32_bf16 v[106:109], v[218:221], v[202:205], v[106:109]
	v_mfma_f32_16x16x32_bf16 v[110:113], v[222:225], v[202:205], v[110:113]
	v_mfma_f32_16x16x32_bf16 v[114:117], v[210:213], v[206:209], v[114:117]
	v_mfma_f32_16x16x32_bf16 v[118:121], v[214:217], v[206:209], v[118:121]
	v_mfma_f32_16x16x32_bf16 v[122:125], v[218:221], v[206:209], v[122:125]
	v_mfma_f32_16x16x32_bf16 v[126:129], v[222:225], v[206:209], v[126:129]
	s_setprio 0
	s_add_i32 s60, s60, 0x6000
	s_cmp_eq_u32 s60, 0x12000
	s_cselect_b32 s60, 0, s60
	s_add_u32 s54, s54, s72
	s_addc_u32 s55, s55, 0
	s_add_u32 s56, s56, s73
	s_addc_u32 s57, s57, 0
	s_add_i32 s61, s61, 0x6000
	s_cmp_eq_u32 s61, 0x12000
	s_cselect_b32 s61, 0, s61
	s_branch .Lup_main

.Lup_nn_b:
	s_waitcnt vmcnt(14) lgkmcnt(0)
	s_barrier
	v_add_u32_e32 v240, s61, v238
	v_add_u32_e32 v241, s61, v239
	s_setprio 1
	s_add_i32 m0, s60, s62
	v_mfma_f32_16x16x32_bf16 v[2:5], v[162:165], v[130:133], 0
	global_load_lds_dwordx4 v226, s[54:55]
	v_mfma_f32_16x16x32_bf16 v[6:9], v[166:169], v[130:133], 0
	global_load_lds_dwordx4 v226, s[54:55] offset:1024
	v_mfma_f32_16x16x32_bf16 v[10:13], v[170:173], v[130:133], 0
	global_load_lds_dwordx4 v226, s[54:55] offset:2048
	v_mfma_f32_16x16x32_bf16 v[14:17], v[174:177], v[130:133], 0
	global_load_lds_dwordx4 v226, s[54:55] offset:3072
	s_add_i32 m0, s60, s63
	v_mfma_f32_16x16x32_bf16 v[18:21], v[162:165], v[134:137], 0
	global_load_lds_dwordx4 v230, s[56:57]
	v_mfma_f32_16x16x32_bf16 v[22:25], v[166:169], v[134:137], 0
	global_load_lds_dwordx4 v231, s[56:57] offset:1024
	v_mfma_f32_16x16x32_bf16 v[26:29], v[170:173], v[134:137], 0
	v_mfma_f32_16x16x32_bf16 v[30:33], v[174:177], v[134:137], 0
	v_mfma_f32_16x16x32_bf16 v[34:37], v[162:165], v[138:141], 0
	ds_read_b128 v[210:213], v241 offset:0
	v_mfma_f32_16x16x32_bf16 v[38:41], v[166:169], v[138:141], 0
	ds_read_b128 v[214:217], v241 offset:256
	v_mfma_f32_16x16x32_bf16 v[42:45], v[170:173], v[138:141], 0
	ds_read_b128 v[218:221], v241 offset:2048
	v_mfma_f32_16x16x32_bf16 v[46:49], v[174:177], v[138:141], 0
	ds_read_b128 v[222:225], v241 offset:2304
	v_mfma_f32_16x16x32_bf16 v[50:53], v[162:165], v[142:145], 0
	ds_read_b128 v[178:181], v240 offset:0
	v_mfma_f32_16x16x32_bf16 v[54:57], v[166:169], v[142:145], 0
	ds_read_b128 v[182:185], v240 offset:1024
	v_mfma_f32_16x16x32_bf16 v[58:61], v[170:173], v[142:145], 0
	ds_read_b128 v[186:189], v240 offset:2048
	v_mfma_f32_16x16x32_bf16 v[62:65], v[174:177], v[142:145], 0
	ds_read_b128 v[190:193], v240 offset:3072
	v_mfma_f32_16x16x32_bf16 v[66:69], v[162:165], v[146:149], 0
	ds_read_b128 v[194:197], v240 offset:4096
	v_mfma_f32_16x16x32_bf16 v[70:73], v[166:169], v[146:149], 0
	ds_read_b128 v[198:201], v240 offset:5120
	v_mfma_f32_16x16x32_bf16 v[74:77], v[170:173], v[146:149], 0
	ds_read_b128 v[202:205], v240 offset:6144
	v_mfma_f32_16x16x32_bf16 v[78:81], v[174:177], v[146:149], 0
	ds_read_b128 v[206:209], v240 offset:7168
	v_mfma_f32_16x16x32_bf16 v[82:85], v[162:165], v[150:153], 0
	v_mfma_f32_16x16x32_bf16 v[86:89], v[166:169], v[150:153], 0
	v_mfma_f32_16x16x32_bf16 v[90:93], v[170:173], v[150:153], 0
	v_mfma_f32_16x16x32_bf16 v[94:97], v[174:177], v[150:153], 0
	v_mfma_f32_16x16x32_bf16 v[98:101], v[162:165], v[154:157], 0
	v_mfma_f32_16x16x32_bf16 v[102:105], v[166:169], v[154:157], 0
	v_mfma_f32_16x16x32_bf16 v[106:109], v[170:173], v[154:157], 0
	v_mfma_f32_16x16x32_bf16 v[110:113], v[174:177], v[154:157], 0
	v_mfma_f32_16x16x32_bf16 v[114:117], v[162:165], v[158:161], 0
	v_mfma_f32_16x16x32_bf16 v[118:121], v[166:169], v[158:161], 0
	v_mfma_f32_16x16x32_bf16 v[122:125], v[170:173], v[158:161], 0
	v_mfma_f32_16x16x32_bf16 v[126:129], v[174:177], v[158:161], 0
	s_setprio 0
	s_add_i32 s60, s60, 0x6000
	s_cmp_eq_u32 s60, 0x12000
	s_cselect_b32 s60, 0, s60
	s_add_u32 s54, s54, s72
	s_addc_u32 s55, s55, 0
	s_add_u32 s56, s56, s73
	s_addc_u32 s57, s57, 0
	s_add_i32 s61, s61, 0x6000
	s_cmp_eq_u32 s61, 0x12000
	s_cselect_b32 s61, 0, s61
	v_mbcnt_lo_u32_b32 v0, -1, 0
	v_lshlrev_b32_e32 v0, 4, v0
	s_lshl_b32 s26, s36, 1
	v_add_u32_e32 v0, s26, v0
	s_lshl_b32 s26, s41, 8
	s_add_i32 m0, s26, 0x13010
	s_mov_b64 exec, 0xffff
	global_load_lds_dwordx4 v0, s[82:83]
	s_mov_b64 exec, -1
	s_waitcnt vmcnt(14) lgkmcnt(0)
	s_barrier
	v_add_u32_e32 v240, s61, v238
	v_add_u32_e32 v241, s61, v239
	s_setprio 1
	s_add_i32 m0, s60, s62
	v_mfma_f32_16x16x32_bf16 v[2:5], v[210:213], v[178:181], v[2:5]
	global_load_lds_dwordx4 v226, s[54:55]
	v_mfma_f32_16x16x32_bf16 v[6:9], v[214:217], v[178:181], v[6:9]
	global_load_lds_dwordx4 v226, s[54:55] offset:1024
	v_mfma_f32_16x16x32_bf16 v[10:13], v[218:221], v[178:181], v[10:13]
	global_load_lds_dwordx4 v226, s[54:55] offset:2048
	v_mfma_f32_16x16x32_bf16 v[14:17], v[222:225], v[178:181], v[14:17]
	global_load_lds_dwordx4 v226, s[54:55] offset:3072
	s_add_i32 m0, s60, s63
	v_mfma_f32_16x16x32_bf16 v[18:21], v[210:213], v[182:185], v[18:21]
	global_load_lds_dwordx4 v230, s[56:57]
	v_mfma_f32_16x16x32_bf16 v[22:25], v[214:217], v[182:185], v[22:25]
	global_load_lds_dwordx4 v231, s[56:57] offset:1024
	v_mfma_f32_16x16x32_bf16 v[26:29], v[218:221], v[182:185], v[26:29]
	v_mfma_f32_16x16x32_bf16 v[30:33], v[222:225], v[182:185], v[30:33]
	v_mfma_f32_16x16x32_bf16 v[34:37], v[210:213], v[186:189], v[34:37]
	ds_read_b128 v[162:165], v241 offset:0
	v_mfma_f32_16x16x32_bf16 v[38:41], v[214:217], v[186:189], v[38:41]
	ds_read_b128 v[166:169], v241 offset:256
	v_mfma_f32_16x16x32_bf16 v[42:45], v[218:221], v[186:189], v[42:45]
	ds_read_b128 v[170:173], v241 offset:2048
	v_mfma_f32_16x16x32_bf16 v[46:49], v[222:225], v[186:189], v[46:49]
	ds_read_b128 v[174:177], v241 offset:2304
	v_mfma_f32_16x16x32_bf16 v[50:53], v[210:213], v[190:193], v[50:53]
	ds_read_b128 v[130:133], v240 offset:0
	v_mfma_f32_16x16x32_bf16 v[54:57], v[214:217], v[190:193], v[54:57]
	ds_read_b128 v[134:137], v240 offset:1024
	v_mfma_f32_16x16x32_bf16 v[58:61], v[218:221], v[190:193], v[58:61]
	ds_read_b128 v[138:141], v240 offset:2048
	v_mfma_f32_16x16x32_bf16 v[62:65], v[222:225], v[190:193], v[62:65]
	ds_read_b128 v[142:145], v240 offset:3072
	v_mfma_f32_16x16x32_bf16 v[66:69], v[210:213], v[194:197], v[66:69]
	ds_read_b128 v[146:149], v240 offset:4096
	v_mfma_f32_16x16x32_bf16 v[70:73], v[214:217], v[194:197], v[70:73]
	ds_read_b128 v[150:153], v240 offset:5120
	v_mfma_f32_16x16x32_bf16 v[74:77], v[218:221], v[194:197], v[74:77]
	ds_read_b128 v[154:157], v240 offset:6144
	v_mfma_f32_16x16x32_bf16 v[78:81], v[222:225], v[194:197], v[78:81]
	ds_read_b128 v[158:161], v240 offset:7168
	v_mfma_f32_16x16x32_bf16 v[82:85], v[210:213], v[198:201], v[82:85]
	v_mfma_f32_16x16x32_bf16 v[86:89], v[214:217], v[198:201], v[86:89]
	v_mfma_f32_16x16x32_bf16 v[90:93], v[218:221], v[198:201], v[90:93]
	v_mfma_f32_16x16x32_bf16 v[94:97], v[222:225], v[198:201], v[94:97]
	v_mfma_f32_16x16x32_bf16 v[98:101], v[210:213], v[202:205], v[98:101]
	v_mfma_f32_16x16x32_bf16 v[102:105], v[214:217], v[202:205], v[102:105]
	v_mfma_f32_16x16x32_bf16 v[106:109], v[218:221], v[202:205], v[106:109]
	v_mfma_f32_16x16x32_bf16 v[110:113], v[222:225], v[202:205], v[110:113]
	v_mfma_f32_16x16x32_bf16 v[114:117], v[210:213], v[206:209], v[114:117]
	v_mfma_f32_16x16x32_bf16 v[118:121], v[214:217], v[206:209], v[118:121]
	v_mfma_f32_16x16x32_bf16 v[122:125], v[218:221], v[206:209], v[122:125]
	v_mfma_f32_16x16x32_bf16 v[126:129], v[222:225], v[206:209], v[126:129]
	s_setprio 0
	s_add_i32 s60, s60, 0x6000
	s_cmp_eq_u32 s60, 0x12000
	s_cselect_b32 s60, 0, s60
	s_add_u32 s54, s54, s72
	s_addc_u32 s55, s55, 0
	s_add_u32 s56, s56, s73
	s_addc_u32 s57, s57, 0
	s_add_i32 s61, s61, 0x6000
	s_cmp_eq_u32 s61, 0x12000
	s_cselect_b32 s61, 0, s61

.Lup_kloop:
	s_waitcnt vmcnt(6) lgkmcnt(0)
	s_barrier
	v_add_u32_e32 v240, s61, v238
	v_add_u32_e32 v241, s61, v239
	s_setprio 1
	s_add_i32 m0, s60, s62
	v_mfma_f32_16x16x32_bf16 v[2:5], v[162:165], v[130:133], v[2:5]
	global_load_lds_dwordx4 v226, s[54:55]
	v_mfma_f32_16x16x32_bf16 v[6:9], v[166:169], v[130:133], v[6:9]
	global_load_lds_dwordx4 v226, s[54:55] offset:1024
	v_mfma_f32_16x16x32_bf16 v[10:13], v[170:173], v[130:133], v[10:13]
	global_load_lds_dwordx4 v226, s[54:55] offset:2048
	v_mfma_f32_16x16x32_bf16 v[14:17], v[174:177], v[130:133], v[14:17]
	global_load_lds_dwordx4 v226, s[54:55] offset:3072
	s_add_i32 m0, s60, s63
	v_mfma_f32_16x16x32_bf16 v[18:21], v[162:165], v[134:137], v[18:21]
	global_load_lds_dwordx4 v230, s[56:57]
	v_mfma_f32_16x16x32_bf16 v[22:25], v[166:169], v[134:137], v[22:25]
	global_load_lds_dwordx4 v231, s[56:57] offset:1024
	v_mfma_f32_16x16x32_bf16 v[26:29], v[170:173], v[134:137], v[26:29]
	v_mfma_f32_16x16x32_bf16 v[30:33], v[174:177], v[134:137], v[30:33]
	v_mfma_f32_16x16x32_bf16 v[34:37], v[162:165], v[138:141], v[34:37]
	ds_read_b128 v[210:213], v241 offset:0
	v_mfma_f32_16x16x32_bf16 v[38:41], v[166:169], v[138:141], v[38:41]
	ds_read_b128 v[214:217], v241 offset:256
	v_mfma_f32_16x16x32_bf16 v[42:45], v[170:173], v[138:141], v[42:45]
	ds_read_b128 v[218:221], v241 offset:2048
	v_mfma_f32_16x16x32_bf16 v[46:49], v[174:177], v[138:141], v[46:49]
	ds_read_b128 v[222:225], v241 offset:2304
	v_mfma_f32_16x16x32_bf16 v[50:53], v[162:165], v[142:145], v[50:53]
	ds_read_b128 v[178:181], v240 offset:0
	v_mfma_f32_16x16x32_bf16 v[54:57], v[166:169], v[142:145], v[54:57]
	ds_read_b128 v[182:185], v240 offset:1024
	v_mfma_f32_16x16x32_bf16 v[58:61], v[170:173], v[142:145], v[58:61]
	ds_read_b128 v[186:189], v240 offset:2048
	v_mfma_f32_16x16x32_bf16 v[62:65], v[174:177], v[142:145], v[62:65]
	ds_read_b128 v[190:193], v240 offset:3072
	v_mfma_f32_16x16x32_bf16 v[66:69], v[162:165], v[146:149], v[66:69]
	ds_read_b128 v[194:197], v240 offset:4096
	v_mfma_f32_16x16x32_bf16 v[70:73], v[166:169], v[146:149], v[70:73]
	ds_read_b128 v[198:201], v240 offset:5120
	v_mfma_f32_16x16x32_bf16 v[74:77], v[170:173], v[146:149], v[74:77]
	ds_read_b128 v[202:205], v240 offset:6144
	v_mfma_f32_16x16x32_bf16 v[78:81], v[174:177], v[146:149], v[78:81]
	ds_read_b128 v[206:209], v240 offset:7168
	v_mfma_f32_16x16x32_bf16 v[82:85], v[162:165], v[150:153], v[82:85]
	v_mfma_f32_16x16x32_bf16 v[86:89], v[166:169], v[150:153], v[86:89]
	v_mfma_f32_16x16x32_bf16 v[90:93], v[170:173], v[150:153], v[90:93]
	v_mfma_f32_16x16x32_bf16 v[94:97], v[174:177], v[150:153], v[94:97]
	v_mfma_f32_16x16x32_bf16 v[98:101], v[162:165], v[154:157], v[98:101]
	v_mfma_f32_16x16x32_bf16 v[102:105], v[166:169], v[154:157], v[102:105]
	v_mfma_f32_16x16x32_bf16 v[106:109], v[170:173], v[154:157], v[106:109]
	v_mfma_f32_16x16x32_bf16 v[110:113], v[174:177], v[154:157], v[110:113]
	v_mfma_f32_16x16x32_bf16 v[114:117], v[162:165], v[158:161], v[114:117]
	v_mfma_f32_16x16x32_bf16 v[118:121], v[166:169], v[158:161], v[118:121]
	v_mfma_f32_16x16x32_bf16 v[122:125], v[170:173], v[158:161], v[122:125]
	v_mfma_f32_16x16x32_bf16 v[126:129], v[174:177], v[158:161], v[126:129]
	s_setprio 0
	s_add_i32 s60, s60, 0x6000
	s_cmp_eq_u32 s60, 0x12000
	s_cselect_b32 s60, 0, s60
	s_add_u32 s54, s54, s72
	s_addc_u32 s55, s55, 0
	s_add_u32 s56, s56, s73
	s_addc_u32 s57, s57, 0
	s_add_i32 s61, s61, 0x6000
	s_cmp_eq_u32 s61, 0x12000
	s_cselect_b32 s61, 0, s61
	s_waitcnt vmcnt(6) lgkmcnt(0)
	s_barrier
	v_add_u32_e32 v240, s61, v238
	v_add_u32_e32 v241, s61, v239
	s_setprio 1
	s_add_i32 m0, s60, s62
	v_mfma_f32_16x16x32_bf16 v[2:5], v[210:213], v[178:181], v[2:5]
	global_load_lds_dwordx4 v226, s[54:55]
	v_mfma_f32_16x16x32_bf16 v[6:9], v[214:217], v[178:181], v[6:9]
	global_load_lds_dwordx4 v226, s[54:55] offset:1024
	v_mfma_f32_16x16x32_bf16 v[10:13], v[218:221], v[178:181], v[10:13]
	global_load_lds_dwordx4 v226, s[54:55] offset:2048
	v_mfma_f32_16x16x32_bf16 v[14:17], v[222:225], v[178:181], v[14:17]
	global_load_lds_dwordx4 v226, s[54:55] offset:3072
	s_add_i32 m0, s60, s63
	v_mfma_f32_16x16x32_bf16 v[18:21], v[210:213], v[182:185], v[18:21]
	global_load_lds_dwordx4 v230, s[56:57]
	v_mfma_f32_16x16x32_bf16 v[22:25], v[214:217], v[182:185], v[22:25]
	global_load_lds_dwordx4 v231, s[56:57] offset:1024
	v_mfma_f32_16x16x32_bf16 v[26:29], v[218:221], v[182:185], v[26:29]
	v_mfma_f32_16x16x32_bf16 v[30:33], v[222:225], v[182:185], v[30:33]
	v_mfma_f32_16x16x32_bf16 v[34:37], v[210:213], v[186:189], v[34:37]
	ds_read_b128 v[162:165], v241 offset:0
	v_mfma_f32_16x16x32_bf16 v[38:41], v[214:217], v[186:189], v[38:41]
	ds_read_b128 v[166:169], v241 offset:256
	v_mfma_f32_16x16x32_bf16 v[42:45], v[218:221], v[186:189], v[42:45]
	ds_read_b128 v[170:173], v241 offset:2048
	v_mfma_f32_16x16x32_bf16 v[46:49], v[222:225], v[186:189], v[46:49]
	ds_read_b128 v[174:177], v241 offset:2304
	v_mfma_f32_16x16x32_bf16 v[50:53], v[210:213], v[190:193], v[50:53]
	ds_read_b128 v[130:133], v240 offset:0
	v_mfma_f32_16x16x32_bf16 v[54:57], v[214:217], v[190:193], v[54:57]
	ds_read_b128 v[134:137], v240 offset:1024
	v_mfma_f32_16x16x32_bf16 v[58:61], v[218:221], v[190:193], v[58:61]
	ds_read_b128 v[138:141], v240 offset:2048
	v_mfma_f32_16x16x32_bf16 v[62:65], v[222:225], v[190:193], v[62:65]
	ds_read_b128 v[142:145], v240 offset:3072
	v_mfma_f32_16x16x32_bf16 v[66:69], v[210:213], v[194:197], v[66:69]
	ds_read_b128 v[146:149], v240 offset:4096
	v_mfma_f32_16x16x32_bf16 v[70:73], v[214:217], v[194:197], v[70:73]
	ds_read_b128 v[150:153], v240 offset:5120
	v_mfma_f32_16x16x32_bf16 v[74:77], v[218:221], v[194:197], v[74:77]
	ds_read_b128 v[154:157], v240 offset:6144
	v_mfma_f32_16x16x32_bf16 v[78:81], v[222:225], v[194:197], v[78:81]
	ds_read_b128 v[158:161], v240 offset:7168
	v_mfma_f32_16x16x32_bf16 v[82:85], v[210:213], v[198:201], v[82:85]
	v_mfma_f32_16x16x32_bf16 v[86:89], v[214:217], v[198:201], v[86:89]
	v_mfma_f32_16x16x32_bf16 v[90:93], v[218:221], v[198:201], v[90:93]
	v_mfma_f32_16x16x32_bf16 v[94:97], v[222:225], v[198:201], v[94:97]
	v_mfma_f32_16x16x32_bf16 v[98:101], v[210:213], v[202:205], v[98:101]
	v_mfma_f32_16x16x32_bf16 v[102:105], v[214:217], v[202:205], v[102:105]
	v_mfma_f32_16x16x32_bf16 v[106:109], v[218:221], v[202:205], v[106:109]
	v_mfma_f32_16x16x32_bf16 v[110:113], v[222:225], v[202:205], v[110:113]
	v_mfma_f32_16x16x32_bf16 v[114:117], v[210:213], v[206:209], v[114:117]
	v_mfma_f32_16x16x32_bf16 v[118:121], v[214:217], v[206:209], v[118:121]
	v_mfma_f32_16x16x32_bf16 v[122:125], v[218:221], v[206:209], v[122:125]
	v_mfma_f32_16x16x32_bf16 v[126:129], v[222:225], v[206:209], v[126:129]
	s_setprio 0
	s_add_i32 s60, s60, 0x6000
	s_cmp_eq_u32 s60, 0x12000
	s_cselect_b32 s60, 0, s60
	s_add_u32 s54, s54, s72
	s_addc_u32 s55, s55, 0
	s_add_u32 s56, s56, s73
	s_addc_u32 s57, s57, 0
	s_add_i32 s61, s61, 0x6000
	s_cmp_eq_u32 s61, 0x12000
	s_cselect_b32 s61, 0, s61
	s_add_i32 s40, s40, -1
	s_cmp_lg_u32 s40, 0
	s_cbranch_scc1 .Lup_kloop
	s_cmp_eq_u32 s37, 0
	s_cbranch_scc1 .Lup_tail_last
	s_waitcnt vmcnt(6) lgkmcnt(0)
	s_barrier
	v_add_u32_e32 v240, s61, v238
	v_add_u32_e32 v241, s61, v239
	s_setprio 1
	s_add_i32 m0, s60, s62
	v_mfma_f32_16x16x32_bf16 v[2:5], v[162:165], v[130:133], v[2:5]
	global_load_lds_dwordx4 v226, s[54:55]
	v_mfma_f32_16x16x32_bf16 v[6:9], v[166:169], v[130:133], v[6:9]
	global_load_lds_dwordx4 v226, s[54:55] offset:1024
	v_mfma_f32_16x16x32_bf16 v[10:13], v[170:173], v[130:133], v[10:13]
	global_load_lds_dwordx4 v226, s[54:55] offset:2048
	v_mfma_f32_16x16x32_bf16 v[14:17], v[174:177], v[130:133], v[14:17]
	global_load_lds_dwordx4 v226, s[54:55] offset:3072
	s_add_i32 m0, s60, s63
	v_mfma_f32_16x16x32_bf16 v[18:21], v[162:165], v[134:137], v[18:21]
	global_load_lds_dwordx4 v230, s[56:57]
	v_mfma_f32_16x16x32_bf16 v[22:25], v[166:169], v[134:137], v[22:25]
	global_load_lds_dwordx4 v231, s[56:57] offset:1024
	v_mfma_f32_16x16x32_bf16 v[26:29], v[170:173], v[134:137], v[26:29]
	v_mfma_f32_16x16x32_bf16 v[30:33], v[174:177], v[134:137], v[30:33]
	v_mfma_f32_16x16x32_bf16 v[34:37], v[162:165], v[138:141], v[34:37]
	ds_read_b128 v[210:213], v241 offset:0
	v_mfma_f32_16x16x32_bf16 v[38:41], v[166:169], v[138:141], v[38:41]
	ds_read_b128 v[214:217], v241 offset:256
	v_mfma_f32_16x16x32_bf16 v[42:45], v[170:173], v[138:141], v[42:45]
	ds_read_b128 v[218:221], v241 offset:2048
	v_mfma_f32_16x16x32_bf16 v[46:49], v[174:177], v[138:141], v[46:49]
	ds_read_b128 v[222:225], v241 offset:2304
	v_mfma_f32_16x16x32_bf16 v[50:53], v[162:165], v[142:145], v[50:53]
	ds_read_b128 v[178:181], v240 offset:0
	v_mfma_f32_16x16x32_bf16 v[54:57], v[166:169], v[142:145], v[54:57]
	ds_read_b128 v[182:185], v240 offset:1024
	v_mfma_f32_16x16x32_bf16 v[58:61], v[170:173], v[142:145], v[58:61]
	ds_read_b128 v[186:189], v240 offset:2048
	v_mfma_f32_16x16x32_bf16 v[62:65], v[174:177], v[142:145], v[62:65]
	ds_read_b128 v[190:193], v240 offset:3072
	v_mfma_f32_16x16x32_bf16 v[66:69], v[162:165], v[146:149], v[66:69]
	ds_read_b128 v[194:197], v240 offset:4096
	v_mfma_f32_16x16x32_bf16 v[70:73], v[166:169], v[146:149], v[70:73]
	ds_read_b128 v[198:201], v240 offset:5120
	v_mfma_f32_16x16x32_bf16 v[74:77], v[170:173], v[146:149], v[74:77]
	ds_read_b128 v[202:205], v240 offset:6144
	v_mfma_f32_16x16x32_bf16 v[78:81], v[174:177], v[146:149], v[78:81]
	ds_read_b128 v[206:209], v240 offset:7168
	v_mfma_f32_16x16x32_bf16 v[82:85], v[162:165], v[150:153], v[82:85]
	v_mfma_f32_16x16x32_bf16 v[86:89], v[166:169], v[150:153], v[86:89]
	v_mfma_f32_16x16x32_bf16 v[90:93], v[170:173], v[150:153], v[90:93]
	v_mfma_f32_16x16x32_bf16 v[94:97], v[174:177], v[150:153], v[94:97]
	v_mfma_f32_16x16x32_bf16 v[98:101], v[162:165], v[154:157], v[98:101]
	v_mfma_f32_16x16x32_bf16 v[102:105], v[166:169], v[154:157], v[102:105]
	v_mfma_f32_16x16x32_bf16 v[106:109], v[170:173], v[154:157], v[106:109]
	v_mfma_f32_16x16x32_bf16 v[110:113], v[174:177], v[154:157], v[110:113]
	v_mfma_f32_16x16x32_bf16 v[114:117], v[162:165], v[158:161], v[114:117]
	v_mfma_f32_16x16x32_bf16 v[118:121], v[166:169], v[158:161], v[118:121]
	v_mfma_f32_16x16x32_bf16 v[122:125], v[170:173], v[158:161], v[122:125]
	v_mfma_f32_16x16x32_bf16 v[126:129], v[174:177], v[158:161], v[126:129]
	s_setprio 0
	s_add_i32 s60, s60, 0x6000
	s_cmp_eq_u32 s60, 0x12000
	s_cselect_b32 s60, 0, s60
	s_add_u32 s54, s54, s72
	s_addc_u32 s55, s55, 0
	s_add_u32 s56, s56, s73
	s_addc_u32 s57, s57, 0
	s_add_i32 s61, s61, 0x6000
	s_cmp_eq_u32 s61, 0x12000
	s_cselect_b32 s61, 0, s61
	v_mov_b32_e32 v226, v232
	v_mov_b32_e32 v230, v236
	v_mov_b32_e32 v231, v237
	s_mov_b64 s[54:55], s[48:49]
	s_mov_b64 s[56:57], s[50:51]
	s_waitcnt vmcnt(6) lgkmcnt(0)
	s_barrier
	v_add_u32_e32 v240, s61, v238
	v_add_u32_e32 v241, s61, v239
	s_setprio 1
	s_add_i32 m0, s60, s62
	v_mfma_f32_16x16x32_bf16 v[2:5], v[210:213], v[178:181], v[2:5]
	global_load_lds_dwordx4 v226, s[54:55]
	v_mfma_f32_16x16x32_bf16 v[6:9], v[214:217], v[178:181], v[6:9]
	global_load_lds_dwordx4 v226, s[54:55] offset:1024
	v_mfma_f32_16x16x32_bf16 v[10:13], v[218:221], v[178:181], v[10:13]
	global_load_lds_dwordx4 v226, s[54:55] offset:2048
	v_mfma_f32_16x16x32_bf16 v[14:17], v[222:225], v[178:181], v[14:17]
	global_load_lds_dwordx4 v226, s[54:55] offset:3072
	s_add_i32 m0, s60, s63
	v_mfma_f32_16x16x32_bf16 v[18:21], v[210:213], v[182:185], v[18:21]
	global_load_lds_dwordx4 v230, s[56:57]
	v_mfma_f32_16x16x32_bf16 v[22:25], v[214:217], v[182:185], v[22:25]
	global_load_lds_dwordx4 v231, s[56:57] offset:1024
	v_mfma_f32_16x16x32_bf16 v[26:29], v[218:221], v[182:185], v[26:29]
	v_mfma_f32_16x16x32_bf16 v[30:33], v[222:225], v[182:185], v[30:33]
	v_mfma_f32_16x16x32_bf16 v[34:37], v[210:213], v[186:189], v[34:37]
	ds_read_b128 v[162:165], v241 offset:0
	v_mfma_f32_16x16x32_bf16 v[38:41], v[214:217], v[186:189], v[38:41]
	ds_read_b128 v[166:169], v241 offset:256
	v_mfma_f32_16x16x32_bf16 v[42:45], v[218:221], v[186:189], v[42:45]
	ds_read_b128 v[170:173], v241 offset:2048
	v_mfma_f32_16x16x32_bf16 v[46:49], v[222:225], v[186:189], v[46:49]
	ds_read_b128 v[174:177], v241 offset:2304
	v_mfma_f32_16x16x32_bf16 v[50:53], v[210:213], v[190:193], v[50:53]
	ds_read_b128 v[130:133], v240 offset:0
	v_mfma_f32_16x16x32_bf16 v[54:57], v[214:217], v[190:193], v[54:57]
	ds_read_b128 v[134:137], v240 offset:1024
	v_mfma_f32_16x16x32_bf16 v[58:61], v[218:221], v[190:193], v[58:61]
	ds_read_b128 v[138:141], v240 offset:2048
	v_mfma_f32_16x16x32_bf16 v[62:65], v[222:225], v[190:193], v[62:65]
	ds_read_b128 v[142:145], v240 offset:3072
	v_mfma_f32_16x16x32_bf16 v[66:69], v[210:213], v[194:197], v[66:69]
	ds_read_b128 v[146:149], v240 offset:4096
	v_mfma_f32_16x16x32_bf16 v[70:73], v[214:217], v[194:197], v[70:73]
	ds_read_b128 v[150:153], v240 offset:5120
	v_mfma_f32_16x16x32_bf16 v[74:77], v[218:221], v[194:197], v[74:77]
	ds_read_b128 v[154:157], v240 offset:6144
	v_mfma_f32_16x16x32_bf16 v[78:81], v[222:225], v[194:197], v[78:81]
	ds_read_b128 v[158:161], v240 offset:7168
	v_mfma_f32_16x16x32_bf16 v[82:85], v[210:213], v[198:201], v[82:85]
	v_mfma_f32_16x16x32_bf16 v[86:89], v[214:217], v[198:201], v[86:89]
	v_mfma_f32_16x16x32_bf16 v[90:93], v[218:221], v[198:201], v[90:93]
	v_mfma_f32_16x16x32_bf16 v[94:97], v[222:225], v[198:201], v[94:97]
	v_mfma_f32_16x16x32_bf16 v[98:101], v[210:213], v[202:205], v[98:101]
	v_mfma_f32_16x16x32_bf16 v[102:105], v[214:217], v[202:205], v[102:105]
	v_mfma_f32_16x16x32_bf16 v[106:109], v[218:221], v[202:205], v[106:109]
	v_mfma_f32_16x16x32_bf16 v[110:113], v[222:225], v[202:205], v[110:113]
	v_mfma_f32_16x16x32_bf16 v[114:117], v[210:213], v[206:209], v[114:117]
	v_mfma_f32_16x16x32_bf16 v[118:121], v[214:217], v[206:209], v[118:121]
	v_mfma_f32_16x16x32_bf16 v[122:125], v[218:221], v[206:209], v[122:125]
	v_mfma_f32_16x16x32_bf16 v[126:129], v[222:225], v[206:209], v[126:129]
	s_setprio 0
	s_add_i32 s60, s60, 0x6000
	s_cmp_eq_u32 s60, 0x12000
	s_cselect_b32 s60, 0, s60
	s_add_u32 s54, s54, s72
	s_addc_u32 s55, s55, 0
	s_add_u32 s56, s56, s73
	s_addc_u32 s57, s57, 0
	s_add_i32 s61, s61, 0x6000
	s_cmp_eq_u32 s61, 0x12000
	s_cselect_b32 s61, 0, s61
	s_waitcnt vmcnt(6) lgkmcnt(0)
	s_barrier
	v_add_u32_e32 v240, s61, v238
	v_add_u32_e32 v241, s61, v239
	s_setprio 1
	s_add_i32 m0, s60, s62
	v_mfma_f32_16x16x32_bf16 v[2:5], v[162:165], v[130:133], v[2:5]
	global_load_lds_dwordx4 v226, s[54:55]
	v_mfma_f32_16x16x32_bf16 v[6:9], v[166:169], v[130:133], v[6:9]
	global_load_lds_dwordx4 v226, s[54:55] offset:1024
	v_mfma_f32_16x16x32_bf16 v[10:13], v[170:173], v[130:133], v[10:13]
	global_load_lds_dwordx4 v226, s[54:55] offset:2048
	v_mfma_f32_16x16x32_bf16 v[14:17], v[174:177], v[130:133], v[14:17]
	global_load_lds_dwordx4 v226, s[54:55] offset:3072
	s_add_i32 m0, s60, s63
	v_mfma_f32_16x16x32_bf16 v[18:21], v[162:165], v[134:137], v[18:21]
	global_load_lds_dwordx4 v230, s[56:57]
	v_mfma_f32_16x16x32_bf16 v[22:25], v[166:169], v[134:137], v[22:25]
	global_load_lds_dwordx4 v231, s[56:57] offset:1024
	v_mfma_f32_16x16x32_bf16 v[26:29], v[170:173], v[134:137], v[26:29]
	v_mfma_f32_16x16x32_bf16 v[30:33], v[174:177], v[134:137], v[30:33]
	v_mfma_f32_16x16x32_bf16 v[34:37], v[162:165], v[138:141], v[34:37]
	ds_read_b128 v[210:213], v241 offset:0
	v_mfma_f32_16x16x32_bf16 v[38:41], v[166:169], v[138:141], v[38:41]
	ds_read_b128 v[214:217], v241 offset:256
	v_mfma_f32_16x16x32_bf16 v[42:45], v[170:173], v[138:141], v[42:45]
	ds_read_b128 v[218:221], v241 offset:2048
	v_mfma_f32_16x16x32_bf16 v[46:49], v[174:177], v[138:141], v[46:49]
	ds_read_b128 v[222:225], v241 offset:2304
	v_mfma_f32_16x16x32_bf16 v[50:53], v[162:165], v[142:145], v[50:53]
	ds_read_b128 v[178:181], v240 offset:0
	v_mfma_f32_16x16x32_bf16 v[54:57], v[166:169], v[142:145], v[54:57]
	ds_read_b128 v[182:185], v240 offset:1024
	v_mfma_f32_16x16x32_bf16 v[58:61], v[170:173], v[142:145], v[58:61]
	ds_read_b128 v[186:189], v240 offset:2048
	v_mfma_f32_16x16x32_bf16 v[62:65], v[174:177], v[142:145], v[62:65]
	ds_read_b128 v[190:193], v240 offset:3072
	v_mfma_f32_16x16x32_bf16 v[66:69], v[162:165], v[146:149], v[66:69]
	ds_read_b128 v[194:197], v240 offset:4096
	v_mfma_f32_16x16x32_bf16 v[70:73], v[166:169], v[146:149], v[70:73]
	ds_read_b128 v[198:201], v240 offset:5120
	v_mfma_f32_16x16x32_bf16 v[74:77], v[170:173], v[146:149], v[74:77]
	ds_read_b128 v[202:205], v240 offset:6144
	v_mfma_f32_16x16x32_bf16 v[78:81], v[174:177], v[146:149], v[78:81]
	ds_read_b128 v[206:209], v240 offset:7168
	v_mfma_f32_16x16x32_bf16 v[82:85], v[162:165], v[150:153], v[82:85]
	v_mfma_f32_16x16x32_bf16 v[86:89], v[166:169], v[150:153], v[86:89]
	v_mfma_f32_16x16x32_bf16 v[90:93], v[170:173], v[150:153], v[90:93]
	v_mfma_f32_16x16x32_bf16 v[94:97], v[174:177], v[150:153], v[94:97]
	v_mfma_f32_16x16x32_bf16 v[98:101], v[162:165], v[154:157], v[98:101]
	v_mfma_f32_16x16x32_bf16 v[102:105], v[166:169], v[154:157], v[102:105]
	v_mfma_f32_16x16x32_bf16 v[106:109], v[170:173], v[154:157], v[106:109]
	v_mfma_f32_16x16x32_bf16 v[110:113], v[174:177], v[154:157], v[110:113]
	v_mfma_f32_16x16x32_bf16 v[114:117], v[162:165], v[158:161], v[114:117]
	v_mfma_f32_16x16x32_bf16 v[118:121], v[166:169], v[158:161], v[118:121]
	v_mfma_f32_16x16x32_bf16 v[122:125], v[170:173], v[158:161], v[122:125]
	v_mfma_f32_16x16x32_bf16 v[126:129], v[174:177], v[158:161], v[126:129]
	s_setprio 0
	s_add_i32 s60, s60, 0x6000
	s_cmp_eq_u32 s60, 0x12000
	s_cselect_b32 s60, 0, s60
	s_add_u32 s54, s54, s72
	s_addc_u32 s55, s55, 0
	s_add_u32 s56, s56, s73
	s_addc_u32 s57, s57, 0
	s_add_i32 s61, s61, 0x6000
	s_cmp_eq_u32 s61, 0x12000
	s_cselect_b32 s61, 0, s61
	s_waitcnt vmcnt(6) lgkmcnt(0)
	s_barrier
	v_add_u32_e32 v240, s61, v238
	v_add_u32_e32 v241, s61, v239
	s_setprio 1
	s_add_i32 m0, s60, s62
	v_mfma_f32_16x16x32_bf16 v[2:5], v[210:213], v[178:181], v[2:5]
	global_load_lds_dwordx4 v226, s[54:55]
	v_mfma_f32_16x16x32_bf16 v[6:9], v[214:217], v[178:181], v[6:9]
	global_load_lds_dwordx4 v226, s[54:55] offset:1024
	v_mfma_f32_16x16x32_bf16 v[10:13], v[218:221], v[178:181], v[10:13]
	global_load_lds_dwordx4 v226, s[54:55] offset:2048
	v_mfma_f32_16x16x32_bf16 v[14:17], v[222:225], v[178:181], v[14:17]
	global_load_lds_dwordx4 v226, s[54:55] offset:3072
	s_add_i32 m0, s60, s63
	v_mfma_f32_16x16x32_bf16 v[18:21], v[210:213], v[182:185], v[18:21]
	global_load_lds_dwordx4 v230, s[56:57]
	v_mfma_f32_16x16x32_bf16 v[22:25], v[214:217], v[182:185], v[22:25]
	global_load_lds_dwordx4 v231, s[56:57] offset:1024
	v_mfma_f32_16x16x32_bf16 v[26:29], v[218:221], v[182:185], v[26:29]
	v_mfma_f32_16x16x32_bf16 v[30:33], v[222:225], v[182:185], v[30:33]
	v_mfma_f32_16x16x32_bf16 v[34:37], v[210:213], v[186:189], v[34:37]
	ds_read_b128 v[162:165], v241 offset:0
	v_mfma_f32_16x16x32_bf16 v[38:41], v[214:217], v[186:189], v[38:41]
	ds_read_b128 v[166:169], v241 offset:256
	v_mfma_f32_16x16x32_bf16 v[42:45], v[218:221], v[186:189], v[42:45]
	ds_read_b128 v[170:173], v241 offset:2048
	v_mfma_f32_16x16x32_bf16 v[46:49], v[222:225], v[186:189], v[46:49]
	ds_read_b128 v[174:177], v241 offset:2304
	v_mfma_f32_16x16x32_bf16 v[50:53], v[210:213], v[190:193], v[50:53]
	ds_read_b128 v[130:133], v240 offset:0
	v_mfma_f32_16x16x32_bf16 v[54:57], v[214:217], v[190:193], v[54:57]
	ds_read_b128 v[134:137], v240 offset:1024
	v_mfma_f32_16x16x32_bf16 v[58:61], v[218:221], v[190:193], v[58:61]
	ds_read_b128 v[138:141], v240 offset:2048
	v_mfma_f32_16x16x32_bf16 v[62:65], v[222:225], v[190:193], v[62:65]
	ds_read_b128 v[142:145], v240 offset:3072
	v_mfma_f32_16x16x32_bf16 v[66:69], v[210:213], v[194:197], v[66:69]
	ds_read_b128 v[146:149], v240 offset:4096
	v_mfma_f32_16x16x32_bf16 v[70:73], v[214:217], v[194:197], v[70:73]
	ds_read_b128 v[150:153], v240 offset:5120
	v_mfma_f32_16x16x32_bf16 v[74:77], v[218:221], v[194:197], v[74:77]
	ds_read_b128 v[154:157], v240 offset:6144
	v_mfma_f32_16x16x32_bf16 v[78:81], v[222:225], v[194:197], v[78:81]
	ds_read_b128 v[158:161], v240 offset:7168
	v_mfma_f32_16x16x32_bf16 v[82:85], v[210:213], v[198:201], v[82:85]
	v_mfma_f32_16x16x32_bf16 v[86:89], v[214:217], v[198:201], v[86:89]
	v_mfma_f32_16x16x32_bf16 v[90:93], v[218:221], v[198:201], v[90:93]
	v_mfma_f32_16x16x32_bf16 v[94:97], v[222:225], v[198:201], v[94:97]
	v_mfma_f32_16x16x32_bf16 v[98:101], v[210:213], v[202:205], v[98:101]
	v_mfma_f32_16x16x32_bf16 v[102:105], v[214:217], v[202:205], v[102:105]
	v_mfma_f32_16x16x32_bf16 v[106:109], v[218:221], v[202:205], v[106:109]
	v_mfma_f32_16x16x32_bf16 v[110:113], v[222:225], v[202:205], v[110:113]
	v_mfma_f32_16x16x32_bf16 v[114:117], v[210:213], v[206:209], v[114:117]
	v_mfma_f32_16x16x32_bf16 v[118:121], v[214:217], v[206:209], v[118:121]
	v_mfma_f32_16x16x32_bf16 v[122:125], v[218:221], v[206:209], v[122:125]
	v_mfma_f32_16x16x32_bf16 v[126:129], v[222:225], v[206:209], v[126:129]
	s_setprio 0
	s_add_i32 s60, s60, 0x6000
	s_cmp_eq_u32 s60, 0x12000
	s_cselect_b32 s60, 0, s60
	s_add_u32 s54, s54, s72
	s_addc_u32 s55, s55, 0
	s_add_u32 s56, s56, s73
	s_addc_u32 s57, s57, 0
	s_add_i32 s61, s61, 0x6000
	s_cmp_eq_u32 s61, 0x12000
	s_cselect_b32 s61, 0, s61
	s_and_b32 s39, s35, 0xfff
	s_lshr_b32 s21, s36, 7
	s_waitcnt vmcnt(18)
	v_mbcnt_lo_u32_b32 v217, -1, 0
	v_mbcnt_hi_u32_b32 v217, -1, v217
	v_lshlrev_b32_e32 v217, 5, v217
	s_lshl_b32 s26, s43, 11
	s_add_i32 s26, s26, 0x12010
	v_add_u32_e32 v217, s26, v217
	s_cmp_eq_u32 s42, 0
	s_cbranch_scc0 .Lup_en_nowr
	ds_write_b128 v217, v[114:117]
	ds_write_b128 v217, v[118:121] offset:16

.Lup_en_cont:
	v_add_u32_e32 v216, 0x13010, v228
	ds_read_b128 v[178:181], v216 offset:0
	ds_read_b128 v[182:185], v216 offset:16
	ds_read_b128 v[186:189], v216 offset:256
	ds_read_b128 v[190:193], v216 offset:272
	ds_read_b128 v[194:197], v216 offset:512
	ds_read_b128 v[198:201], v216 offset:528
	ds_read_b128 v[202:205], v216 offset:768
	ds_read_b128 v[206:209], v216 offset:784
	s_lshl_b32 s26, s21, 1
	s_add_i32 s26, s26, s43
	s_lshl_b32 s26, s26, 20
	s_lshl_b32 s27, s35, 6
	s_add_u32 s18, s52, s26
	s_addc_u32 s19, s53, 0
	s_add_u32 s18, s18, s27
	s_addc_u32 s19, s19, 0
	s_sub_u32 s18, s18, 0x80
	s_subb_u32 s19, s19, 0
	s_add_u32 s6, s18, 0x1000
	s_addc_u32 s7, s19, 0
	s_sub_i32 s66, 0x1002, s39
	s_waitcnt lgkmcnt(0)
	v_mov_b32_dpp v210, v98 row_ror:1 row_mask:0xf bank_mask:0xf
	v_mov_b32_dpp v212, v98 row_ror:2 row_mask:0xf bank_mask:0xf
	v_mov_b32_dpp v211, v99 row_ror:1 row_mask:0xf bank_mask:0xf
	v_mov_b32_dpp v213, v99 row_ror:2 row_mask:0xf bank_mask:0xf
	s_nop 1
	v_mov_b32_dpp v210, v114 row_shr:1 row_mask:0xf bank_mask:0xf
	v_mov_b32_dpp v212, v114 row_shr:2 row_mask:0xf bank_mask:0xf
	v_mov_b32_dpp v211, v115 row_shr:1 row_mask:0xf bank_mask:0xf
	v_mov_b32_dpp v213, v115 row_shr:2 row_mask:0xf bank_mask:0xf
	s_nop 1
	v_pk_mul_f32 v[210:211], v[186:187], v[210:211]
	v_pk_fma_f32 v[214:215], v[194:195], v[114:115], v[210:211]
	v_pk_fma_f32 v[214:215], v[178:179], v[212:213], v[214:215]
	v_pk_add_f32 v[214:215], v[202:203], v[214:215]
	v_pk_mul_f32 v[216:217], v[214:215], s[92:93]
	v_pk_mul_f32 v[216:217], v[214:215], v[216:217]
	v_pk_fma_f32 v[216:217], v[214:215], v[216:217], v[214:215]
	v_pk_mul_f32 v[216:217], v[216:217], s[96:97]
	v_pk_mul_f32 v[216:217], v[216:217], s[28:29]
	v_exp_f32_e32 v216, v216
	v_exp_f32_e32 v217, v217
	s_nop 0
	v_add_f32_e32 v216, 1.0, v216
	v_add_f32_e32 v217, 1.0, v217
	v_rcp_f32_e32 v216, v216
	v_rcp_f32_e32 v217, v217
	s_nop 0
	v_pk_mul_f32 v[214:215], v[214:215], v[216:217]
	v_pk_mul_f32 v[214:215], v[122:123], v[214:215]
	v_cvt_pk_bf16_f32 v122, v214, v215
	v_mov_b32_dpp v210, v100 row_ror:1 row_mask:0xf bank_mask:0xf
	v_mov_b32_dpp v212, v100 row_ror:2 row_mask:0xf bank_mask:0xf
	v_mov_b32_dpp v211, v101 row_ror:1 row_mask:0xf bank_mask:0xf
	v_mov_b32_dpp v213, v101 row_ror:2 row_mask:0xf bank_mask:0xf
	s_nop 1
	v_mov_b32_dpp v210, v116 row_shr:1 row_mask:0xf bank_mask:0xf
	v_mov_b32_dpp v212, v116 row_shr:2 row_mask:0xf bank_mask:0xf
	v_mov_b32_dpp v211, v117 row_shr:1 row_mask:0xf bank_mask:0xf
	v_mov_b32_dpp v213, v117 row_shr:2 row_mask:0xf bank_mask:0xf
	s_nop 1
	v_pk_mul_f32 v[210:211], v[188:189], v[210:211]
	v_pk_fma_f32 v[214:215], v[196:197], v[116:117], v[210:211]
	v_pk_fma_f32 v[214:215], v[180:181], v[212:213], v[214:215]
	v_pk_add_f32 v[214:215], v[204:205], v[214:215]
	v_pk_mul_f32 v[216:217], v[214:215], s[92:93]
	v_pk_mul_f32 v[216:217], v[214:215], v[216:217]
	v_pk_fma_f32 v[216:217], v[214:215], v[216:217], v[214:215]
	v_pk_mul_f32 v[216:217], v[216:217], s[96:97]
	v_pk_mul_f32 v[216:217], v[216:217], s[28:29]
	v_exp_f32_e32 v216, v216
	v_exp_f32_e32 v217, v217
	s_nop 0
	v_add_f32_e32 v216, 1.0, v216
	v_add_f32_e32 v217, 1.0, v217
	v_rcp_f32_e32 v216, v216
	v_rcp_f32_e32 v217, v217
	s_nop 0
	v_pk_mul_f32 v[214:215], v[214:215], v[216:217]
	v_pk_mul_f32 v[214:215], v[124:125], v[214:215]
	v_cvt_pk_bf16_f32 v123, v214, v215
	v_mov_b32_dpp v210, v102 row_ror:1 row_mask:0xf bank_mask:0xf
	v_mov_b32_dpp v212, v102 row_ror:2 row_mask:0xf bank_mask:0xf
	v_mov_b32_dpp v211, v103 row_ror:1 row_mask:0xf bank_mask:0xf
	v_mov_b32_dpp v213, v103 row_ror:2 row_mask:0xf bank_mask:0xf
	s_nop 1
	v_mov_b32_dpp v210, v118 row_shr:1 row_mask:0xf bank_mask:0xf
	v_mov_b32_dpp v212, v118 row_shr:2 row_mask:0xf bank_mask:0xf
	v_mov_b32_dpp v211, v119 row_shr:1 row_mask:0xf bank_mask:0xf
	v_mov_b32_dpp v213, v119 row_shr:2 row_mask:0xf bank_mask:0xf
	s_nop 1
	v_pk_mul_f32 v[210:211], v[190:191], v[210:211]
	v_pk_fma_f32 v[214:215], v[198:199], v[118:119], v[210:211]
	v_pk_fma_f32 v[214:215], v[182:183], v[212:213], v[214:215]
	v_pk_add_f32 v[214:215], v[206:207], v[214:215]
	v_pk_mul_f32 v[216:217], v[214:215], s[92:93]
	v_pk_mul_f32 v[216:217], v[214:215], v[216:217]
	v_pk_fma_f32 v[216:217], v[214:215], v[216:217], v[214:215]
	v_pk_mul_f32 v[216:217], v[216:217], s[96:97]
	v_pk_mul_f32 v[216:217], v[216:217], s[28:29]
	v_exp_f32_e32 v216, v216
	v_exp_f32_e32 v217, v217
	s_nop 0
	v_add_f32_e32 v216, 1.0, v216
	v_add_f32_e32 v217, 1.0, v217
	v_rcp_f32_e32 v216, v216
	v_rcp_f32_e32 v217, v217
	s_nop 0
	v_pk_mul_f32 v[214:215], v[214:215], v[216:217]
	v_pk_mul_f32 v[214:215], v[126:127], v[214:215]
	v_cvt_pk_bf16_f32 v124, v214, v215
	v_mov_b32_dpp v210, v104 row_ror:1 row_mask:0xf bank_mask:0xf
	v_mov_b32_dpp v212, v104 row_ror:2 row_mask:0xf bank_mask:0xf
	v_mov_b32_dpp v211, v105 row_ror:1 row_mask:0xf bank_mask:0xf
	v_mov_b32_dpp v213, v105 row_ror:2 row_mask:0xf bank_mask:0xf
	s_nop 1
	v_mov_b32_dpp v210, v120 row_shr:1 row_mask:0xf bank_mask:0xf
	v_mov_b32_dpp v212, v120 row_shr:2 row_mask:0xf bank_mask:0xf
	v_mov_b32_dpp v211, v121 row_shr:1 row_mask:0xf bank_mask:0xf
	v_mov_b32_dpp v213, v121 row_shr:2 row_mask:0xf bank_mask:0xf
	s_nop 1
	v_pk_mul_f32 v[210:211], v[192:193], v[210:211]
	v_pk_fma_f32 v[214:215], v[200:201], v[120:121], v[210:211]
	v_pk_fma_f32 v[214:215], v[184:185], v[212:213], v[214:215]
	v_pk_add_f32 v[214:215], v[208:209], v[214:215]
	v_pk_mul_f32 v[216:217], v[214:215], s[92:93]
	v_pk_mul_f32 v[216:217], v[214:215], v[216:217]
	v_pk_fma_f32 v[216:217], v[214:215], v[216:217], v[214:215]
	v_pk_mul_f32 v[216:217], v[216:217], s[96:97]
	v_pk_mul_f32 v[216:217], v[216:217], s[28:29]
	v_exp_f32_e32 v216, v216
	v_exp_f32_e32 v217, v217
	s_nop 0
	v_add_f32_e32 v216, 1.0, v216
	v_add_f32_e32 v217, 1.0, v217
	v_rcp_f32_e32 v216, v216
	v_rcp_f32_e32 v217, v217
	s_nop 0
	v_pk_mul_f32 v[214:215], v[214:215], v[216:217]
	v_pk_mul_f32 v[214:215], v[128:129], v[214:215]
	v_cvt_pk_bf16_f32 v125, v214, v215
	s_add_i32 s26, s66, -112
	v_cmp_gt_i32_e64 s[24:25], s26, v227
	s_nop 1
	s_and_saveexec_b64 s[26:27], s[24:25]
	global_store_dwordx4 v242, v[122:125], s[6:7] offset:3072
	s_mov_b64 exec, s[26:27]
	s_nop 4
	v_mov_b32_dpp v210, v82 row_ror:1 row_mask:0xf bank_mask:0xf
	v_mov_b32_dpp v212, v82 row_ror:2 row_mask:0xf bank_mask:0xf
	v_mov_b32_dpp v211, v83 row_ror:1 row_mask:0xf bank_mask:0xf
	v_mov_b32_dpp v213, v83 row_ror:2 row_mask:0xf bank_mask:0xf
	s_nop 1
	v_mov_b32_dpp v210, v98 row_shr:1 row_mask:0xf bank_mask:0xf
	v_mov_b32_dpp v212, v98 row_shr:2 row_mask:0xf bank_mask:0xf
	v_mov_b32_dpp v211, v99 row_shr:1 row_mask:0xf bank_mask:0xf
	v_mov_b32_dpp v213, v99 row_shr:2 row_mask:0xf bank_mask:0xf
	s_nop 1
	v_pk_mul_f32 v[210:211], v[186:187], v[210:211]
	v_pk_fma_f32 v[214:215], v[194:195], v[98:99], v[210:211]
	v_pk_fma_f32 v[214:215], v[178:179], v[212:213], v[214:215]
	v_pk_add_f32 v[214:215], v[202:203], v[214:215]
	v_pk_mul_f32 v[216:217], v[214:215], s[92:93]
	v_pk_mul_f32 v[216:217], v[214:215], v[216:217]
	v_pk_fma_f32 v[216:217], v[214:215], v[216:217], v[214:215]
	v_pk_mul_f32 v[216:217], v[216:217], s[96:97]
	v_pk_mul_f32 v[216:217], v[216:217], s[28:29]
	v_exp_f32_e32 v216, v216
	v_exp_f32_e32 v217, v217
	s_nop 0
	v_add_f32_e32 v216, 1.0, v216
	v_add_f32_e32 v217, 1.0, v217
	v_rcp_f32_e32 v216, v216
	v_rcp_f32_e32 v217, v217
	s_nop 0
	v_pk_mul_f32 v[214:215], v[214:215], v[216:217]
	v_pk_mul_f32 v[214:215], v[106:107], v[214:215]
	v_cvt_pk_bf16_f32 v106, v214, v215
	v_mov_b32_dpp v210, v84 row_ror:1 row_mask:0xf bank_mask:0xf
	v_mov_b32_dpp v212, v84 row_ror:2 row_mask:0xf bank_mask:0xf
	v_mov_b32_dpp v211, v85 row_ror:1 row_mask:0xf bank_mask:0xf
	v_mov_b32_dpp v213, v85 row_ror:2 row_mask:0xf bank_mask:0xf
	s_nop 1
	v_mov_b32_dpp v210, v100 row_shr:1 row_mask:0xf bank_mask:0xf
	v_mov_b32_dpp v212, v100 row_shr:2 row_mask:0xf bank_mask:0xf
	v_mov_b32_dpp v211, v101 row_shr:1 row_mask:0xf bank_mask:0xf
	v_mov_b32_dpp v213, v101 row_shr:2 row_mask:0xf bank_mask:0xf
	s_nop 1
	v_pk_mul_f32 v[210:211], v[188:189], v[210:211]
	v_pk_fma_f32 v[214:215], v[196:197], v[100:101], v[210:211]
	v_pk_fma_f32 v[214:215], v[180:181], v[212:213], v[214:215]
	v_pk_add_f32 v[214:215], v[204:205], v[214:215]
	v_pk_mul_f32 v[216:217], v[214:215], s[92:93]
	v_pk_mul_f32 v[216:217], v[214:215], v[216:217]
	v_pk_fma_f32 v[216:217], v[214:215], v[216:217], v[214:215]
	v_pk_mul_f32 v[216:217], v[216:217], s[96:97]
	v_pk_mul_f32 v[216:217], v[216:217], s[28:29]
	v_exp_f32_e32 v216, v216
	v_exp_f32_e32 v217, v217
	s_nop 0
	v_add_f32_e32 v216, 1.0, v216
	v_add_f32_e32 v217, 1.0, v217
	v_rcp_f32_e32 v216, v216
	v_rcp_f32_e32 v217, v217
	s_nop 0
	v_pk_mul_f32 v[214:215], v[214:215], v[216:217]
	v_pk_mul_f32 v[214:215], v[108:109], v[214:215]
	v_cvt_pk_bf16_f32 v107, v214, v215
	v_mov_b32_dpp v210, v86 row_ror:1 row_mask:0xf bank_mask:0xf
	v_mov_b32_dpp v212, v86 row_ror:2 row_mask:0xf bank_mask:0xf
	v_mov_b32_dpp v211, v87 row_ror:1 row_mask:0xf bank_mask:0xf
	v_mov_b32_dpp v213, v87 row_ror:2 row_mask:0xf bank_mask:0xf
	s_nop 1
	v_mov_b32_dpp v210, v102 row_shr:1 row_mask:0xf bank_mask:0xf
	v_mov_b32_dpp v212, v102 row_shr:2 row_mask:0xf bank_mask:0xf
	v_mov_b32_dpp v211, v103 row_shr:1 row_mask:0xf bank_mask:0xf
	v_mov_b32_dpp v213, v103 row_shr:2 row_mask:0xf bank_mask:0xf
	s_nop 1
	v_pk_mul_f32 v[210:211], v[190:191], v[210:211]
	v_pk_fma_f32 v[214:215], v[198:199], v[102:103], v[210:211]
	v_pk_fma_f32 v[214:215], v[182:183], v[212:213], v[214:215]
	v_pk_add_f32 v[214:215], v[206:207], v[214:215]
	v_pk_mul_f32 v[216:217], v[214:215], s[92:93]
	v_pk_mul_f32 v[216:217], v[214:215], v[216:217]
	v_pk_fma_f32 v[216:217], v[214:215], v[216:217], v[214:215]
	v_pk_mul_f32 v[216:217], v[216:217], s[96:97]
	v_pk_mul_f32 v[216:217], v[216:217], s[28:29]
	v_exp_f32_e32 v216, v216
	v_exp_f32_e32 v217, v217
	s_nop 0
	v_add_f32_e32 v216, 1.0, v216
	v_add_f32_e32 v217, 1.0, v217
	v_rcp_f32_e32 v216, v216
	v_rcp_f32_e32 v217, v217
	s_nop 0
	v_pk_mul_f32 v[214:215], v[214:215], v[216:217]
	v_pk_mul_f32 v[214:215], v[110:111], v[214:215]
	v_cvt_pk_bf16_f32 v108, v214, v215
	v_mov_b32_dpp v210, v88 row_ror:1 row_mask:0xf bank_mask:0xf
	v_mov_b32_dpp v212, v88 row_ror:2 row_mask:0xf bank_mask:0xf
	v_mov_b32_dpp v211, v89 row_ror:1 row_mask:0xf bank_mask:0xf
	v_mov_b32_dpp v213, v89 row_ror:2 row_mask:0xf bank_mask:0xf
	s_nop 1
	v_mov_b32_dpp v210, v104 row_shr:1 row_mask:0xf bank_mask:0xf
	v_mov_b32_dpp v212, v104 row_shr:2 row_mask:0xf bank_mask:0xf
	v_mov_b32_dpp v211, v105 row_shr:1 row_mask:0xf bank_mask:0xf
	v_mov_b32_dpp v213, v105 row_shr:2 row_mask:0xf bank_mask:0xf
	s_nop 1
	v_pk_mul_f32 v[210:211], v[192:193], v[210:211]
	v_pk_fma_f32 v[214:215], v[200:201], v[104:105], v[210:211]
	v_pk_fma_f32 v[214:215], v[184:185], v[212:213], v[214:215]
	v_pk_add_f32 v[214:215], v[208:209], v[214:215]
	v_pk_mul_f32 v[216:217], v[214:215], s[92:93]
	v_pk_mul_f32 v[216:217], v[214:215], v[216:217]
	v_pk_fma_f32 v[216:217], v[214:215], v[216:217], v[214:215]
	v_pk_mul_f32 v[216:217], v[216:217], s[96:97]
	v_pk_mul_f32 v[216:217], v[216:217], s[28:29]
	v_exp_f32_e32 v216, v216
	v_exp_f32_e32 v217, v217
	s_nop 0
	v_add_f32_e32 v216, 1.0, v216
	v_add_f32_e32 v217, 1.0, v217
	v_rcp_f32_e32 v216, v216
	v_rcp_f32_e32 v217, v217
	s_nop 0
	v_pk_mul_f32 v[214:215], v[214:215], v[216:217]
	v_pk_mul_f32 v[214:215], v[112:113], v[214:215]
	v_cvt_pk_bf16_f32 v109, v214, v215
	s_add_i32 s26, s66, -96
	v_cmp_gt_i32_e64 s[24:25], s26, v227
	s_nop 1
	s_and_saveexec_b64 s[26:27], s[24:25]
	global_store_dwordx4 v242, v[106:109], s[6:7] offset:2048
	s_mov_b64 exec, s[26:27]
	s_nop 4
	v_mov_b32_dpp v210, v66 row_ror:1 row_mask:0xf bank_mask:0xf
	v_mov_b32_dpp v212, v66 row_ror:2 row_mask:0xf bank_mask:0xf
	v_mov_b32_dpp v211, v67 row_ror:1 row_mask:0xf bank_mask:0xf
	v_mov_b32_dpp v213, v67 row_ror:2 row_mask:0xf bank_mask:0xf
	s_nop 1
	v_mov_b32_dpp v210, v82 row_shr:1 row_mask:0xf bank_mask:0xf
	v_mov_b32_dpp v212, v82 row_shr:2 row_mask:0xf bank_mask:0xf
	v_mov_b32_dpp v211, v83 row_shr:1 row_mask:0xf bank_mask:0xf
	v_mov_b32_dpp v213, v83 row_shr:2 row_mask:0xf bank_mask:0xf
	s_nop 1
	v_pk_mul_f32 v[210:211], v[186:187], v[210:211]
	v_pk_fma_f32 v[214:215], v[194:195], v[82:83], v[210:211]
	v_pk_fma_f32 v[214:215], v[178:179], v[212:213], v[214:215]
	v_pk_add_f32 v[214:215], v[202:203], v[214:215]
	v_pk_mul_f32 v[216:217], v[214:215], s[92:93]
	v_pk_mul_f32 v[216:217], v[214:215], v[216:217]
	v_pk_fma_f32 v[216:217], v[214:215], v[216:217], v[214:215]
	v_pk_mul_f32 v[216:217], v[216:217], s[96:97]
	v_pk_mul_f32 v[216:217], v[216:217], s[28:29]
	v_exp_f32_e32 v216, v216
	v_exp_f32_e32 v217, v217
	s_nop 0
	v_add_f32_e32 v216, 1.0, v216
	v_add_f32_e32 v217, 1.0, v217
	v_rcp_f32_e32 v216, v216
	v_rcp_f32_e32 v217, v217
	s_nop 0
	v_pk_mul_f32 v[214:215], v[214:215], v[216:217]
	v_pk_mul_f32 v[214:215], v[90:91], v[214:215]
	v_cvt_pk_bf16_f32 v90, v214, v215
	v_mov_b32_dpp v210, v68 row_ror:1 row_mask:0xf bank_mask:0xf
	v_mov_b32_dpp v212, v68 row_ror:2 row_mask:0xf bank_mask:0xf
	v_mov_b32_dpp v211, v69 row_ror:1 row_mask:0xf bank_mask:0xf
	v_mov_b32_dpp v213, v69 row_ror:2 row_mask:0xf bank_mask:0xf
	s_nop 1
	v_mov_b32_dpp v210, v84 row_shr:1 row_mask:0xf bank_mask:0xf
	v_mov_b32_dpp v212, v84 row_shr:2 row_mask:0xf bank_mask:0xf
	v_mov_b32_dpp v211, v85 row_shr:1 row_mask:0xf bank_mask:0xf
	v_mov_b32_dpp v213, v85 row_shr:2 row_mask:0xf bank_mask:0xf
	s_nop 1
	v_pk_mul_f32 v[210:211], v[188:189], v[210:211]
	v_pk_fma_f32 v[214:215], v[196:197], v[84:85], v[210:211]
	v_pk_fma_f32 v[214:215], v[180:181], v[212:213], v[214:215]
	v_pk_add_f32 v[214:215], v[204:205], v[214:215]
	v_pk_mul_f32 v[216:217], v[214:215], s[92:93]
	v_pk_mul_f32 v[216:217], v[214:215], v[216:217]
	v_pk_fma_f32 v[216:217], v[214:215], v[216:217], v[214:215]
	v_pk_mul_f32 v[216:217], v[216:217], s[96:97]
	v_pk_mul_f32 v[216:217], v[216:217], s[28:29]
	v_exp_f32_e32 v216, v216
	v_exp_f32_e32 v217, v217
	s_nop 0
	v_add_f32_e32 v216, 1.0, v216
	v_add_f32_e32 v217, 1.0, v217
	v_rcp_f32_e32 v216, v216
	v_rcp_f32_e32 v217, v217
	s_nop 0
	v_pk_mul_f32 v[214:215], v[214:215], v[216:217]
	v_pk_mul_f32 v[214:215], v[92:93], v[214:215]
	v_cvt_pk_bf16_f32 v91, v214, v215
	v_mov_b32_dpp v210, v70 row_ror:1 row_mask:0xf bank_mask:0xf
	v_mov_b32_dpp v212, v70 row_ror:2 row_mask:0xf bank_mask:0xf
	v_mov_b32_dpp v211, v71 row_ror:1 row_mask:0xf bank_mask:0xf
	v_mov_b32_dpp v213, v71 row_ror:2 row_mask:0xf bank_mask:0xf
	s_nop 1
	v_mov_b32_dpp v210, v86 row_shr:1 row_mask:0xf bank_mask:0xf
	v_mov_b32_dpp v212, v86 row_shr:2 row_mask:0xf bank_mask:0xf
	v_mov_b32_dpp v211, v87 row_shr:1 row_mask:0xf bank_mask:0xf
	v_mov_b32_dpp v213, v87 row_shr:2 row_mask:0xf bank_mask:0xf
	s_nop 1
	v_pk_mul_f32 v[210:211], v[190:191], v[210:211]
	v_pk_fma_f32 v[214:215], v[198:199], v[86:87], v[210:211]
	v_pk_fma_f32 v[214:215], v[182:183], v[212:213], v[214:215]
	v_pk_add_f32 v[214:215], v[206:207], v[214:215]
	v_pk_mul_f32 v[216:217], v[214:215], s[92:93]
	v_pk_mul_f32 v[216:217], v[214:215], v[216:217]
	v_pk_fma_f32 v[216:217], v[214:215], v[216:217], v[214:215]
	v_pk_mul_f32 v[216:217], v[216:217], s[96:97]
	v_pk_mul_f32 v[216:217], v[216:217], s[28:29]
	v_exp_f32_e32 v216, v216
	v_exp_f32_e32 v217, v217
	s_nop 0
	v_add_f32_e32 v216, 1.0, v216
	v_add_f32_e32 v217, 1.0, v217
	v_rcp_f32_e32 v216, v216
	v_rcp_f32_e32 v217, v217
	s_nop 0
	v_pk_mul_f32 v[214:215], v[214:215], v[216:217]
	v_pk_mul_f32 v[214:215], v[94:95], v[214:215]
	v_cvt_pk_bf16_f32 v92, v214, v215
	v_mov_b32_dpp v210, v72 row_ror:1 row_mask:0xf bank_mask:0xf
	v_mov_b32_dpp v212, v72 row_ror:2 row_mask:0xf bank_mask:0xf
	v_mov_b32_dpp v211, v73 row_ror:1 row_mask:0xf bank_mask:0xf
	v_mov_b32_dpp v213, v73 row_ror:2 row_mask:0xf bank_mask:0xf
	s_nop 1
	v_mov_b32_dpp v210, v88 row_shr:1 row_mask:0xf bank_mask:0xf
	v_mov_b32_dpp v212, v88 row_shr:2 row_mask:0xf bank_mask:0xf
	v_mov_b32_dpp v211, v89 row_shr:1 row_mask:0xf bank_mask:0xf
	v_mov_b32_dpp v213, v89 row_shr:2 row_mask:0xf bank_mask:0xf
	s_nop 1
	v_pk_mul_f32 v[210:211], v[192:193], v[210:211]
	v_pk_fma_f32 v[214:215], v[200:201], v[88:89], v[210:211]
	v_pk_fma_f32 v[214:215], v[184:185], v[212:213], v[214:215]
	v_pk_add_f32 v[214:215], v[208:209], v[214:215]
	v_pk_mul_f32 v[216:217], v[214:215], s[92:93]
	v_pk_mul_f32 v[216:217], v[214:215], v[216:217]
	v_pk_fma_f32 v[216:217], v[214:215], v[216:217], v[214:215]
	v_pk_mul_f32 v[216:217], v[216:217], s[96:97]
	v_pk_mul_f32 v[216:217], v[216:217], s[28:29]
	v_exp_f32_e32 v216, v216
	v_exp_f32_e32 v217, v217
	s_nop 0
	v_add_f32_e32 v216, 1.0, v216
	v_add_f32_e32 v217, 1.0, v217
	v_rcp_f32_e32 v216, v216
	v_rcp_f32_e32 v217, v217
	s_nop 0
	v_pk_mul_f32 v[214:215], v[214:215], v[216:217]
	v_pk_mul_f32 v[214:215], v[96:97], v[214:215]
	v_cvt_pk_bf16_f32 v93, v214, v215
	s_add_i32 s26, s66, -80
	v_cmp_gt_i32_e64 s[24:25], s26, v227
	s_nop 1
	s_and_saveexec_b64 s[26:27], s[24:25]
	global_store_dwordx4 v242, v[90:93], s[6:7] offset:1024
	s_mov_b64 exec, s[26:27]
	s_nop 4
	v_mov_b32_dpp v210, v50 row_ror:1 row_mask:0xf bank_mask:0xf
	v_mov_b32_dpp v212, v50 row_ror:2 row_mask:0xf bank_mask:0xf
	v_mov_b32_dpp v211, v51 row_ror:1 row_mask:0xf bank_mask:0xf
	v_mov_b32_dpp v213, v51 row_ror:2 row_mask:0xf bank_mask:0xf
	s_nop 1
	v_mov_b32_dpp v210, v66 row_shr:1 row_mask:0xf bank_mask:0xf
	v_mov_b32_dpp v212, v66 row_shr:2 row_mask:0xf bank_mask:0xf
	v_mov_b32_dpp v211, v67 row_shr:1 row_mask:0xf bank_mask:0xf
	v_mov_b32_dpp v213, v67 row_shr:2 row_mask:0xf bank_mask:0xf
	s_nop 1
	v_pk_mul_f32 v[210:211], v[186:187], v[210:211]
	v_pk_fma_f32 v[214:215], v[194:195], v[66:67], v[210:211]
	v_pk_fma_f32 v[214:215], v[178:179], v[212:213], v[214:215]
	v_pk_add_f32 v[214:215], v[202:203], v[214:215]
	v_pk_mul_f32 v[216:217], v[214:215], s[92:93]
	v_pk_mul_f32 v[216:217], v[214:215], v[216:217]
	v_pk_fma_f32 v[216:217], v[214:215], v[216:217], v[214:215]
	v_pk_mul_f32 v[216:217], v[216:217], s[96:97]
	v_pk_mul_f32 v[216:217], v[216:217], s[28:29]
	v_exp_f32_e32 v216, v216
	v_exp_f32_e32 v217, v217
	s_nop 0
	v_add_f32_e32 v216, 1.0, v216
	v_add_f32_e32 v217, 1.0, v217
	v_rcp_f32_e32 v216, v216
	v_rcp_f32_e32 v217, v217
	s_nop 0
	v_pk_mul_f32 v[214:215], v[214:215], v[216:217]
	v_pk_mul_f32 v[214:215], v[74:75], v[214:215]
	v_cvt_pk_bf16_f32 v74, v214, v215
	v_mov_b32_dpp v210, v52 row_ror:1 row_mask:0xf bank_mask:0xf
	v_mov_b32_dpp v212, v52 row_ror:2 row_mask:0xf bank_mask:0xf
	v_mov_b32_dpp v211, v53 row_ror:1 row_mask:0xf bank_mask:0xf
	v_mov_b32_dpp v213, v53 row_ror:2 row_mask:0xf bank_mask:0xf
	s_nop 1
	v_mov_b32_dpp v210, v68 row_shr:1 row_mask:0xf bank_mask:0xf
	v_mov_b32_dpp v212, v68 row_shr:2 row_mask:0xf bank_mask:0xf
	v_mov_b32_dpp v211, v69 row_shr:1 row_mask:0xf bank_mask:0xf
	v_mov_b32_dpp v213, v69 row_shr:2 row_mask:0xf bank_mask:0xf
	s_nop 1
	v_pk_mul_f32 v[210:211], v[188:189], v[210:211]
	v_pk_fma_f32 v[214:215], v[196:197], v[68:69], v[210:211]
	v_pk_fma_f32 v[214:215], v[180:181], v[212:213], v[214:215]
	v_pk_add_f32 v[214:215], v[204:205], v[214:215]
	v_pk_mul_f32 v[216:217], v[214:215], s[92:93]
	v_pk_mul_f32 v[216:217], v[214:215], v[216:217]
	v_pk_fma_f32 v[216:217], v[214:215], v[216:217], v[214:215]
	v_pk_mul_f32 v[216:217], v[216:217], s[96:97]
	v_pk_mul_f32 v[216:217], v[216:217], s[28:29]
	v_exp_f32_e32 v216, v216
	v_exp_f32_e32 v217, v217
	s_nop 0
	v_add_f32_e32 v216, 1.0, v216
	v_add_f32_e32 v217, 1.0, v217
	v_rcp_f32_e32 v216, v216
	v_rcp_f32_e32 v217, v217
	s_nop 0
	v_pk_mul_f32 v[214:215], v[214:215], v[216:217]
	v_pk_mul_f32 v[214:215], v[76:77], v[214:215]
	v_cvt_pk_bf16_f32 v75, v214, v215
	v_mov_b32_dpp v210, v54 row_ror:1 row_mask:0xf bank_mask:0xf
	v_mov_b32_dpp v212, v54 row_ror:2 row_mask:0xf bank_mask:0xf
	v_mov_b32_dpp v211, v55 row_ror:1 row_mask:0xf bank_mask:0xf
	v_mov_b32_dpp v213, v55 row_ror:2 row_mask:0xf bank_mask:0xf
	s_nop 1
	v_mov_b32_dpp v210, v70 row_shr:1 row_mask:0xf bank_mask:0xf
	v_mov_b32_dpp v212, v70 row_shr:2 row_mask:0xf bank_mask:0xf
	v_mov_b32_dpp v211, v71 row_shr:1 row_mask:0xf bank_mask:0xf
	v_mov_b32_dpp v213, v71 row_shr:2 row_mask:0xf bank_mask:0xf
	s_nop 1
	v_pk_mul_f32 v[210:211], v[190:191], v[210:211]
	v_pk_fma_f32 v[214:215], v[198:199], v[70:71], v[210:211]
	v_pk_fma_f32 v[214:215], v[182:183], v[212:213], v[214:215]
	v_pk_add_f32 v[214:215], v[206:207], v[214:215]
	v_pk_mul_f32 v[216:217], v[214:215], s[92:93]
	v_pk_mul_f32 v[216:217], v[214:215], v[216:217]
	v_pk_fma_f32 v[216:217], v[214:215], v[216:217], v[214:215]
	v_pk_mul_f32 v[216:217], v[216:217], s[96:97]
	v_pk_mul_f32 v[216:217], v[216:217], s[28:29]
	v_exp_f32_e32 v216, v216
	v_exp_f32_e32 v217, v217
	s_nop 0
	v_add_f32_e32 v216, 1.0, v216
	v_add_f32_e32 v217, 1.0, v217
	v_rcp_f32_e32 v216, v216
	v_rcp_f32_e32 v217, v217
	s_nop 0
	v_pk_mul_f32 v[214:215], v[214:215], v[216:217]
	v_pk_mul_f32 v[214:215], v[78:79], v[214:215]
	v_cvt_pk_bf16_f32 v76, v214, v215
	v_mov_b32_dpp v210, v56 row_ror:1 row_mask:0xf bank_mask:0xf
	v_mov_b32_dpp v212, v56 row_ror:2 row_mask:0xf bank_mask:0xf
	v_mov_b32_dpp v211, v57 row_ror:1 row_mask:0xf bank_mask:0xf
	v_mov_b32_dpp v213, v57 row_ror:2 row_mask:0xf bank_mask:0xf
	s_nop 1
	v_mov_b32_dpp v210, v72 row_shr:1 row_mask:0xf bank_mask:0xf
	v_mov_b32_dpp v212, v72 row_shr:2 row_mask:0xf bank_mask:0xf
	v_mov_b32_dpp v211, v73 row_shr:1 row_mask:0xf bank_mask:0xf
	v_mov_b32_dpp v213, v73 row_shr:2 row_mask:0xf bank_mask:0xf
	s_nop 1
	v_pk_mul_f32 v[210:211], v[192:193], v[210:211]
	v_pk_fma_f32 v[214:215], v[200:201], v[72:73], v[210:211]
	v_pk_fma_f32 v[214:215], v[184:185], v[212:213], v[214:215]
	v_pk_add_f32 v[214:215], v[208:209], v[214:215]
	v_pk_mul_f32 v[216:217], v[214:215], s[92:93]
	v_pk_mul_f32 v[216:217], v[214:215], v[216:217]
	v_pk_fma_f32 v[216:217], v[214:215], v[216:217], v[214:215]
	v_pk_mul_f32 v[216:217], v[216:217], s[96:97]
	v_pk_mul_f32 v[216:217], v[216:217], s[28:29]
	v_exp_f32_e32 v216, v216
	v_exp_f32_e32 v217, v217
	s_nop 0
	v_add_f32_e32 v216, 1.0, v216
	v_add_f32_e32 v217, 1.0, v217
	v_rcp_f32_e32 v216, v216
	v_rcp_f32_e32 v217, v217
	s_nop 0
	v_pk_mul_f32 v[214:215], v[214:215], v[216:217]
	v_pk_mul_f32 v[214:215], v[80:81], v[214:215]
	v_cvt_pk_bf16_f32 v77, v214, v215
	s_add_i32 s26, s66, -64
	v_cmp_gt_i32_e64 s[24:25], s26, v227
	s_nop 1
	s_and_saveexec_b64 s[26:27], s[24:25]
	global_store_dwordx4 v242, v[74:77], s[6:7]
	s_mov_b64 exec, s[26:27]
	s_nop 4
	v_mov_b32_dpp v210, v34 row_ror:1 row_mask:0xf bank_mask:0xf
	v_mov_b32_dpp v212, v34 row_ror:2 row_mask:0xf bank_mask:0xf
	v_mov_b32_dpp v211, v35 row_ror:1 row_mask:0xf bank_mask:0xf
	v_mov_b32_dpp v213, v35 row_ror:2 row_mask:0xf bank_mask:0xf
	s_nop 1
	v_mov_b32_dpp v210, v50 row_shr:1 row_mask:0xf bank_mask:0xf
	v_mov_b32_dpp v212, v50 row_shr:2 row_mask:0xf bank_mask:0xf
	v_mov_b32_dpp v211, v51 row_shr:1 row_mask:0xf bank_mask:0xf
	v_mov_b32_dpp v213, v51 row_shr:2 row_mask:0xf bank_mask:0xf
	s_nop 1
	v_pk_mul_f32 v[210:211], v[186:187], v[210:211]
	v_pk_fma_f32 v[214:215], v[194:195], v[50:51], v[210:211]
	v_pk_fma_f32 v[214:215], v[178:179], v[212:213], v[214:215]
	v_pk_add_f32 v[214:215], v[202:203], v[214:215]
	v_pk_mul_f32 v[216:217], v[214:215], s[92:93]
	v_pk_mul_f32 v[216:217], v[214:215], v[216:217]
	v_pk_fma_f32 v[216:217], v[214:215], v[216:217], v[214:215]
	v_pk_mul_f32 v[216:217], v[216:217], s[96:97]
	v_pk_mul_f32 v[216:217], v[216:217], s[28:29]
	v_exp_f32_e32 v216, v216
	v_exp_f32_e32 v217, v217
	s_nop 0
	v_add_f32_e32 v216, 1.0, v216
	v_add_f32_e32 v217, 1.0, v217
	v_rcp_f32_e32 v216, v216
	v_rcp_f32_e32 v217, v217
	s_nop 0
	v_pk_mul_f32 v[214:215], v[214:215], v[216:217]
	v_pk_mul_f32 v[214:215], v[58:59], v[214:215]
	v_cvt_pk_bf16_f32 v58, v214, v215
	v_mov_b32_dpp v210, v36 row_ror:1 row_mask:0xf bank_mask:0xf
	v_mov_b32_dpp v212, v36 row_ror:2 row_mask:0xf bank_mask:0xf
	v_mov_b32_dpp v211, v37 row_ror:1 row_mask:0xf bank_mask:0xf
	v_mov_b32_dpp v213, v37 row_ror:2 row_mask:0xf bank_mask:0xf
	s_nop 1
	v_mov_b32_dpp v210, v52 row_shr:1 row_mask:0xf bank_mask:0xf
	v_mov_b32_dpp v212, v52 row_shr:2 row_mask:0xf bank_mask:0xf
	v_mov_b32_dpp v211, v53 row_shr:1 row_mask:0xf bank_mask:0xf
	v_mov_b32_dpp v213, v53 row_shr:2 row_mask:0xf bank_mask:0xf
	s_nop 1
	v_pk_mul_f32 v[210:211], v[188:189], v[210:211]
	v_pk_fma_f32 v[214:215], v[196:197], v[52:53], v[210:211]
	v_pk_fma_f32 v[214:215], v[180:181], v[212:213], v[214:215]
	v_pk_add_f32 v[214:215], v[204:205], v[214:215]
	v_pk_mul_f32 v[216:217], v[214:215], s[92:93]
	v_pk_mul_f32 v[216:217], v[214:215], v[216:217]
	v_pk_fma_f32 v[216:217], v[214:215], v[216:217], v[214:215]
	v_pk_mul_f32 v[216:217], v[216:217], s[96:97]
	v_pk_mul_f32 v[216:217], v[216:217], s[28:29]
	v_exp_f32_e32 v216, v216
	v_exp_f32_e32 v217, v217
	s_nop 0
	v_add_f32_e32 v216, 1.0, v216
	v_add_f32_e32 v217, 1.0, v217
	v_rcp_f32_e32 v216, v216
	v_rcp_f32_e32 v217, v217
	s_nop 0
	v_pk_mul_f32 v[214:215], v[214:215], v[216:217]
	v_pk_mul_f32 v[214:215], v[60:61], v[214:215]
	v_cvt_pk_bf16_f32 v59, v214, v215
	v_mov_b32_dpp v210, v38 row_ror:1 row_mask:0xf bank_mask:0xf
	v_mov_b32_dpp v212, v38 row_ror:2 row_mask:0xf bank_mask:0xf
	v_mov_b32_dpp v211, v39 row_ror:1 row_mask:0xf bank_mask:0xf
	v_mov_b32_dpp v213, v39 row_ror:2 row_mask:0xf bank_mask:0xf
	s_nop 1
	v_mov_b32_dpp v210, v54 row_shr:1 row_mask:0xf bank_mask:0xf
	v_mov_b32_dpp v212, v54 row_shr:2 row_mask:0xf bank_mask:0xf
	v_mov_b32_dpp v211, v55 row_shr:1 row_mask:0xf bank_mask:0xf
	v_mov_b32_dpp v213, v55 row_shr:2 row_mask:0xf bank_mask:0xf
	s_nop 1
	v_pk_mul_f32 v[210:211], v[190:191], v[210:211]
	v_pk_fma_f32 v[214:215], v[198:199], v[54:55], v[210:211]
	v_pk_fma_f32 v[214:215], v[182:183], v[212:213], v[214:215]
	v_pk_add_f32 v[214:215], v[206:207], v[214:215]
	v_pk_mul_f32 v[216:217], v[214:215], s[92:93]
	v_pk_mul_f32 v[216:217], v[214:215], v[216:217]
	v_pk_fma_f32 v[216:217], v[214:215], v[216:217], v[214:215]
	v_pk_mul_f32 v[216:217], v[216:217], s[96:97]
	v_pk_mul_f32 v[216:217], v[216:217], s[28:29]
	v_exp_f32_e32 v216, v216
	v_exp_f32_e32 v217, v217
	s_nop 0
	v_add_f32_e32 v216, 1.0, v216
	v_add_f32_e32 v217, 1.0, v217
	v_rcp_f32_e32 v216, v216
	v_rcp_f32_e32 v217, v217
	s_nop 0
	v_pk_mul_f32 v[214:215], v[214:215], v[216:217]
	v_pk_mul_f32 v[214:215], v[62:63], v[214:215]
	v_cvt_pk_bf16_f32 v60, v214, v215
	v_mov_b32_dpp v210, v40 row_ror:1 row_mask:0xf bank_mask:0xf
	v_mov_b32_dpp v212, v40 row_ror:2 row_mask:0xf bank_mask:0xf
	v_mov_b32_dpp v211, v41 row_ror:1 row_mask:0xf bank_mask:0xf
	v_mov_b32_dpp v213, v41 row_ror:2 row_mask:0xf bank_mask:0xf
	s_nop 1
	v_mov_b32_dpp v210, v56 row_shr:1 row_mask:0xf bank_mask:0xf
	v_mov_b32_dpp v212, v56 row_shr:2 row_mask:0xf bank_mask:0xf
	v_mov_b32_dpp v211, v57 row_shr:1 row_mask:0xf bank_mask:0xf
	v_mov_b32_dpp v213, v57 row_shr:2 row_mask:0xf bank_mask:0xf
	s_nop 1
	v_pk_mul_f32 v[210:211], v[192:193], v[210:211]
	v_pk_fma_f32 v[214:215], v[200:201], v[56:57], v[210:211]
	v_pk_fma_f32 v[214:215], v[184:185], v[212:213], v[214:215]
	v_pk_add_f32 v[214:215], v[208:209], v[214:215]
	v_pk_mul_f32 v[216:217], v[214:215], s[92:93]
	v_pk_mul_f32 v[216:217], v[214:215], v[216:217]
	v_pk_fma_f32 v[216:217], v[214:215], v[216:217], v[214:215]
	v_pk_mul_f32 v[216:217], v[216:217], s[96:97]
	v_pk_mul_f32 v[216:217], v[216:217], s[28:29]
	v_exp_f32_e32 v216, v216
	v_exp_f32_e32 v217, v217
	s_nop 0
	v_add_f32_e32 v216, 1.0, v216
	v_add_f32_e32 v217, 1.0, v217
	v_rcp_f32_e32 v216, v216
	v_rcp_f32_e32 v217, v217
	s_nop 0
	v_pk_mul_f32 v[214:215], v[214:215], v[216:217]
	v_pk_mul_f32 v[214:215], v[64:65], v[214:215]
	v_cvt_pk_bf16_f32 v61, v214, v215
	s_add_i32 s26, s66, -48
	v_cmp_gt_i32_e64 s[24:25], s26, v227
	s_nop 1
	s_and_saveexec_b64 s[26:27], s[24:25]
	global_store_dwordx4 v242, v[58:61], s[18:19] offset:3072
	s_mov_b64 exec, s[26:27]
	s_nop 4
	v_mov_b32_dpp v210, v18 row_ror:1 row_mask:0xf bank_mask:0xf
	v_mov_b32_dpp v212, v18 row_ror:2 row_mask:0xf bank_mask:0xf
	v_mov_b32_dpp v211, v19 row_ror:1 row_mask:0xf bank_mask:0xf
	v_mov_b32_dpp v213, v19 row_ror:2 row_mask:0xf bank_mask:0xf
	s_nop 1
	v_mov_b32_dpp v210, v34 row_shr:1 row_mask:0xf bank_mask:0xf
	v_mov_b32_dpp v212, v34 row_shr:2 row_mask:0xf bank_mask:0xf
	v_mov_b32_dpp v211, v35 row_shr:1 row_mask:0xf bank_mask:0xf
	v_mov_b32_dpp v213, v35 row_shr:2 row_mask:0xf bank_mask:0xf
	s_nop 1
	v_pk_mul_f32 v[210:211], v[186:187], v[210:211]
	v_pk_fma_f32 v[214:215], v[194:195], v[34:35], v[210:211]
	v_pk_fma_f32 v[214:215], v[178:179], v[212:213], v[214:215]
	v_pk_add_f32 v[214:215], v[202:203], v[214:215]
	v_pk_mul_f32 v[216:217], v[214:215], s[92:93]
	v_pk_mul_f32 v[216:217], v[214:215], v[216:217]
	v_pk_fma_f32 v[216:217], v[214:215], v[216:217], v[214:215]
	v_pk_mul_f32 v[216:217], v[216:217], s[96:97]
	v_pk_mul_f32 v[216:217], v[216:217], s[28:29]
	v_exp_f32_e32 v216, v216
	v_exp_f32_e32 v217, v217
	s_nop 0
	v_add_f32_e32 v216, 1.0, v216
	v_add_f32_e32 v217, 1.0, v217
	v_rcp_f32_e32 v216, v216
	v_rcp_f32_e32 v217, v217
	s_nop 0
	v_pk_mul_f32 v[214:215], v[214:215], v[216:217]
	v_pk_mul_f32 v[214:215], v[42:43], v[214:215]
	v_cvt_pk_bf16_f32 v42, v214, v215
	v_mov_b32_dpp v210, v20 row_ror:1 row_mask:0xf bank_mask:0xf
	v_mov_b32_dpp v212, v20 row_ror:2 row_mask:0xf bank_mask:0xf
	v_mov_b32_dpp v211, v21 row_ror:1 row_mask:0xf bank_mask:0xf
	v_mov_b32_dpp v213, v21 row_ror:2 row_mask:0xf bank_mask:0xf
	s_nop 1
	v_mov_b32_dpp v210, v36 row_shr:1 row_mask:0xf bank_mask:0xf
	v_mov_b32_dpp v212, v36 row_shr:2 row_mask:0xf bank_mask:0xf
	v_mov_b32_dpp v211, v37 row_shr:1 row_mask:0xf bank_mask:0xf
	v_mov_b32_dpp v213, v37 row_shr:2 row_mask:0xf bank_mask:0xf
	s_nop 1
	v_pk_mul_f32 v[210:211], v[188:189], v[210:211]
	v_pk_fma_f32 v[214:215], v[196:197], v[36:37], v[210:211]
	v_pk_fma_f32 v[214:215], v[180:181], v[212:213], v[214:215]
	v_pk_add_f32 v[214:215], v[204:205], v[214:215]
	v_pk_mul_f32 v[216:217], v[214:215], s[92:93]
	v_pk_mul_f32 v[216:217], v[214:215], v[216:217]
	v_pk_fma_f32 v[216:217], v[214:215], v[216:217], v[214:215]
	v_pk_mul_f32 v[216:217], v[216:217], s[96:97]
	v_pk_mul_f32 v[216:217], v[216:217], s[28:29]
	v_exp_f32_e32 v216, v216
	v_exp_f32_e32 v217, v217
	s_nop 0
	v_add_f32_e32 v216, 1.0, v216
	v_add_f32_e32 v217, 1.0, v217
	v_rcp_f32_e32 v216, v216
	v_rcp_f32_e32 v217, v217
	s_nop 0
	v_pk_mul_f32 v[214:215], v[214:215], v[216:217]
	v_pk_mul_f32 v[214:215], v[44:45], v[214:215]
	v_cvt_pk_bf16_f32 v43, v214, v215
	v_mov_b32_dpp v210, v22 row_ror:1 row_mask:0xf bank_mask:0xf
	v_mov_b32_dpp v212, v22 row_ror:2 row_mask:0xf bank_mask:0xf
	v_mov_b32_dpp v211, v23 row_ror:1 row_mask:0xf bank_mask:0xf
	v_mov_b32_dpp v213, v23 row_ror:2 row_mask:0xf bank_mask:0xf
	s_nop 1
	v_mov_b32_dpp v210, v38 row_shr:1 row_mask:0xf bank_mask:0xf
	v_mov_b32_dpp v212, v38 row_shr:2 row_mask:0xf bank_mask:0xf
	v_mov_b32_dpp v211, v39 row_shr:1 row_mask:0xf bank_mask:0xf
	v_mov_b32_dpp v213, v39 row_shr:2 row_mask:0xf bank_mask:0xf
	s_nop 1
	v_pk_mul_f32 v[210:211], v[190:191], v[210:211]
	v_pk_fma_f32 v[214:215], v[198:199], v[38:39], v[210:211]
	v_pk_fma_f32 v[214:215], v[182:183], v[212:213], v[214:215]
	v_pk_add_f32 v[214:215], v[206:207], v[214:215]
	v_pk_mul_f32 v[216:217], v[214:215], s[92:93]
	v_pk_mul_f32 v[216:217], v[214:215], v[216:217]
	v_pk_fma_f32 v[216:217], v[214:215], v[216:217], v[214:215]
	v_pk_mul_f32 v[216:217], v[216:217], s[96:97]
	v_pk_mul_f32 v[216:217], v[216:217], s[28:29]
	v_exp_f32_e32 v216, v216
	v_exp_f32_e32 v217, v217
	s_nop 0
	v_add_f32_e32 v216, 1.0, v216
	v_add_f32_e32 v217, 1.0, v217
	v_rcp_f32_e32 v216, v216
	v_rcp_f32_e32 v217, v217
	s_nop 0
	v_pk_mul_f32 v[214:215], v[214:215], v[216:217]
	v_pk_mul_f32 v[214:215], v[46:47], v[214:215]
	v_cvt_pk_bf16_f32 v44, v214, v215
	v_mov_b32_dpp v210, v24 row_ror:1 row_mask:0xf bank_mask:0xf
	v_mov_b32_dpp v212, v24 row_ror:2 row_mask:0xf bank_mask:0xf
	v_mov_b32_dpp v211, v25 row_ror:1 row_mask:0xf bank_mask:0xf
	v_mov_b32_dpp v213, v25 row_ror:2 row_mask:0xf bank_mask:0xf
	s_nop 1
	v_mov_b32_dpp v210, v40 row_shr:1 row_mask:0xf bank_mask:0xf
	v_mov_b32_dpp v212, v40 row_shr:2 row_mask:0xf bank_mask:0xf
	v_mov_b32_dpp v211, v41 row_shr:1 row_mask:0xf bank_mask:0xf
	v_mov_b32_dpp v213, v41 row_shr:2 row_mask:0xf bank_mask:0xf
	s_nop 1
	v_pk_mul_f32 v[210:211], v[192:193], v[210:211]
	v_pk_fma_f32 v[214:215], v[200:201], v[40:41], v[210:211]
	v_pk_fma_f32 v[214:215], v[184:185], v[212:213], v[214:215]
	v_pk_add_f32 v[214:215], v[208:209], v[214:215]
	v_pk_mul_f32 v[216:217], v[214:215], s[92:93]
	v_pk_mul_f32 v[216:217], v[214:215], v[216:217]
	v_pk_fma_f32 v[216:217], v[214:215], v[216:217], v[214:215]
	v_pk_mul_f32 v[216:217], v[216:217], s[96:97]
	v_pk_mul_f32 v[216:217], v[216:217], s[28:29]
	v_exp_f32_e32 v216, v216
	v_exp_f32_e32 v217, v217
	s_nop 0
	v_add_f32_e32 v216, 1.0, v216
	v_add_f32_e32 v217, 1.0, v217
	v_rcp_f32_e32 v216, v216
	v_rcp_f32_e32 v217, v217
	s_nop 0
	v_pk_mul_f32 v[214:215], v[214:215], v[216:217]
	v_pk_mul_f32 v[214:215], v[48:49], v[214:215]
	v_cvt_pk_bf16_f32 v45, v214, v215
	s_add_i32 s26, s66, -32
	v_cmp_gt_i32_e64 s[24:25], s26, v227
	s_nop 1
	s_and_saveexec_b64 s[26:27], s[24:25]
	global_store_dwordx4 v242, v[42:45], s[18:19] offset:2048
	s_mov_b64 exec, s[26:27]
	s_nop 4
	v_mov_b32_dpp v210, v2 row_ror:1 row_mask:0xf bank_mask:0xf
	v_mov_b32_dpp v212, v2 row_ror:2 row_mask:0xf bank_mask:0xf
	v_mov_b32_dpp v211, v3 row_ror:1 row_mask:0xf bank_mask:0xf
	v_mov_b32_dpp v213, v3 row_ror:2 row_mask:0xf bank_mask:0xf
	s_nop 1
	v_mov_b32_dpp v210, v18 row_shr:1 row_mask:0xf bank_mask:0xf
	v_mov_b32_dpp v212, v18 row_shr:2 row_mask:0xf bank_mask:0xf
	v_mov_b32_dpp v211, v19 row_shr:1 row_mask:0xf bank_mask:0xf
	v_mov_b32_dpp v213, v19 row_shr:2 row_mask:0xf bank_mask:0xf
	s_nop 1
	v_pk_mul_f32 v[210:211], v[186:187], v[210:211]
	v_pk_fma_f32 v[214:215], v[194:195], v[18:19], v[210:211]
	v_pk_fma_f32 v[214:215], v[178:179], v[212:213], v[214:215]
	v_pk_add_f32 v[214:215], v[202:203], v[214:215]
	v_pk_mul_f32 v[216:217], v[214:215], s[92:93]
	v_pk_mul_f32 v[216:217], v[214:215], v[216:217]
	v_pk_fma_f32 v[216:217], v[214:215], v[216:217], v[214:215]
	v_pk_mul_f32 v[216:217], v[216:217], s[96:97]
	v_pk_mul_f32 v[216:217], v[216:217], s[28:29]
	v_exp_f32_e32 v216, v216
	v_exp_f32_e32 v217, v217
	s_nop 0
	v_add_f32_e32 v216, 1.0, v216
	v_add_f32_e32 v217, 1.0, v217
	v_rcp_f32_e32 v216, v216
	v_rcp_f32_e32 v217, v217
	s_nop 0
	v_pk_mul_f32 v[214:215], v[214:215], v[216:217]
	v_pk_mul_f32 v[214:215], v[26:27], v[214:215]
	v_cvt_pk_bf16_f32 v26, v214, v215
	v_mov_b32_dpp v210, v4 row_ror:1 row_mask:0xf bank_mask:0xf
	v_mov_b32_dpp v212, v4 row_ror:2 row_mask:0xf bank_mask:0xf
	v_mov_b32_dpp v211, v5 row_ror:1 row_mask:0xf bank_mask:0xf
	v_mov_b32_dpp v213, v5 row_ror:2 row_mask:0xf bank_mask:0xf
	s_nop 1
	v_mov_b32_dpp v210, v20 row_shr:1 row_mask:0xf bank_mask:0xf
	v_mov_b32_dpp v212, v20 row_shr:2 row_mask:0xf bank_mask:0xf
	v_mov_b32_dpp v211, v21 row_shr:1 row_mask:0xf bank_mask:0xf
	v_mov_b32_dpp v213, v21 row_shr:2 row_mask:0xf bank_mask:0xf
	s_nop 1
	v_pk_mul_f32 v[210:211], v[188:189], v[210:211]
	v_pk_fma_f32 v[214:215], v[196:197], v[20:21], v[210:211]
	v_pk_fma_f32 v[214:215], v[180:181], v[212:213], v[214:215]
	v_pk_add_f32 v[214:215], v[204:205], v[214:215]
	v_pk_mul_f32 v[216:217], v[214:215], s[92:93]
	v_pk_mul_f32 v[216:217], v[214:215], v[216:217]
	v_pk_fma_f32 v[216:217], v[214:215], v[216:217], v[214:215]
	v_pk_mul_f32 v[216:217], v[216:217], s[96:97]
	v_pk_mul_f32 v[216:217], v[216:217], s[28:29]
	v_exp_f32_e32 v216, v216
	v_exp_f32_e32 v217, v217
	s_nop 0
	v_add_f32_e32 v216, 1.0, v216
	v_add_f32_e32 v217, 1.0, v217
	v_rcp_f32_e32 v216, v216
	v_rcp_f32_e32 v217, v217
	s_nop 0
	v_pk_mul_f32 v[214:215], v[214:215], v[216:217]
	v_pk_mul_f32 v[214:215], v[28:29], v[214:215]
	v_cvt_pk_bf16_f32 v27, v214, v215
	v_mov_b32_dpp v210, v6 row_ror:1 row_mask:0xf bank_mask:0xf
	v_mov_b32_dpp v212, v6 row_ror:2 row_mask:0xf bank_mask:0xf
	v_mov_b32_dpp v211, v7 row_ror:1 row_mask:0xf bank_mask:0xf
	v_mov_b32_dpp v213, v7 row_ror:2 row_mask:0xf bank_mask:0xf
	s_nop 1
	v_mov_b32_dpp v210, v22 row_shr:1 row_mask:0xf bank_mask:0xf
	v_mov_b32_dpp v212, v22 row_shr:2 row_mask:0xf bank_mask:0xf
	v_mov_b32_dpp v211, v23 row_shr:1 row_mask:0xf bank_mask:0xf
	v_mov_b32_dpp v213, v23 row_shr:2 row_mask:0xf bank_mask:0xf
	s_nop 1
	v_pk_mul_f32 v[210:211], v[190:191], v[210:211]
	v_pk_fma_f32 v[214:215], v[198:199], v[22:23], v[210:211]
	v_pk_fma_f32 v[214:215], v[182:183], v[212:213], v[214:215]
	v_pk_add_f32 v[214:215], v[206:207], v[214:215]
	v_pk_mul_f32 v[216:217], v[214:215], s[92:93]
	v_pk_mul_f32 v[216:217], v[214:215], v[216:217]
	v_pk_fma_f32 v[216:217], v[214:215], v[216:217], v[214:215]
	v_pk_mul_f32 v[216:217], v[216:217], s[96:97]
	v_pk_mul_f32 v[216:217], v[216:217], s[28:29]
	v_exp_f32_e32 v216, v216
	v_exp_f32_e32 v217, v217
	s_nop 0
	v_add_f32_e32 v216, 1.0, v216
	v_add_f32_e32 v217, 1.0, v217
	v_rcp_f32_e32 v216, v216
	v_rcp_f32_e32 v217, v217
	s_nop 0
	v_pk_mul_f32 v[214:215], v[214:215], v[216:217]
	v_pk_mul_f32 v[214:215], v[30:31], v[214:215]
	v_cvt_pk_bf16_f32 v28, v214, v215
	v_mov_b32_dpp v210, v8 row_ror:1 row_mask:0xf bank_mask:0xf
	v_mov_b32_dpp v212, v8 row_ror:2 row_mask:0xf bank_mask:0xf
	v_mov_b32_dpp v211, v9 row_ror:1 row_mask:0xf bank_mask:0xf
	v_mov_b32_dpp v213, v9 row_ror:2 row_mask:0xf bank_mask:0xf
	s_nop 1
	v_mov_b32_dpp v210, v24 row_shr:1 row_mask:0xf bank_mask:0xf
	v_mov_b32_dpp v212, v24 row_shr:2 row_mask:0xf bank_mask:0xf
	v_mov_b32_dpp v211, v25 row_shr:1 row_mask:0xf bank_mask:0xf
	v_mov_b32_dpp v213, v25 row_shr:2 row_mask:0xf bank_mask:0xf
	s_nop 1
	v_pk_mul_f32 v[210:211], v[192:193], v[210:211]
	v_pk_fma_f32 v[214:215], v[200:201], v[24:25], v[210:211]
	v_pk_fma_f32 v[214:215], v[184:185], v[212:213], v[214:215]
	v_pk_add_f32 v[214:215], v[208:209], v[214:215]
	v_pk_mul_f32 v[216:217], v[214:215], s[92:93]
	v_pk_mul_f32 v[216:217], v[214:215], v[216:217]
	v_pk_fma_f32 v[216:217], v[214:215], v[216:217], v[214:215]
	v_pk_mul_f32 v[216:217], v[216:217], s[96:97]
	v_pk_mul_f32 v[216:217], v[216:217], s[28:29]
	v_exp_f32_e32 v216, v216
	v_exp_f32_e32 v217, v217
	s_nop 0
	v_add_f32_e32 v216, 1.0, v216
	v_add_f32_e32 v217, 1.0, v217
	v_rcp_f32_e32 v216, v216
	v_rcp_f32_e32 v217, v217
	s_nop 0
	v_pk_mul_f32 v[214:215], v[214:215], v[216:217]
	v_pk_mul_f32 v[214:215], v[32:33], v[214:215]
	v_cvt_pk_bf16_f32 v29, v214, v215
	s_add_i32 s26, s66, -16
	v_cmp_gt_i32_e64 s[24:25], s26, v227
	s_nop 1
	s_and_saveexec_b64 s[26:27], s[24:25]
	global_store_dwordx4 v242, v[26:29], s[18:19] offset:1024
	s_mov_b64 exec, s[26:27]
	s_nop 4
	v_mov_b32_dpp v210, v218 row_ror:1 row_mask:0xf bank_mask:0xf
	v_mov_b32_dpp v212, v218 row_ror:2 row_mask:0xf bank_mask:0xf
	v_mov_b32_dpp v211, v219 row_ror:1 row_mask:0xf bank_mask:0xf
	v_mov_b32_dpp v213, v219 row_ror:2 row_mask:0xf bank_mask:0xf
	s_nop 1
	v_mov_b32_dpp v210, v2 row_shr:1 row_mask:0xf bank_mask:0xf
	v_mov_b32_dpp v212, v2 row_shr:2 row_mask:0xf bank_mask:0xf
	v_mov_b32_dpp v211, v3 row_shr:1 row_mask:0xf bank_mask:0xf
	v_mov_b32_dpp v213, v3 row_shr:2 row_mask:0xf bank_mask:0xf
	s_nop 1
	v_pk_mul_f32 v[210:211], v[186:187], v[210:211]
	v_pk_fma_f32 v[214:215], v[194:195], v[2:3], v[210:211]
	v_pk_fma_f32 v[214:215], v[178:179], v[212:213], v[214:215]
	v_pk_add_f32 v[214:215], v[202:203], v[214:215]
	v_pk_mul_f32 v[216:217], v[214:215], s[92:93]
	v_pk_mul_f32 v[216:217], v[214:215], v[216:217]
	v_pk_fma_f32 v[216:217], v[214:215], v[216:217], v[214:215]
	v_pk_mul_f32 v[216:217], v[216:217], s[96:97]
	v_pk_mul_f32 v[216:217], v[216:217], s[28:29]
	v_exp_f32_e32 v216, v216
	v_exp_f32_e32 v217, v217
	s_nop 0
	v_add_f32_e32 v216, 1.0, v216
	v_add_f32_e32 v217, 1.0, v217
	v_rcp_f32_e32 v216, v216
	v_rcp_f32_e32 v217, v217
	s_nop 0
	v_pk_mul_f32 v[214:215], v[214:215], v[216:217]
	v_pk_mul_f32 v[214:215], v[10:11], v[214:215]
	v_cvt_pk_bf16_f32 v10, v214, v215
	v_mov_b32_dpp v210, v220 row_ror:1 row_mask:0xf bank_mask:0xf
	v_mov_b32_dpp v212, v220 row_ror:2 row_mask:0xf bank_mask:0xf
	v_mov_b32_dpp v211, v221 row_ror:1 row_mask:0xf bank_mask:0xf
	v_mov_b32_dpp v213, v221 row_ror:2 row_mask:0xf bank_mask:0xf
	s_nop 1
	v_mov_b32_dpp v210, v4 row_shr:1 row_mask:0xf bank_mask:0xf
	v_mov_b32_dpp v212, v4 row_shr:2 row_mask:0xf bank_mask:0xf
	v_mov_b32_dpp v211, v5 row_shr:1 row_mask:0xf bank_mask:0xf
	v_mov_b32_dpp v213, v5 row_shr:2 row_mask:0xf bank_mask:0xf
	s_nop 1
	v_pk_mul_f32 v[210:211], v[188:189], v[210:211]
	v_pk_fma_f32 v[214:215], v[196:197], v[4:5], v[210:211]
	v_pk_fma_f32 v[214:215], v[180:181], v[212:213], v[214:215]
	v_pk_add_f32 v[214:215], v[204:205], v[214:215]
	v_pk_mul_f32 v[216:217], v[214:215], s[92:93]
	v_pk_mul_f32 v[216:217], v[214:215], v[216:217]
	v_pk_fma_f32 v[216:217], v[214:215], v[216:217], v[214:215]
	v_pk_mul_f32 v[216:217], v[216:217], s[96:97]
	v_pk_mul_f32 v[216:217], v[216:217], s[28:29]
	v_exp_f32_e32 v216, v216
	v_exp_f32_e32 v217, v217
	s_nop 0
	v_add_f32_e32 v216, 1.0, v216
	v_add_f32_e32 v217, 1.0, v217
	v_rcp_f32_e32 v216, v216
	v_rcp_f32_e32 v217, v217
	s_nop 0
	v_pk_mul_f32 v[214:215], v[214:215], v[216:217]
	v_pk_mul_f32 v[214:215], v[12:13], v[214:215]
	v_cvt_pk_bf16_f32 v11, v214, v215
	v_mov_b32_dpp v210, v222 row_ror:1 row_mask:0xf bank_mask:0xf
	v_mov_b32_dpp v212, v222 row_ror:2 row_mask:0xf bank_mask:0xf
	v_mov_b32_dpp v211, v223 row_ror:1 row_mask:0xf bank_mask:0xf
	v_mov_b32_dpp v213, v223 row_ror:2 row_mask:0xf bank_mask:0xf
	s_nop 1
	v_mov_b32_dpp v210, v6 row_shr:1 row_mask:0xf bank_mask:0xf
	v_mov_b32_dpp v212, v6 row_shr:2 row_mask:0xf bank_mask:0xf
	v_mov_b32_dpp v211, v7 row_shr:1 row_mask:0xf bank_mask:0xf
	v_mov_b32_dpp v213, v7 row_shr:2 row_mask:0xf bank_mask:0xf
	s_nop 1
	v_pk_mul_f32 v[210:211], v[190:191], v[210:211]
	v_pk_fma_f32 v[214:215], v[198:199], v[6:7], v[210:211]
	v_pk_fma_f32 v[214:215], v[182:183], v[212:213], v[214:215]
	v_pk_add_f32 v[214:215], v[206:207], v[214:215]
	v_pk_mul_f32 v[216:217], v[214:215], s[92:93]
	v_pk_mul_f32 v[216:217], v[214:215], v[216:217]
	v_pk_fma_f32 v[216:217], v[214:215], v[216:217], v[214:215]
	v_pk_mul_f32 v[216:217], v[216:217], s[96:97]
	v_pk_mul_f32 v[216:217], v[216:217], s[28:29]
	v_exp_f32_e32 v216, v216
	v_exp_f32_e32 v217, v217
	s_nop 0
	v_add_f32_e32 v216, 1.0, v216
	v_add_f32_e32 v217, 1.0, v217
	v_rcp_f32_e32 v216, v216
	v_rcp_f32_e32 v217, v217
	s_nop 0
	v_pk_mul_f32 v[214:215], v[214:215], v[216:217]
	v_pk_mul_f32 v[214:215], v[14:15], v[214:215]
	v_cvt_pk_bf16_f32 v12, v214, v215
	v_mov_b32_dpp v210, v224 row_ror:1 row_mask:0xf bank_mask:0xf
	v_mov_b32_dpp v212, v224 row_ror:2 row_mask:0xf bank_mask:0xf
	v_mov_b32_dpp v211, v225 row_ror:1 row_mask:0xf bank_mask:0xf
	v_mov_b32_dpp v213, v225 row_ror:2 row_mask:0xf bank_mask:0xf
	s_nop 1
	v_mov_b32_dpp v210, v8 row_shr:1 row_mask:0xf bank_mask:0xf
	v_mov_b32_dpp v212, v8 row_shr:2 row_mask:0xf bank_mask:0xf
	v_mov_b32_dpp v211, v9 row_shr:1 row_mask:0xf bank_mask:0xf
	v_mov_b32_dpp v213, v9 row_shr:2 row_mask:0xf bank_mask:0xf
	s_nop 1
	v_pk_mul_f32 v[210:211], v[192:193], v[210:211]
	v_pk_fma_f32 v[214:215], v[200:201], v[8:9], v[210:211]
	v_pk_fma_f32 v[214:215], v[184:185], v[212:213], v[214:215]
	v_pk_add_f32 v[214:215], v[208:209], v[214:215]
	v_pk_mul_f32 v[216:217], v[214:215], s[92:93]
	v_pk_mul_f32 v[216:217], v[214:215], v[216:217]
	v_pk_fma_f32 v[216:217], v[214:215], v[216:217], v[214:215]
	v_pk_mul_f32 v[216:217], v[216:217], s[96:97]
	v_pk_mul_f32 v[216:217], v[216:217], s[28:29]
	v_exp_f32_e32 v216, v216
	v_exp_f32_e32 v217, v217
	s_nop 0
	v_add_f32_e32 v216, 1.0, v216
	v_add_f32_e32 v217, 1.0, v217
	v_rcp_f32_e32 v216, v216
	v_rcp_f32_e32 v217, v217
	s_nop 0
	v_pk_mul_f32 v[214:215], v[214:215], v[216:217]
	v_pk_mul_f32 v[214:215], v[16:17], v[214:215]
	v_cvt_pk_bf16_f32 v13, v214, v215
	s_add_i32 s26, s66, 0
	v_cmp_gt_i32_e64 s[24:25], s26, v227
	v_cmp_lt_u32_e32 vcc, 1, v227
	s_and_b64 s[24:25], s[24:25], vcc
	s_nop 1
	s_and_saveexec_b64 s[26:27], s[24:25]
	global_store_dwordx4 v242, v[10:13], s[18:19]
	s_mov_b64 exec, s[26:27]
	s_nop 4
	s_mov_b32 s34, s38
	s_mov_b32 s35, s30
	s_mov_b32 s36, s31
	s_branch .Lup_tile
.Lup_tail_last:
	s_waitcnt vmcnt(6) lgkmcnt(0)
	s_barrier
	v_add_u32_e32 v240, s61, v238
	v_add_u32_e32 v241, s61, v239
	s_setprio 1
	s_add_i32 m0, s60, s62
	v_mfma_f32_16x16x32_bf16 v[2:5], v[162:165], v[130:133], v[2:5]
	global_load_lds_dwordx4 v226, s[54:55]
	v_mfma_f32_16x16x32_bf16 v[6:9], v[166:169], v[130:133], v[6:9]
	global_load_lds_dwordx4 v226, s[54:55] offset:1024
	v_mfma_f32_16x16x32_bf16 v[10:13], v[170:173], v[130:133], v[10:13]
	global_load_lds_dwordx4 v226, s[54:55] offset:2048
	v_mfma_f32_16x16x32_bf16 v[14:17], v[174:177], v[130:133], v[14:17]
	global_load_lds_dwordx4 v226, s[54:55] offset:3072
	s_add_i32 m0, s60, s63
	v_mfma_f32_16x16x32_bf16 v[18:21], v[162:165], v[134:137], v[18:21]
	global_load_lds_dwordx4 v230, s[56:57]
	v_mfma_f32_16x16x32_bf16 v[22:25], v[166:169], v[134:137], v[22:25]
	global_load_lds_dwordx4 v231, s[56:57] offset:1024
	v_mfma_f32_16x16x32_bf16 v[26:29], v[170:173], v[134:137], v[26:29]
	v_mfma_f32_16x16x32_bf16 v[30:33], v[174:177], v[134:137], v[30:33]
	v_mfma_f32_16x16x32_bf16 v[34:37], v[162:165], v[138:141], v[34:37]
	ds_read_b128 v[210:213], v241 offset:0
	v_mfma_f32_16x16x32_bf16 v[38:41], v[166:169], v[138:141], v[38:41]
	ds_read_b128 v[214:217], v241 offset:256
	v_mfma_f32_16x16x32_bf16 v[42:45], v[170:173], v[138:141], v[42:45]
	ds_read_b128 v[218:221], v241 offset:2048
	v_mfma_f32_16x16x32_bf16 v[46:49], v[174:177], v[138:141], v[46:49]
	ds_read_b128 v[222:225], v241 offset:2304
	v_mfma_f32_16x16x32_bf16 v[50:53], v[162:165], v[142:145], v[50:53]
	ds_read_b128 v[178:181], v240 offset:0
	v_mfma_f32_16x16x32_bf16 v[54:57], v[166:169], v[142:145], v[54:57]
	ds_read_b128 v[182:185], v240 offset:1024
	v_mfma_f32_16x16x32_bf16 v[58:61], v[170:173], v[142:145], v[58:61]
	ds_read_b128 v[186:189], v240 offset:2048
	v_mfma_f32_16x16x32_bf16 v[62:65], v[174:177], v[142:145], v[62:65]
	ds_read_b128 v[190:193], v240 offset:3072
	v_mfma_f32_16x16x32_bf16 v[66:69], v[162:165], v[146:149], v[66:69]
	ds_read_b128 v[194:197], v240 offset:4096
	v_mfma_f32_16x16x32_bf16 v[70:73], v[166:169], v[146:149], v[70:73]
	ds_read_b128 v[198:201], v240 offset:5120
	v_mfma_f32_16x16x32_bf16 v[74:77], v[170:173], v[146:149], v[74:77]
	ds_read_b128 v[202:205], v240 offset:6144
	v_mfma_f32_16x16x32_bf16 v[78:81], v[174:177], v[146:149], v[78:81]
	ds_read_b128 v[206:209], v240 offset:7168
	v_mfma_f32_16x16x32_bf16 v[82:85], v[162:165], v[150:153], v[82:85]
	v_mfma_f32_16x16x32_bf16 v[86:89], v[166:169], v[150:153], v[86:89]
	v_mfma_f32_16x16x32_bf16 v[90:93], v[170:173], v[150:153], v[90:93]
	v_mfma_f32_16x16x32_bf16 v[94:97], v[174:177], v[150:153], v[94:97]
	v_mfma_f32_16x16x32_bf16 v[98:101], v[162:165], v[154:157], v[98:101]
	v_mfma_f32_16x16x32_bf16 v[102:105], v[166:169], v[154:157], v[102:105]
	v_mfma_f32_16x16x32_bf16 v[106:109], v[170:173], v[154:157], v[106:109]
	v_mfma_f32_16x16x32_bf16 v[110:113], v[174:177], v[154:157], v[110:113]
	v_mfma_f32_16x16x32_bf16 v[114:117], v[162:165], v[158:161], v[114:117]
	v_mfma_f32_16x16x32_bf16 v[118:121], v[166:169], v[158:161], v[118:121]
	v_mfma_f32_16x16x32_bf16 v[122:125], v[170:173], v[158:161], v[122:125]
	v_mfma_f32_16x16x32_bf16 v[126:129], v[174:177], v[158:161], v[126:129]
	s_setprio 0
	s_add_i32 s60, s60, 0x6000
	s_cmp_eq_u32 s60, 0x12000
	s_cselect_b32 s60, 0, s60
	s_add_u32 s54, s54, s72
	s_addc_u32 s55, s55, 0
	s_add_u32 s56, s56, s73
	s_addc_u32 s57, s57, 0
	s_add_i32 s61, s61, 0x6000
	s_cmp_eq_u32 s61, 0x12000
	s_cselect_b32 s61, 0, s61
	s_waitcnt vmcnt(6) lgkmcnt(0)
	s_barrier
	v_add_u32_e32 v240, s61, v238
	v_add_u32_e32 v241, s61, v239
	s_setprio 1
	v_mfma_f32_16x16x32_bf16 v[2:5], v[210:213], v[178:181], v[2:5]
	v_mfma_f32_16x16x32_bf16 v[6:9], v[214:217], v[178:181], v[6:9]
	v_mfma_f32_16x16x32_bf16 v[10:13], v[218:221], v[178:181], v[10:13]
	v_mfma_f32_16x16x32_bf16 v[14:17], v[222:225], v[178:181], v[14:17]
	v_mfma_f32_16x16x32_bf16 v[18:21], v[210:213], v[182:185], v[18:21]
	v_mfma_f32_16x16x32_bf16 v[22:25], v[214:217], v[182:185], v[22:25]
	v_mfma_f32_16x16x32_bf16 v[26:29], v[218:221], v[182:185], v[26:29]
	v_mfma_f32_16x16x32_bf16 v[30:33], v[222:225], v[182:185], v[30:33]
	v_mfma_f32_16x16x32_bf16 v[34:37], v[210:213], v[186:189], v[34:37]
	ds_read_b128 v[162:165], v241 offset:0
	v_mfma_f32_16x16x32_bf16 v[38:41], v[214:217], v[186:189], v[38:41]
	ds_read_b128 v[166:169], v241 offset:256
	v_mfma_f32_16x16x32_bf16 v[42:45], v[218:221], v[186:189], v[42:45]
	ds_read_b128 v[170:173], v241 offset:2048
	v_mfma_f32_16x16x32_bf16 v[46:49], v[222:225], v[186:189], v[46:49]
	ds_read_b128 v[174:177], v241 offset:2304
	v_mfma_f32_16x16x32_bf16 v[50:53], v[210:213], v[190:193], v[50:53]
	ds_read_b128 v[130:133], v240 offset:0
	v_mfma_f32_16x16x32_bf16 v[54:57], v[214:217], v[190:193], v[54:57]
	ds_read_b128 v[134:137], v240 offset:1024
	v_mfma_f32_16x16x32_bf16 v[58:61], v[218:221], v[190:193], v[58:61]
	ds_read_b128 v[138:141], v240 offset:2048
	v_mfma_f32_16x16x32_bf16 v[62:65], v[222:225], v[190:193], v[62:65]
	ds_read_b128 v[142:145], v240 offset:3072
	v_mfma_f32_16x16x32_bf16 v[66:69], v[210:213], v[194:197], v[66:69]
	ds_read_b128 v[146:149], v240 offset:4096
	v_mfma_f32_16x16x32_bf16 v[70:73], v[214:217], v[194:197], v[70:73]
	ds_read_b128 v[150:153], v240 offset:5120
	v_mfma_f32_16x16x32_bf16 v[74:77], v[218:221], v[194:197], v[74:77]
	ds_read_b128 v[154:157], v240 offset:6144
	v_mfma_f32_16x16x32_bf16 v[78:81], v[222:225], v[194:197], v[78:81]
	ds_read_b128 v[158:161], v240 offset:7168
	v_mfma_f32_16x16x32_bf16 v[82:85], v[210:213], v[198:201], v[82:85]
	v_mfma_f32_16x16x32_bf16 v[86:89], v[214:217], v[198:201], v[86:89]
	v_mfma_f32_16x16x32_bf16 v[90:93], v[218:221], v[198:201], v[90:93]
	v_mfma_f32_16x16x32_bf16 v[94:97], v[222:225], v[198:201], v[94:97]
	v_mfma_f32_16x16x32_bf16 v[98:101], v[210:213], v[202:205], v[98:101]
	v_mfma_f32_16x16x32_bf16 v[102:105], v[214:217], v[202:205], v[102:105]
	v_mfma_f32_16x16x32_bf16 v[106:109], v[218:221], v[202:205], v[106:109]
	v_mfma_f32_16x16x32_bf16 v[110:113], v[222:225], v[202:205], v[110:113]
	v_mfma_f32_16x16x32_bf16 v[114:117], v[210:213], v[206:209], v[114:117]
	v_mfma_f32_16x16x32_bf16 v[118:121], v[214:217], v[206:209], v[118:121]
	v_mfma_f32_16x16x32_bf16 v[122:125], v[218:221], v[206:209], v[122:125]
	v_mfma_f32_16x16x32_bf16 v[126:129], v[222:225], v[206:209], v[126:129]
	s_setprio 0
	s_add_i32 s61, s61, 0x6000
	s_cmp_eq_u32 s61, 0x12000
	s_cselect_b32 s61, 0, s61
	s_waitcnt vmcnt(0) lgkmcnt(0)
	s_barrier
	v_add_u32_e32 v240, s61, v238
	v_add_u32_e32 v241, s61, v239
	s_setprio 1
	v_mfma_f32_16x16x32_bf16 v[2:5], v[162:165], v[130:133], v[2:5]
	v_mfma_f32_16x16x32_bf16 v[6:9], v[166:169], v[130:133], v[6:9]
	v_mfma_f32_16x16x32_bf16 v[10:13], v[170:173], v[130:133], v[10:13]
	v_mfma_f32_16x16x32_bf16 v[14:17], v[174:177], v[130:133], v[14:17]
	v_mfma_f32_16x16x32_bf16 v[18:21], v[162:165], v[134:137], v[18:21]
	v_mfma_f32_16x16x32_bf16 v[22:25], v[166:169], v[134:137], v[22:25]
	v_mfma_f32_16x16x32_bf16 v[26:29], v[170:173], v[134:137], v[26:29]
	v_mfma_f32_16x16x32_bf16 v[30:33], v[174:177], v[134:137], v[30:33]
	v_mfma_f32_16x16x32_bf16 v[34:37], v[162:165], v[138:141], v[34:37]
	ds_read_b128 v[210:213], v241 offset:0
	v_mfma_f32_16x16x32_bf16 v[38:41], v[166:169], v[138:141], v[38:41]
	ds_read_b128 v[214:217], v241 offset:256
	v_mfma_f32_16x16x32_bf16 v[42:45], v[170:173], v[138:141], v[42:45]
	ds_read_b128 v[218:221], v241 offset:2048
	v_mfma_f32_16x16x32_bf16 v[46:49], v[174:177], v[138:141], v[46:49]
	ds_read_b128 v[222:225], v241 offset:2304
	v_mfma_f32_16x16x32_bf16 v[50:53], v[162:165], v[142:145], v[50:53]
	ds_read_b128 v[178:181], v240 offset:0
	v_mfma_f32_16x16x32_bf16 v[54:57], v[166:169], v[142:145], v[54:57]
	ds_read_b128 v[182:185], v240 offset:1024
	v_mfma_f32_16x16x32_bf16 v[58:61], v[170:173], v[142:145], v[58:61]
	ds_read_b128 v[186:189], v240 offset:2048
	v_mfma_f32_16x16x32_bf16 v[62:65], v[174:177], v[142:145], v[62:65]
	ds_read_b128 v[190:193], v240 offset:3072
	v_mfma_f32_16x16x32_bf16 v[66:69], v[162:165], v[146:149], v[66:69]
	ds_read_b128 v[194:197], v240 offset:4096
	v_mfma_f32_16x16x32_bf16 v[70:73], v[166:169], v[146:149], v[70:73]
	ds_read_b128 v[198:201], v240 offset:5120
	v_mfma_f32_16x16x32_bf16 v[74:77], v[170:173], v[146:149], v[74:77]
	ds_read_b128 v[202:205], v240 offset:6144
	v_mfma_f32_16x16x32_bf16 v[78:81], v[174:177], v[146:149], v[78:81]
	ds_read_b128 v[206:209], v240 offset:7168
	v_mfma_f32_16x16x32_bf16 v[82:85], v[162:165], v[150:153], v[82:85]
	v_mfma_f32_16x16x32_bf16 v[86:89], v[166:169], v[150:153], v[86:89]
	v_mfma_f32_16x16x32_bf16 v[90:93], v[170:173], v[150:153], v[90:93]
	v_mfma_f32_16x16x32_bf16 v[94:97], v[174:177], v[150:153], v[94:97]
	v_mfma_f32_16x16x32_bf16 v[98:101], v[162:165], v[154:157], v[98:101]
	v_mfma_f32_16x16x32_bf16 v[102:105], v[166:169], v[154:157], v[102:105]
	v_mfma_f32_16x16x32_bf16 v[106:109], v[170:173], v[154:157], v[106:109]
	v_mfma_f32_16x16x32_bf16 v[110:113], v[174:177], v[154:157], v[110:113]
	v_mfma_f32_16x16x32_bf16 v[114:117], v[162:165], v[158:161], v[114:117]
	v_mfma_f32_16x16x32_bf16 v[118:121], v[166:169], v[158:161], v[118:121]
	v_mfma_f32_16x16x32_bf16 v[122:125], v[170:173], v[158:161], v[122:125]
	v_mfma_f32_16x16x32_bf16 v[126:129], v[174:177], v[158:161], v[126:129]
	s_setprio 0
	s_add_i32 s61, s61, 0x6000
	s_cmp_eq_u32 s61, 0x12000
	s_cselect_b32 s61, 0, s61
	s_waitcnt lgkmcnt(0)
	s_barrier
	s_setprio 1
	v_mfma_f32_16x16x32_bf16 v[2:5], v[210:213], v[178:181], v[2:5]
	v_mfma_f32_16x16x32_bf16 v[6:9], v[214:217], v[178:181], v[6:9]
	v_mfma_f32_16x16x32_bf16 v[10:13], v[218:221], v[178:181], v[10:13]
	v_mfma_f32_16x16x32_bf16 v[14:17], v[222:225], v[178:181], v[14:17]
	v_mfma_f32_16x16x32_bf16 v[18:21], v[210:213], v[182:185], v[18:21]
	v_mfma_f32_16x16x32_bf16 v[22:25], v[214:217], v[182:185], v[22:25]
	v_mfma_f32_16x16x32_bf16 v[26:29], v[218:221], v[182:185], v[26:29]
	v_mfma_f32_16x16x32_bf16 v[30:33], v[222:225], v[182:185], v[30:33]
	v_mfma_f32_16x16x32_bf16 v[34:37], v[210:213], v[186:189], v[34:37]
	v_mfma_f32_16x16x32_bf16 v[38:41], v[214:217], v[186:189], v[38:41]
	v_mfma_f32_16x16x32_bf16 v[42:45], v[218:221], v[186:189], v[42:45]
	v_mfma_f32_16x16x32_bf16 v[46:49], v[222:225], v[186:189], v[46:49]
	v_mfma_f32_16x16x32_bf16 v[50:53], v[210:213], v[190:193], v[50:53]
	v_mfma_f32_16x16x32_bf16 v[54:57], v[214:217], v[190:193], v[54:57]
	v_mfma_f32_16x16x32_bf16 v[58:61], v[218:221], v[190:193], v[58:61]
	v_mfma_f32_16x16x32_bf16 v[62:65], v[222:225], v[190:193], v[62:65]
	v_mfma_f32_16x16x32_bf16 v[66:69], v[210:213], v[194:197], v[66:69]
	v_mfma_f32_16x16x32_bf16 v[70:73], v[214:217], v[194:197], v[70:73]
	v_mfma_f32_16x16x32_bf16 v[74:77], v[218:221], v[194:197], v[74:77]
	v_mfma_f32_16x16x32_bf16 v[78:81], v[222:225], v[194:197], v[78:81]
	v_mfma_f32_16x16x32_bf16 v[82:85], v[210:213], v[198:201], v[82:85]
	v_mfma_f32_16x16x32_bf16 v[86:89], v[214:217], v[198:201], v[86:89]
	v_mfma_f32_16x16x32_bf16 v[90:93], v[218:221], v[198:201], v[90:93]
	v_mfma_f32_16x16x32_bf16 v[94:97], v[222:225], v[198:201], v[94:97]
	v_mfma_f32_16x16x32_bf16 v[98:101], v[210:213], v[202:205], v[98:101]
	v_mfma_f32_16x16x32_bf16 v[102:105], v[214:217], v[202:205], v[102:105]
	v_mfma_f32_16x16x32_bf16 v[106:109], v[218:221], v[202:205], v[106:109]
	v_mfma_f32_16x16x32_bf16 v[110:113], v[222:225], v[202:205], v[110:113]
	v_mfma_f32_16x16x32_bf16 v[114:117], v[210:213], v[206:209], v[114:117]
	v_mfma_f32_16x16x32_bf16 v[118:121], v[214:217], v[206:209], v[118:121]
	v_mfma_f32_16x16x32_bf16 v[122:125], v[218:221], v[206:209], v[122:125]
	v_mfma_f32_16x16x32_bf16 v[126:129], v[222:225], v[206:209], v[126:129]
	s_setprio 0
	s_and_b32 s39, s35, 0xfff
	s_lshr_b32 s21, s36, 7
	s_waitcnt vmcnt(0)
	v_mbcnt_lo_u32_b32 v217, -1, 0
	v_mbcnt_hi_u32_b32 v217, -1, v217
	v_lshlrev_b32_e32 v217, 5, v217
	s_lshl_b32 s26, s43, 11
	s_add_i32 s26, s26, 0x12010
	v_add_u32_e32 v217, s26, v217
	s_cmp_eq_u32 s42, 0
	s_cbranch_scc0 .Lup_el_nowr
	ds_write_b128 v217, v[114:117]
	ds_write_b128 v217, v[118:121] offset:16

.Lup_el_cont:
	v_add_u32_e32 v216, 0x13010, v228
	ds_read_b128 v[178:181], v216 offset:0
	ds_read_b128 v[182:185], v216 offset:16
	ds_read_b128 v[186:189], v216 offset:256
	ds_read_b128 v[190:193], v216 offset:272
	ds_read_b128 v[194:197], v216 offset:512
	ds_read_b128 v[198:201], v216 offset:528
	ds_read_b128 v[202:205], v216 offset:768
	ds_read_b128 v[206:209], v216 offset:784
	s_lshl_b32 s26, s21, 1
	s_add_i32 s26, s26, s43
	s_lshl_b32 s26, s26, 20
	s_lshl_b32 s27, s35, 6
	s_add_u32 s18, s52, s26
	s_addc_u32 s19, s53, 0
	s_add_u32 s18, s18, s27
	s_addc_u32 s19, s19, 0
	s_sub_u32 s18, s18, 0x80
	s_subb_u32 s19, s19, 0
	s_add_u32 s6, s18, 0x1000
	s_addc_u32 s7, s19, 0
	s_sub_i32 s66, 0x1002, s39
	s_waitcnt lgkmcnt(0)
	v_mov_b32_dpp v210, v98 row_ror:1 row_mask:0xf bank_mask:0xf
	v_mov_b32_dpp v212, v98 row_ror:2 row_mask:0xf bank_mask:0xf
	v_mov_b32_dpp v211, v99 row_ror:1 row_mask:0xf bank_mask:0xf
	v_mov_b32_dpp v213, v99 row_ror:2 row_mask:0xf bank_mask:0xf
	s_nop 1
	v_mov_b32_dpp v210, v114 row_shr:1 row_mask:0xf bank_mask:0xf
	v_mov_b32_dpp v212, v114 row_shr:2 row_mask:0xf bank_mask:0xf
	v_mov_b32_dpp v211, v115 row_shr:1 row_mask:0xf bank_mask:0xf
	v_mov_b32_dpp v213, v115 row_shr:2 row_mask:0xf bank_mask:0xf
	s_nop 1
	v_pk_mul_f32 v[210:211], v[186:187], v[210:211]
	v_pk_fma_f32 v[214:215], v[194:195], v[114:115], v[210:211]
	v_pk_fma_f32 v[214:215], v[178:179], v[212:213], v[214:215]
	v_pk_add_f32 v[214:215], v[202:203], v[214:215]
	v_pk_mul_f32 v[216:217], v[214:215], s[92:93]
	v_pk_mul_f32 v[216:217], v[214:215], v[216:217]
	v_pk_fma_f32 v[216:217], v[214:215], v[216:217], v[214:215]
	v_pk_mul_f32 v[216:217], v[216:217], s[96:97]
	v_pk_mul_f32 v[216:217], v[216:217], s[28:29]
	v_exp_f32_e32 v216, v216
	v_exp_f32_e32 v217, v217
	s_nop 0
	v_add_f32_e32 v216, 1.0, v216
	v_add_f32_e32 v217, 1.0, v217
	v_rcp_f32_e32 v216, v216
	v_rcp_f32_e32 v217, v217
	s_nop 0
	v_pk_mul_f32 v[214:215], v[214:215], v[216:217]
	v_pk_mul_f32 v[214:215], v[122:123], v[214:215]
	v_cvt_pk_bf16_f32 v122, v214, v215
	v_mov_b32_dpp v210, v100 row_ror:1 row_mask:0xf bank_mask:0xf
	v_mov_b32_dpp v212, v100 row_ror:2 row_mask:0xf bank_mask:0xf
	v_mov_b32_dpp v211, v101 row_ror:1 row_mask:0xf bank_mask:0xf
	v_mov_b32_dpp v213, v101 row_ror:2 row_mask:0xf bank_mask:0xf
	s_nop 1
	v_mov_b32_dpp v210, v116 row_shr:1 row_mask:0xf bank_mask:0xf
	v_mov_b32_dpp v212, v116 row_shr:2 row_mask:0xf bank_mask:0xf
	v_mov_b32_dpp v211, v117 row_shr:1 row_mask:0xf bank_mask:0xf
	v_mov_b32_dpp v213, v117 row_shr:2 row_mask:0xf bank_mask:0xf
	s_nop 1
	v_pk_mul_f32 v[210:211], v[188:189], v[210:211]
	v_pk_fma_f32 v[214:215], v[196:197], v[116:117], v[210:211]
	v_pk_fma_f32 v[214:215], v[180:181], v[212:213], v[214:215]
	v_pk_add_f32 v[214:215], v[204:205], v[214:215]
	v_pk_mul_f32 v[216:217], v[214:215], s[92:93]
	v_pk_mul_f32 v[216:217], v[214:215], v[216:217]
	v_pk_fma_f32 v[216:217], v[214:215], v[216:217], v[214:215]
	v_pk_mul_f32 v[216:217], v[216:217], s[96:97]
	v_pk_mul_f32 v[216:217], v[216:217], s[28:29]
	v_exp_f32_e32 v216, v216
	v_exp_f32_e32 v217, v217
	s_nop 0
	v_add_f32_e32 v216, 1.0, v216
	v_add_f32_e32 v217, 1.0, v217
	v_rcp_f32_e32 v216, v216
	v_rcp_f32_e32 v217, v217
	s_nop 0
	v_pk_mul_f32 v[214:215], v[214:215], v[216:217]
	v_pk_mul_f32 v[214:215], v[124:125], v[214:215]
	v_cvt_pk_bf16_f32 v123, v214, v215
	v_mov_b32_dpp v210, v102 row_ror:1 row_mask:0xf bank_mask:0xf
	v_mov_b32_dpp v212, v102 row_ror:2 row_mask:0xf bank_mask:0xf
	v_mov_b32_dpp v211, v103 row_ror:1 row_mask:0xf bank_mask:0xf
	v_mov_b32_dpp v213, v103 row_ror:2 row_mask:0xf bank_mask:0xf
	s_nop 1
	v_mov_b32_dpp v210, v118 row_shr:1 row_mask:0xf bank_mask:0xf
	v_mov_b32_dpp v212, v118 row_shr:2 row_mask:0xf bank_mask:0xf
	v_mov_b32_dpp v211, v119 row_shr:1 row_mask:0xf bank_mask:0xf
	v_mov_b32_dpp v213, v119 row_shr:2 row_mask:0xf bank_mask:0xf
	s_nop 1
	v_pk_mul_f32 v[210:211], v[190:191], v[210:211]
	v_pk_fma_f32 v[214:215], v[198:199], v[118:119], v[210:211]
	v_pk_fma_f32 v[214:215], v[182:183], v[212:213], v[214:215]
	v_pk_add_f32 v[214:215], v[206:207], v[214:215]
	v_pk_mul_f32 v[216:217], v[214:215], s[92:93]
	v_pk_mul_f32 v[216:217], v[214:215], v[216:217]
	v_pk_fma_f32 v[216:217], v[214:215], v[216:217], v[214:215]
	v_pk_mul_f32 v[216:217], v[216:217], s[96:97]
	v_pk_mul_f32 v[216:217], v[216:217], s[28:29]
	v_exp_f32_e32 v216, v216
	v_exp_f32_e32 v217, v217
	s_nop 0
	v_add_f32_e32 v216, 1.0, v216
	v_add_f32_e32 v217, 1.0, v217
	v_rcp_f32_e32 v216, v216
	v_rcp_f32_e32 v217, v217
	s_nop 0
	v_pk_mul_f32 v[214:215], v[214:215], v[216:217]
	v_pk_mul_f32 v[214:215], v[126:127], v[214:215]
	v_cvt_pk_bf16_f32 v124, v214, v215
	v_mov_b32_dpp v210, v104 row_ror:1 row_mask:0xf bank_mask:0xf
	v_mov_b32_dpp v212, v104 row_ror:2 row_mask:0xf bank_mask:0xf
	v_mov_b32_dpp v211, v105 row_ror:1 row_mask:0xf bank_mask:0xf
	v_mov_b32_dpp v213, v105 row_ror:2 row_mask:0xf bank_mask:0xf
	s_nop 1
	v_mov_b32_dpp v210, v120 row_shr:1 row_mask:0xf bank_mask:0xf
	v_mov_b32_dpp v212, v120 row_shr:2 row_mask:0xf bank_mask:0xf
	v_mov_b32_dpp v211, v121 row_shr:1 row_mask:0xf bank_mask:0xf
	v_mov_b32_dpp v213, v121 row_shr:2 row_mask:0xf bank_mask:0xf
	s_nop 1
	v_pk_mul_f32 v[210:211], v[192:193], v[210:211]
	v_pk_fma_f32 v[214:215], v[200:201], v[120:121], v[210:211]
	v_pk_fma_f32 v[214:215], v[184:185], v[212:213], v[214:215]
	v_pk_add_f32 v[214:215], v[208:209], v[214:215]
	v_pk_mul_f32 v[216:217], v[214:215], s[92:93]
	v_pk_mul_f32 v[216:217], v[214:215], v[216:217]
	v_pk_fma_f32 v[216:217], v[214:215], v[216:217], v[214:215]
	v_pk_mul_f32 v[216:217], v[216:217], s[96:97]
	v_pk_mul_f32 v[216:217], v[216:217], s[28:29]
	v_exp_f32_e32 v216, v216
	v_exp_f32_e32 v217, v217
	s_nop 0
	v_add_f32_e32 v216, 1.0, v216
	v_add_f32_e32 v217, 1.0, v217
	v_rcp_f32_e32 v216, v216
	v_rcp_f32_e32 v217, v217
	s_nop 0
	v_pk_mul_f32 v[214:215], v[214:215], v[216:217]
	v_pk_mul_f32 v[214:215], v[128:129], v[214:215]
	v_cvt_pk_bf16_f32 v125, v214, v215
	s_add_i32 s26, s66, -112
	v_cmp_gt_i32_e64 s[24:25], s26, v227
	s_nop 1
	s_and_saveexec_b64 s[26:27], s[24:25]
	global_store_dwordx4 v242, v[122:125], s[6:7] offset:3072
	s_mov_b64 exec, s[26:27]
	s_nop 4
	v_mov_b32_dpp v210, v82 row_ror:1 row_mask:0xf bank_mask:0xf
	v_mov_b32_dpp v212, v82 row_ror:2 row_mask:0xf bank_mask:0xf
	v_mov_b32_dpp v211, v83 row_ror:1 row_mask:0xf bank_mask:0xf
	v_mov_b32_dpp v213, v83 row_ror:2 row_mask:0xf bank_mask:0xf
	s_nop 1
	v_mov_b32_dpp v210, v98 row_shr:1 row_mask:0xf bank_mask:0xf
	v_mov_b32_dpp v212, v98 row_shr:2 row_mask:0xf bank_mask:0xf
	v_mov_b32_dpp v211, v99 row_shr:1 row_mask:0xf bank_mask:0xf
	v_mov_b32_dpp v213, v99 row_shr:2 row_mask:0xf bank_mask:0xf
	s_nop 1
	v_pk_mul_f32 v[210:211], v[186:187], v[210:211]
	v_pk_fma_f32 v[214:215], v[194:195], v[98:99], v[210:211]
	v_pk_fma_f32 v[214:215], v[178:179], v[212:213], v[214:215]
	v_pk_add_f32 v[214:215], v[202:203], v[214:215]
	v_pk_mul_f32 v[216:217], v[214:215], s[92:93]
	v_pk_mul_f32 v[216:217], v[214:215], v[216:217]
	v_pk_fma_f32 v[216:217], v[214:215], v[216:217], v[214:215]
	v_pk_mul_f32 v[216:217], v[216:217], s[96:97]
	v_pk_mul_f32 v[216:217], v[216:217], s[28:29]
	v_exp_f32_e32 v216, v216
	v_exp_f32_e32 v217, v217
	s_nop 0
	v_add_f32_e32 v216, 1.0, v216
	v_add_f32_e32 v217, 1.0, v217
	v_rcp_f32_e32 v216, v216
	v_rcp_f32_e32 v217, v217
	s_nop 0
	v_pk_mul_f32 v[214:215], v[214:215], v[216:217]
	v_pk_mul_f32 v[214:215], v[106:107], v[214:215]
	v_cvt_pk_bf16_f32 v106, v214, v215
	v_mov_b32_dpp v210, v84 row_ror:1 row_mask:0xf bank_mask:0xf
	v_mov_b32_dpp v212, v84 row_ror:2 row_mask:0xf bank_mask:0xf
	v_mov_b32_dpp v211, v85 row_ror:1 row_mask:0xf bank_mask:0xf
	v_mov_b32_dpp v213, v85 row_ror:2 row_mask:0xf bank_mask:0xf
	s_nop 1
	v_mov_b32_dpp v210, v100 row_shr:1 row_mask:0xf bank_mask:0xf
	v_mov_b32_dpp v212, v100 row_shr:2 row_mask:0xf bank_mask:0xf
	v_mov_b32_dpp v211, v101 row_shr:1 row_mask:0xf bank_mask:0xf
	v_mov_b32_dpp v213, v101 row_shr:2 row_mask:0xf bank_mask:0xf
	s_nop 1
	v_pk_mul_f32 v[210:211], v[188:189], v[210:211]
	v_pk_fma_f32 v[214:215], v[196:197], v[100:101], v[210:211]
	v_pk_fma_f32 v[214:215], v[180:181], v[212:213], v[214:215]
	v_pk_add_f32 v[214:215], v[204:205], v[214:215]
	v_pk_mul_f32 v[216:217], v[214:215], s[92:93]
	v_pk_mul_f32 v[216:217], v[214:215], v[216:217]
	v_pk_fma_f32 v[216:217], v[214:215], v[216:217], v[214:215]
	v_pk_mul_f32 v[216:217], v[216:217], s[96:97]
	v_pk_mul_f32 v[216:217], v[216:217], s[28:29]
	v_exp_f32_e32 v216, v216
	v_exp_f32_e32 v217, v217
	s_nop 0
	v_add_f32_e32 v216, 1.0, v216
	v_add_f32_e32 v217, 1.0, v217
	v_rcp_f32_e32 v216, v216
	v_rcp_f32_e32 v217, v217
	s_nop 0
	v_pk_mul_f32 v[214:215], v[214:215], v[216:217]
	v_pk_mul_f32 v[214:215], v[108:109], v[214:215]
	v_cvt_pk_bf16_f32 v107, v214, v215
	v_mov_b32_dpp v210, v86 row_ror:1 row_mask:0xf bank_mask:0xf
	v_mov_b32_dpp v212, v86 row_ror:2 row_mask:0xf bank_mask:0xf
	v_mov_b32_dpp v211, v87 row_ror:1 row_mask:0xf bank_mask:0xf
	v_mov_b32_dpp v213, v87 row_ror:2 row_mask:0xf bank_mask:0xf
	s_nop 1
	v_mov_b32_dpp v210, v102 row_shr:1 row_mask:0xf bank_mask:0xf
	v_mov_b32_dpp v212, v102 row_shr:2 row_mask:0xf bank_mask:0xf
	v_mov_b32_dpp v211, v103 row_shr:1 row_mask:0xf bank_mask:0xf
	v_mov_b32_dpp v213, v103 row_shr:2 row_mask:0xf bank_mask:0xf
	s_nop 1
	v_pk_mul_f32 v[210:211], v[190:191], v[210:211]
	v_pk_fma_f32 v[214:215], v[198:199], v[102:103], v[210:211]
	v_pk_fma_f32 v[214:215], v[182:183], v[212:213], v[214:215]
	v_pk_add_f32 v[214:215], v[206:207], v[214:215]
	v_pk_mul_f32 v[216:217], v[214:215], s[92:93]
	v_pk_mul_f32 v[216:217], v[214:215], v[216:217]
	v_pk_fma_f32 v[216:217], v[214:215], v[216:217], v[214:215]
	v_pk_mul_f32 v[216:217], v[216:217], s[96:97]
	v_pk_mul_f32 v[216:217], v[216:217], s[28:29]
	v_exp_f32_e32 v216, v216
	v_exp_f32_e32 v217, v217
	s_nop 0
	v_add_f32_e32 v216, 1.0, v216
	v_add_f32_e32 v217, 1.0, v217
	v_rcp_f32_e32 v216, v216
	v_rcp_f32_e32 v217, v217
	s_nop 0
	v_pk_mul_f32 v[214:215], v[214:215], v[216:217]
	v_pk_mul_f32 v[214:215], v[110:111], v[214:215]
	v_cvt_pk_bf16_f32 v108, v214, v215
	v_mov_b32_dpp v210, v88 row_ror:1 row_mask:0xf bank_mask:0xf
	v_mov_b32_dpp v212, v88 row_ror:2 row_mask:0xf bank_mask:0xf
	v_mov_b32_dpp v211, v89 row_ror:1 row_mask:0xf bank_mask:0xf
	v_mov_b32_dpp v213, v89 row_ror:2 row_mask:0xf bank_mask:0xf
	s_nop 1
	v_mov_b32_dpp v210, v104 row_shr:1 row_mask:0xf bank_mask:0xf
	v_mov_b32_dpp v212, v104 row_shr:2 row_mask:0xf bank_mask:0xf
	v_mov_b32_dpp v211, v105 row_shr:1 row_mask:0xf bank_mask:0xf
	v_mov_b32_dpp v213, v105 row_shr:2 row_mask:0xf bank_mask:0xf
	s_nop 1
	v_pk_mul_f32 v[210:211], v[192:193], v[210:211]
	v_pk_fma_f32 v[214:215], v[200:201], v[104:105], v[210:211]
	v_pk_fma_f32 v[214:215], v[184:185], v[212:213], v[214:215]
	v_pk_add_f32 v[214:215], v[208:209], v[214:215]
	v_pk_mul_f32 v[216:217], v[214:215], s[92:93]
	v_pk_mul_f32 v[216:217], v[214:215], v[216:217]
	v_pk_fma_f32 v[216:217], v[214:215], v[216:217], v[214:215]
	v_pk_mul_f32 v[216:217], v[216:217], s[96:97]
	v_pk_mul_f32 v[216:217], v[216:217], s[28:29]
	v_exp_f32_e32 v216, v216
	v_exp_f32_e32 v217, v217
	s_nop 0
	v_add_f32_e32 v216, 1.0, v216
	v_add_f32_e32 v217, 1.0, v217
	v_rcp_f32_e32 v216, v216
	v_rcp_f32_e32 v217, v217
	s_nop 0
	v_pk_mul_f32 v[214:215], v[214:215], v[216:217]
	v_pk_mul_f32 v[214:215], v[112:113], v[214:215]
	v_cvt_pk_bf16_f32 v109, v214, v215
	s_add_i32 s26, s66, -96
	v_cmp_gt_i32_e64 s[24:25], s26, v227
	s_nop 1
	s_and_saveexec_b64 s[26:27], s[24:25]
	global_store_dwordx4 v242, v[106:109], s[6:7] offset:2048
	s_mov_b64 exec, s[26:27]
	s_nop 4
	v_mov_b32_dpp v210, v66 row_ror:1 row_mask:0xf bank_mask:0xf
	v_mov_b32_dpp v212, v66 row_ror:2 row_mask:0xf bank_mask:0xf
	v_mov_b32_dpp v211, v67 row_ror:1 row_mask:0xf bank_mask:0xf
	v_mov_b32_dpp v213, v67 row_ror:2 row_mask:0xf bank_mask:0xf
	s_nop 1
	v_mov_b32_dpp v210, v82 row_shr:1 row_mask:0xf bank_mask:0xf
	v_mov_b32_dpp v212, v82 row_shr:2 row_mask:0xf bank_mask:0xf
	v_mov_b32_dpp v211, v83 row_shr:1 row_mask:0xf bank_mask:0xf
	v_mov_b32_dpp v213, v83 row_shr:2 row_mask:0xf bank_mask:0xf
	s_nop 1
	v_pk_mul_f32 v[210:211], v[186:187], v[210:211]
	v_pk_fma_f32 v[214:215], v[194:195], v[82:83], v[210:211]
	v_pk_fma_f32 v[214:215], v[178:179], v[212:213], v[214:215]
	v_pk_add_f32 v[214:215], v[202:203], v[214:215]
	v_pk_mul_f32 v[216:217], v[214:215], s[92:93]
	v_pk_mul_f32 v[216:217], v[214:215], v[216:217]
	v_pk_fma_f32 v[216:217], v[214:215], v[216:217], v[214:215]
	v_pk_mul_f32 v[216:217], v[216:217], s[96:97]
	v_pk_mul_f32 v[216:217], v[216:217], s[28:29]
	v_exp_f32_e32 v216, v216
	v_exp_f32_e32 v217, v217
	s_nop 0
	v_add_f32_e32 v216, 1.0, v216
	v_add_f32_e32 v217, 1.0, v217
	v_rcp_f32_e32 v216, v216
	v_rcp_f32_e32 v217, v217
	s_nop 0
	v_pk_mul_f32 v[214:215], v[214:215], v[216:217]
	v_pk_mul_f32 v[214:215], v[90:91], v[214:215]
	v_cvt_pk_bf16_f32 v90, v214, v215
	v_mov_b32_dpp v210, v68 row_ror:1 row_mask:0xf bank_mask:0xf
	v_mov_b32_dpp v212, v68 row_ror:2 row_mask:0xf bank_mask:0xf
	v_mov_b32_dpp v211, v69 row_ror:1 row_mask:0xf bank_mask:0xf
	v_mov_b32_dpp v213, v69 row_ror:2 row_mask:0xf bank_mask:0xf
	s_nop 1
	v_mov_b32_dpp v210, v84 row_shr:1 row_mask:0xf bank_mask:0xf
	v_mov_b32_dpp v212, v84 row_shr:2 row_mask:0xf bank_mask:0xf
	v_mov_b32_dpp v211, v85 row_shr:1 row_mask:0xf bank_mask:0xf
	v_mov_b32_dpp v213, v85 row_shr:2 row_mask:0xf bank_mask:0xf
	s_nop 1
	v_pk_mul_f32 v[210:211], v[188:189], v[210:211]
	v_pk_fma_f32 v[214:215], v[196:197], v[84:85], v[210:211]
	v_pk_fma_f32 v[214:215], v[180:181], v[212:213], v[214:215]
	v_pk_add_f32 v[214:215], v[204:205], v[214:215]
	v_pk_mul_f32 v[216:217], v[214:215], s[92:93]
	v_pk_mul_f32 v[216:217], v[214:215], v[216:217]
	v_pk_fma_f32 v[216:217], v[214:215], v[216:217], v[214:215]
	v_pk_mul_f32 v[216:217], v[216:217], s[96:97]
	v_pk_mul_f32 v[216:217], v[216:217], s[28:29]
	v_exp_f32_e32 v216, v216
	v_exp_f32_e32 v217, v217
	s_nop 0
	v_add_f32_e32 v216, 1.0, v216
	v_add_f32_e32 v217, 1.0, v217
	v_rcp_f32_e32 v216, v216
	v_rcp_f32_e32 v217, v217
	s_nop 0
	v_pk_mul_f32 v[214:215], v[214:215], v[216:217]
	v_pk_mul_f32 v[214:215], v[92:93], v[214:215]
	v_cvt_pk_bf16_f32 v91, v214, v215
	v_mov_b32_dpp v210, v70 row_ror:1 row_mask:0xf bank_mask:0xf
	v_mov_b32_dpp v212, v70 row_ror:2 row_mask:0xf bank_mask:0xf
	v_mov_b32_dpp v211, v71 row_ror:1 row_mask:0xf bank_mask:0xf
	v_mov_b32_dpp v213, v71 row_ror:2 row_mask:0xf bank_mask:0xf
	s_nop 1
	v_mov_b32_dpp v210, v86 row_shr:1 row_mask:0xf bank_mask:0xf
	v_mov_b32_dpp v212, v86 row_shr:2 row_mask:0xf bank_mask:0xf
	v_mov_b32_dpp v211, v87 row_shr:1 row_mask:0xf bank_mask:0xf
	v_mov_b32_dpp v213, v87 row_shr:2 row_mask:0xf bank_mask:0xf
	s_nop 1
	v_pk_mul_f32 v[210:211], v[190:191], v[210:211]
	v_pk_fma_f32 v[214:215], v[198:199], v[86:87], v[210:211]
	v_pk_fma_f32 v[214:215], v[182:183], v[212:213], v[214:215]
	v_pk_add_f32 v[214:215], v[206:207], v[214:215]
	v_pk_mul_f32 v[216:217], v[214:215], s[92:93]
	v_pk_mul_f32 v[216:217], v[214:215], v[216:217]
	v_pk_fma_f32 v[216:217], v[214:215], v[216:217], v[214:215]
	v_pk_mul_f32 v[216:217], v[216:217], s[96:97]
	v_pk_mul_f32 v[216:217], v[216:217], s[28:29]
	v_exp_f32_e32 v216, v216
	v_exp_f32_e32 v217, v217
	s_nop 0
	v_add_f32_e32 v216, 1.0, v216
	v_add_f32_e32 v217, 1.0, v217
	v_rcp_f32_e32 v216, v216
	v_rcp_f32_e32 v217, v217
	s_nop 0
	v_pk_mul_f32 v[214:215], v[214:215], v[216:217]
	v_pk_mul_f32 v[214:215], v[94:95], v[214:215]
	v_cvt_pk_bf16_f32 v92, v214, v215
	v_mov_b32_dpp v210, v72 row_ror:1 row_mask:0xf bank_mask:0xf
	v_mov_b32_dpp v212, v72 row_ror:2 row_mask:0xf bank_mask:0xf
	v_mov_b32_dpp v211, v73 row_ror:1 row_mask:0xf bank_mask:0xf
	v_mov_b32_dpp v213, v73 row_ror:2 row_mask:0xf bank_mask:0xf
	s_nop 1
	v_mov_b32_dpp v210, v88 row_shr:1 row_mask:0xf bank_mask:0xf
	v_mov_b32_dpp v212, v88 row_shr:2 row_mask:0xf bank_mask:0xf
	v_mov_b32_dpp v211, v89 row_shr:1 row_mask:0xf bank_mask:0xf
	v_mov_b32_dpp v213, v89 row_shr:2 row_mask:0xf bank_mask:0xf
	s_nop 1
	v_pk_mul_f32 v[210:211], v[192:193], v[210:211]
	v_pk_fma_f32 v[214:215], v[200:201], v[88:89], v[210:211]
	v_pk_fma_f32 v[214:215], v[184:185], v[212:213], v[214:215]
	v_pk_add_f32 v[214:215], v[208:209], v[214:215]
	v_pk_mul_f32 v[216:217], v[214:215], s[92:93]
	v_pk_mul_f32 v[216:217], v[214:215], v[216:217]
	v_pk_fma_f32 v[216:217], v[214:215], v[216:217], v[214:215]
	v_pk_mul_f32 v[216:217], v[216:217], s[96:97]
	v_pk_mul_f32 v[216:217], v[216:217], s[28:29]
	v_exp_f32_e32 v216, v216
	v_exp_f32_e32 v217, v217
	s_nop 0
	v_add_f32_e32 v216, 1.0, v216
	v_add_f32_e32 v217, 1.0, v217
	v_rcp_f32_e32 v216, v216
	v_rcp_f32_e32 v217, v217
	s_nop 0
	v_pk_mul_f32 v[214:215], v[214:215], v[216:217]
	v_pk_mul_f32 v[214:215], v[96:97], v[214:215]
	v_cvt_pk_bf16_f32 v93, v214, v215
	s_add_i32 s26, s66, -80
	v_cmp_gt_i32_e64 s[24:25], s26, v227
	s_nop 1
	s_and_saveexec_b64 s[26:27], s[24:25]
	global_store_dwordx4 v242, v[90:93], s[6:7] offset:1024
	s_mov_b64 exec, s[26:27]
	s_nop 4
	v_mov_b32_dpp v210, v50 row_ror:1 row_mask:0xf bank_mask:0xf
	v_mov_b32_dpp v212, v50 row_ror:2 row_mask:0xf bank_mask:0xf
	v_mov_b32_dpp v211, v51 row_ror:1 row_mask:0xf bank_mask:0xf
	v_mov_b32_dpp v213, v51 row_ror:2 row_mask:0xf bank_mask:0xf
	s_nop 1
	v_mov_b32_dpp v210, v66 row_shr:1 row_mask:0xf bank_mask:0xf
	v_mov_b32_dpp v212, v66 row_shr:2 row_mask:0xf bank_mask:0xf
	v_mov_b32_dpp v211, v67 row_shr:1 row_mask:0xf bank_mask:0xf
	v_mov_b32_dpp v213, v67 row_shr:2 row_mask:0xf bank_mask:0xf
	s_nop 1
	v_pk_mul_f32 v[210:211], v[186:187], v[210:211]
	v_pk_fma_f32 v[214:215], v[194:195], v[66:67], v[210:211]
	v_pk_fma_f32 v[214:215], v[178:179], v[212:213], v[214:215]
	v_pk_add_f32 v[214:215], v[202:203], v[214:215]
	v_pk_mul_f32 v[216:217], v[214:215], s[92:93]
	v_pk_mul_f32 v[216:217], v[214:215], v[216:217]
	v_pk_fma_f32 v[216:217], v[214:215], v[216:217], v[214:215]
	v_pk_mul_f32 v[216:217], v[216:217], s[96:97]
	v_pk_mul_f32 v[216:217], v[216:217], s[28:29]
	v_exp_f32_e32 v216, v216
	v_exp_f32_e32 v217, v217
	s_nop 0
	v_add_f32_e32 v216, 1.0, v216
	v_add_f32_e32 v217, 1.0, v217
	v_rcp_f32_e32 v216, v216
	v_rcp_f32_e32 v217, v217
	s_nop 0
	v_pk_mul_f32 v[214:215], v[214:215], v[216:217]
	v_pk_mul_f32 v[214:215], v[74:75], v[214:215]
	v_cvt_pk_bf16_f32 v74, v214, v215
	v_mov_b32_dpp v210, v52 row_ror:1 row_mask:0xf bank_mask:0xf
	v_mov_b32_dpp v212, v52 row_ror:2 row_mask:0xf bank_mask:0xf
	v_mov_b32_dpp v211, v53 row_ror:1 row_mask:0xf bank_mask:0xf
	v_mov_b32_dpp v213, v53 row_ror:2 row_mask:0xf bank_mask:0xf
	s_nop 1
	v_mov_b32_dpp v210, v68 row_shr:1 row_mask:0xf bank_mask:0xf
	v_mov_b32_dpp v212, v68 row_shr:2 row_mask:0xf bank_mask:0xf
	v_mov_b32_dpp v211, v69 row_shr:1 row_mask:0xf bank_mask:0xf
	v_mov_b32_dpp v213, v69 row_shr:2 row_mask:0xf bank_mask:0xf
	s_nop 1
	v_pk_mul_f32 v[210:211], v[188:189], v[210:211]
	v_pk_fma_f32 v[214:215], v[196:197], v[68:69], v[210:211]
	v_pk_fma_f32 v[214:215], v[180:181], v[212:213], v[214:215]
	v_pk_add_f32 v[214:215], v[204:205], v[214:215]
	v_pk_mul_f32 v[216:217], v[214:215], s[92:93]
	v_pk_mul_f32 v[216:217], v[214:215], v[216:217]
	v_pk_fma_f32 v[216:217], v[214:215], v[216:217], v[214:215]
	v_pk_mul_f32 v[216:217], v[216:217], s[96:97]
	v_pk_mul_f32 v[216:217], v[216:217], s[28:29]
	v_exp_f32_e32 v216, v216
	v_exp_f32_e32 v217, v217
	s_nop 0
	v_add_f32_e32 v216, 1.0, v216
	v_add_f32_e32 v217, 1.0, v217
	v_rcp_f32_e32 v216, v216
	v_rcp_f32_e32 v217, v217
	s_nop 0
	v_pk_mul_f32 v[214:215], v[214:215], v[216:217]
	v_pk_mul_f32 v[214:215], v[76:77], v[214:215]
	v_cvt_pk_bf16_f32 v75, v214, v215
	v_mov_b32_dpp v210, v54 row_ror:1 row_mask:0xf bank_mask:0xf
	v_mov_b32_dpp v212, v54 row_ror:2 row_mask:0xf bank_mask:0xf
	v_mov_b32_dpp v211, v55 row_ror:1 row_mask:0xf bank_mask:0xf
	v_mov_b32_dpp v213, v55 row_ror:2 row_mask:0xf bank_mask:0xf
	s_nop 1
	v_mov_b32_dpp v210, v70 row_shr:1 row_mask:0xf bank_mask:0xf
	v_mov_b32_dpp v212, v70 row_shr:2 row_mask:0xf bank_mask:0xf
	v_mov_b32_dpp v211, v71 row_shr:1 row_mask:0xf bank_mask:0xf
	v_mov_b32_dpp v213, v71 row_shr:2 row_mask:0xf bank_mask:0xf
	s_nop 1
	v_pk_mul_f32 v[210:211], v[190:191], v[210:211]
	v_pk_fma_f32 v[214:215], v[198:199], v[70:71], v[210:211]
	v_pk_fma_f32 v[214:215], v[182:183], v[212:213], v[214:215]
	v_pk_add_f32 v[214:215], v[206:207], v[214:215]
	v_pk_mul_f32 v[216:217], v[214:215], s[92:93]
	v_pk_mul_f32 v[216:217], v[214:215], v[216:217]
	v_pk_fma_f32 v[216:217], v[214:215], v[216:217], v[214:215]
	v_pk_mul_f32 v[216:217], v[216:217], s[96:97]
	v_pk_mul_f32 v[216:217], v[216:217], s[28:29]
	v_exp_f32_e32 v216, v216
	v_exp_f32_e32 v217, v217
	s_nop 0
	v_add_f32_e32 v216, 1.0, v216
	v_add_f32_e32 v217, 1.0, v217
	v_rcp_f32_e32 v216, v216
	v_rcp_f32_e32 v217, v217
	s_nop 0
	v_pk_mul_f32 v[214:215], v[214:215], v[216:217]
	v_pk_mul_f32 v[214:215], v[78:79], v[214:215]
	v_cvt_pk_bf16_f32 v76, v214, v215
	v_mov_b32_dpp v210, v56 row_ror:1 row_mask:0xf bank_mask:0xf
	v_mov_b32_dpp v212, v56 row_ror:2 row_mask:0xf bank_mask:0xf
	v_mov_b32_dpp v211, v57 row_ror:1 row_mask:0xf bank_mask:0xf
	v_mov_b32_dpp v213, v57 row_ror:2 row_mask:0xf bank_mask:0xf
	s_nop 1
	v_mov_b32_dpp v210, v72 row_shr:1 row_mask:0xf bank_mask:0xf
	v_mov_b32_dpp v212, v72 row_shr:2 row_mask:0xf bank_mask:0xf
	v_mov_b32_dpp v211, v73 row_shr:1 row_mask:0xf bank_mask:0xf
	v_mov_b32_dpp v213, v73 row_shr:2 row_mask:0xf bank_mask:0xf
	s_nop 1
	v_pk_mul_f32 v[210:211], v[192:193], v[210:211]
	v_pk_fma_f32 v[214:215], v[200:201], v[72:73], v[210:211]
	v_pk_fma_f32 v[214:215], v[184:185], v[212:213], v[214:215]
	v_pk_add_f32 v[214:215], v[208:209], v[214:215]
	v_pk_mul_f32 v[216:217], v[214:215], s[92:93]
	v_pk_mul_f32 v[216:217], v[214:215], v[216:217]
	v_pk_fma_f32 v[216:217], v[214:215], v[216:217], v[214:215]
	v_pk_mul_f32 v[216:217], v[216:217], s[96:97]
	v_pk_mul_f32 v[216:217], v[216:217], s[28:29]
	v_exp_f32_e32 v216, v216
	v_exp_f32_e32 v217, v217
	s_nop 0
	v_add_f32_e32 v216, 1.0, v216
	v_add_f32_e32 v217, 1.0, v217
	v_rcp_f32_e32 v216, v216
	v_rcp_f32_e32 v217, v217
	s_nop 0
	v_pk_mul_f32 v[214:215], v[214:215], v[216:217]
	v_pk_mul_f32 v[214:215], v[80:81], v[214:215]
	v_cvt_pk_bf16_f32 v77, v214, v215
	s_add_i32 s26, s66, -64
	v_cmp_gt_i32_e64 s[24:25], s26, v227
	s_nop 1
	s_and_saveexec_b64 s[26:27], s[24:25]
	global_store_dwordx4 v242, v[74:77], s[6:7]
	s_mov_b64 exec, s[26:27]
	s_nop 4
	v_mov_b32_dpp v210, v34 row_ror:1 row_mask:0xf bank_mask:0xf
	v_mov_b32_dpp v212, v34 row_ror:2 row_mask:0xf bank_mask:0xf
	v_mov_b32_dpp v211, v35 row_ror:1 row_mask:0xf bank_mask:0xf
	v_mov_b32_dpp v213, v35 row_ror:2 row_mask:0xf bank_mask:0xf
	s_nop 1
	v_mov_b32_dpp v210, v50 row_shr:1 row_mask:0xf bank_mask:0xf
	v_mov_b32_dpp v212, v50 row_shr:2 row_mask:0xf bank_mask:0xf
	v_mov_b32_dpp v211, v51 row_shr:1 row_mask:0xf bank_mask:0xf
	v_mov_b32_dpp v213, v51 row_shr:2 row_mask:0xf bank_mask:0xf
	s_nop 1
	v_pk_mul_f32 v[210:211], v[186:187], v[210:211]
	v_pk_fma_f32 v[214:215], v[194:195], v[50:51], v[210:211]
	v_pk_fma_f32 v[214:215], v[178:179], v[212:213], v[214:215]
	v_pk_add_f32 v[214:215], v[202:203], v[214:215]
	v_pk_mul_f32 v[216:217], v[214:215], s[92:93]
	v_pk_mul_f32 v[216:217], v[214:215], v[216:217]
	v_pk_fma_f32 v[216:217], v[214:215], v[216:217], v[214:215]
	v_pk_mul_f32 v[216:217], v[216:217], s[96:97]
	v_pk_mul_f32 v[216:217], v[216:217], s[28:29]
	v_exp_f32_e32 v216, v216
	v_exp_f32_e32 v217, v217
	s_nop 0
	v_add_f32_e32 v216, 1.0, v216
	v_add_f32_e32 v217, 1.0, v217
	v_rcp_f32_e32 v216, v216
	v_rcp_f32_e32 v217, v217
	s_nop 0
	v_pk_mul_f32 v[214:215], v[214:215], v[216:217]
	v_pk_mul_f32 v[214:215], v[58:59], v[214:215]
	v_cvt_pk_bf16_f32 v58, v214, v215
	v_mov_b32_dpp v210, v36 row_ror:1 row_mask:0xf bank_mask:0xf
	v_mov_b32_dpp v212, v36 row_ror:2 row_mask:0xf bank_mask:0xf
	v_mov_b32_dpp v211, v37 row_ror:1 row_mask:0xf bank_mask:0xf
	v_mov_b32_dpp v213, v37 row_ror:2 row_mask:0xf bank_mask:0xf
	s_nop 1
	v_mov_b32_dpp v210, v52 row_shr:1 row_mask:0xf bank_mask:0xf
	v_mov_b32_dpp v212, v52 row_shr:2 row_mask:0xf bank_mask:0xf
	v_mov_b32_dpp v211, v53 row_shr:1 row_mask:0xf bank_mask:0xf
	v_mov_b32_dpp v213, v53 row_shr:2 row_mask:0xf bank_mask:0xf
	s_nop 1
	v_pk_mul_f32 v[210:211], v[188:189], v[210:211]
	v_pk_fma_f32 v[214:215], v[196:197], v[52:53], v[210:211]
	v_pk_fma_f32 v[214:215], v[180:181], v[212:213], v[214:215]
	v_pk_add_f32 v[214:215], v[204:205], v[214:215]
	v_pk_mul_f32 v[216:217], v[214:215], s[92:93]
	v_pk_mul_f32 v[216:217], v[214:215], v[216:217]
	v_pk_fma_f32 v[216:217], v[214:215], v[216:217], v[214:215]
	v_pk_mul_f32 v[216:217], v[216:217], s[96:97]
	v_pk_mul_f32 v[216:217], v[216:217], s[28:29]
	v_exp_f32_e32 v216, v216
	v_exp_f32_e32 v217, v217
	s_nop 0
	v_add_f32_e32 v216, 1.0, v216
	v_add_f32_e32 v217, 1.0, v217
	v_rcp_f32_e32 v216, v216
	v_rcp_f32_e32 v217, v217
	s_nop 0
	v_pk_mul_f32 v[214:215], v[214:215], v[216:217]
	v_pk_mul_f32 v[214:215], v[60:61], v[214:215]
	v_cvt_pk_bf16_f32 v59, v214, v215
	v_mov_b32_dpp v210, v38 row_ror:1 row_mask:0xf bank_mask:0xf
	v_mov_b32_dpp v212, v38 row_ror:2 row_mask:0xf bank_mask:0xf
	v_mov_b32_dpp v211, v39 row_ror:1 row_mask:0xf bank_mask:0xf
	v_mov_b32_dpp v213, v39 row_ror:2 row_mask:0xf bank_mask:0xf
	s_nop 1
	v_mov_b32_dpp v210, v54 row_shr:1 row_mask:0xf bank_mask:0xf
	v_mov_b32_dpp v212, v54 row_shr:2 row_mask:0xf bank_mask:0xf
	v_mov_b32_dpp v211, v55 row_shr:1 row_mask:0xf bank_mask:0xf
	v_mov_b32_dpp v213, v55 row_shr:2 row_mask:0xf bank_mask:0xf
	s_nop 1
	v_pk_mul_f32 v[210:211], v[190:191], v[210:211]
	v_pk_fma_f32 v[214:215], v[198:199], v[54:55], v[210:211]
	v_pk_fma_f32 v[214:215], v[182:183], v[212:213], v[214:215]
	v_pk_add_f32 v[214:215], v[206:207], v[214:215]
	v_pk_mul_f32 v[216:217], v[214:215], s[92:93]
	v_pk_mul_f32 v[216:217], v[214:215], v[216:217]
	v_pk_fma_f32 v[216:217], v[214:215], v[216:217], v[214:215]
	v_pk_mul_f32 v[216:217], v[216:217], s[96:97]
	v_pk_mul_f32 v[216:217], v[216:217], s[28:29]
	v_exp_f32_e32 v216, v216
	v_exp_f32_e32 v217, v217
	s_nop 0
	v_add_f32_e32 v216, 1.0, v216
	v_add_f32_e32 v217, 1.0, v217
	v_rcp_f32_e32 v216, v216
	v_rcp_f32_e32 v217, v217
	s_nop 0
	v_pk_mul_f32 v[214:215], v[214:215], v[216:217]
	v_pk_mul_f32 v[214:215], v[62:63], v[214:215]
	v_cvt_pk_bf16_f32 v60, v214, v215
	v_mov_b32_dpp v210, v40 row_ror:1 row_mask:0xf bank_mask:0xf
	v_mov_b32_dpp v212, v40 row_ror:2 row_mask:0xf bank_mask:0xf
	v_mov_b32_dpp v211, v41 row_ror:1 row_mask:0xf bank_mask:0xf
	v_mov_b32_dpp v213, v41 row_ror:2 row_mask:0xf bank_mask:0xf
	s_nop 1
	v_mov_b32_dpp v210, v56 row_shr:1 row_mask:0xf bank_mask:0xf
	v_mov_b32_dpp v212, v56 row_shr:2 row_mask:0xf bank_mask:0xf
	v_mov_b32_dpp v211, v57 row_shr:1 row_mask:0xf bank_mask:0xf
	v_mov_b32_dpp v213, v57 row_shr:2 row_mask:0xf bank_mask:0xf
	s_nop 1
	v_pk_mul_f32 v[210:211], v[192:193], v[210:211]
	v_pk_fma_f32 v[214:215], v[200:201], v[56:57], v[210:211]
	v_pk_fma_f32 v[214:215], v[184:185], v[212:213], v[214:215]
	v_pk_add_f32 v[214:215], v[208:209], v[214:215]
	v_pk_mul_f32 v[216:217], v[214:215], s[92:93]
	v_pk_mul_f32 v[216:217], v[214:215], v[216:217]
	v_pk_fma_f32 v[216:217], v[214:215], v[216:217], v[214:215]
	v_pk_mul_f32 v[216:217], v[216:217], s[96:97]
	v_pk_mul_f32 v[216:217], v[216:217], s[28:29]
	v_exp_f32_e32 v216, v216
	v_exp_f32_e32 v217, v217
	s_nop 0
	v_add_f32_e32 v216, 1.0, v216
	v_add_f32_e32 v217, 1.0, v217
	v_rcp_f32_e32 v216, v216
	v_rcp_f32_e32 v217, v217
	s_nop 0
	v_pk_mul_f32 v[214:215], v[214:215], v[216:217]
	v_pk_mul_f32 v[214:215], v[64:65], v[214:215]
	v_cvt_pk_bf16_f32 v61, v214, v215
	s_add_i32 s26, s66, -48
	v_cmp_gt_i32_e64 s[24:25], s26, v227
	s_nop 1
	s_and_saveexec_b64 s[26:27], s[24:25]
	global_store_dwordx4 v242, v[58:61], s[18:19] offset:3072
	s_mov_b64 exec, s[26:27]
	s_nop 4
	v_mov_b32_dpp v210, v18 row_ror:1 row_mask:0xf bank_mask:0xf
	v_mov_b32_dpp v212, v18 row_ror:2 row_mask:0xf bank_mask:0xf
	v_mov_b32_dpp v211, v19 row_ror:1 row_mask:0xf bank_mask:0xf
	v_mov_b32_dpp v213, v19 row_ror:2 row_mask:0xf bank_mask:0xf
	s_nop 1
	v_mov_b32_dpp v210, v34 row_shr:1 row_mask:0xf bank_mask:0xf
	v_mov_b32_dpp v212, v34 row_shr:2 row_mask:0xf bank_mask:0xf
	v_mov_b32_dpp v211, v35 row_shr:1 row_mask:0xf bank_mask:0xf
	v_mov_b32_dpp v213, v35 row_shr:2 row_mask:0xf bank_mask:0xf
	s_nop 1
	v_pk_mul_f32 v[210:211], v[186:187], v[210:211]
	v_pk_fma_f32 v[214:215], v[194:195], v[34:35], v[210:211]
	v_pk_fma_f32 v[214:215], v[178:179], v[212:213], v[214:215]
	v_pk_add_f32 v[214:215], v[202:203], v[214:215]
	v_pk_mul_f32 v[216:217], v[214:215], s[92:93]
	v_pk_mul_f32 v[216:217], v[214:215], v[216:217]
	v_pk_fma_f32 v[216:217], v[214:215], v[216:217], v[214:215]
	v_pk_mul_f32 v[216:217], v[216:217], s[96:97]
	v_pk_mul_f32 v[216:217], v[216:217], s[28:29]
	v_exp_f32_e32 v216, v216
	v_exp_f32_e32 v217, v217
	s_nop 0
	v_add_f32_e32 v216, 1.0, v216
	v_add_f32_e32 v217, 1.0, v217
	v_rcp_f32_e32 v216, v216
	v_rcp_f32_e32 v217, v217
	s_nop 0
	v_pk_mul_f32 v[214:215], v[214:215], v[216:217]
	v_pk_mul_f32 v[214:215], v[42:43], v[214:215]
	v_cvt_pk_bf16_f32 v42, v214, v215
	v_mov_b32_dpp v210, v20 row_ror:1 row_mask:0xf bank_mask:0xf
	v_mov_b32_dpp v212, v20 row_ror:2 row_mask:0xf bank_mask:0xf
	v_mov_b32_dpp v211, v21 row_ror:1 row_mask:0xf bank_mask:0xf
	v_mov_b32_dpp v213, v21 row_ror:2 row_mask:0xf bank_mask:0xf
	s_nop 1
	v_mov_b32_dpp v210, v36 row_shr:1 row_mask:0xf bank_mask:0xf
	v_mov_b32_dpp v212, v36 row_shr:2 row_mask:0xf bank_mask:0xf
	v_mov_b32_dpp v211, v37 row_shr:1 row_mask:0xf bank_mask:0xf
	v_mov_b32_dpp v213, v37 row_shr:2 row_mask:0xf bank_mask:0xf
	s_nop 1
	v_pk_mul_f32 v[210:211], v[188:189], v[210:211]
	v_pk_fma_f32 v[214:215], v[196:197], v[36:37], v[210:211]
	v_pk_fma_f32 v[214:215], v[180:181], v[212:213], v[214:215]
	v_pk_add_f32 v[214:215], v[204:205], v[214:215]
	v_pk_mul_f32 v[216:217], v[214:215], s[92:93]
	v_pk_mul_f32 v[216:217], v[214:215], v[216:217]
	v_pk_fma_f32 v[216:217], v[214:215], v[216:217], v[214:215]
	v_pk_mul_f32 v[216:217], v[216:217], s[96:97]
	v_pk_mul_f32 v[216:217], v[216:217], s[28:29]
	v_exp_f32_e32 v216, v216
	v_exp_f32_e32 v217, v217
	s_nop 0
	v_add_f32_e32 v216, 1.0, v216
	v_add_f32_e32 v217, 1.0, v217
	v_rcp_f32_e32 v216, v216
	v_rcp_f32_e32 v217, v217
	s_nop 0
	v_pk_mul_f32 v[214:215], v[214:215], v[216:217]
	v_pk_mul_f32 v[214:215], v[44:45], v[214:215]
	v_cvt_pk_bf16_f32 v43, v214, v215
	v_mov_b32_dpp v210, v22 row_ror:1 row_mask:0xf bank_mask:0xf
	v_mov_b32_dpp v212, v22 row_ror:2 row_mask:0xf bank_mask:0xf
	v_mov_b32_dpp v211, v23 row_ror:1 row_mask:0xf bank_mask:0xf
	v_mov_b32_dpp v213, v23 row_ror:2 row_mask:0xf bank_mask:0xf
	s_nop 1
	v_mov_b32_dpp v210, v38 row_shr:1 row_mask:0xf bank_mask:0xf
	v_mov_b32_dpp v212, v38 row_shr:2 row_mask:0xf bank_mask:0xf
	v_mov_b32_dpp v211, v39 row_shr:1 row_mask:0xf bank_mask:0xf
	v_mov_b32_dpp v213, v39 row_shr:2 row_mask:0xf bank_mask:0xf
	s_nop 1
	v_pk_mul_f32 v[210:211], v[190:191], v[210:211]
	v_pk_fma_f32 v[214:215], v[198:199], v[38:39], v[210:211]
	v_pk_fma_f32 v[214:215], v[182:183], v[212:213], v[214:215]
	v_pk_add_f32 v[214:215], v[206:207], v[214:215]
	v_pk_mul_f32 v[216:217], v[214:215], s[92:93]
	v_pk_mul_f32 v[216:217], v[214:215], v[216:217]
	v_pk_fma_f32 v[216:217], v[214:215], v[216:217], v[214:215]
	v_pk_mul_f32 v[216:217], v[216:217], s[96:97]
	v_pk_mul_f32 v[216:217], v[216:217], s[28:29]
	v_exp_f32_e32 v216, v216
	v_exp_f32_e32 v217, v217
	s_nop 0
	v_add_f32_e32 v216, 1.0, v216
	v_add_f32_e32 v217, 1.0, v217
	v_rcp_f32_e32 v216, v216
	v_rcp_f32_e32 v217, v217
	s_nop 0
	v_pk_mul_f32 v[214:215], v[214:215], v[216:217]
	v_pk_mul_f32 v[214:215], v[46:47], v[214:215]
	v_cvt_pk_bf16_f32 v44, v214, v215
	v_mov_b32_dpp v210, v24 row_ror:1 row_mask:0xf bank_mask:0xf
	v_mov_b32_dpp v212, v24 row_ror:2 row_mask:0xf bank_mask:0xf
	v_mov_b32_dpp v211, v25 row_ror:1 row_mask:0xf bank_mask:0xf
	v_mov_b32_dpp v213, v25 row_ror:2 row_mask:0xf bank_mask:0xf
	s_nop 1
	v_mov_b32_dpp v210, v40 row_shr:1 row_mask:0xf bank_mask:0xf
	v_mov_b32_dpp v212, v40 row_shr:2 row_mask:0xf bank_mask:0xf
	v_mov_b32_dpp v211, v41 row_shr:1 row_mask:0xf bank_mask:0xf
	v_mov_b32_dpp v213, v41 row_shr:2 row_mask:0xf bank_mask:0xf
	s_nop 1
	v_pk_mul_f32 v[210:211], v[192:193], v[210:211]
	v_pk_fma_f32 v[214:215], v[200:201], v[40:41], v[210:211]
	v_pk_fma_f32 v[214:215], v[184:185], v[212:213], v[214:215]
	v_pk_add_f32 v[214:215], v[208:209], v[214:215]
	v_pk_mul_f32 v[216:217], v[214:215], s[92:93]
	v_pk_mul_f32 v[216:217], v[214:215], v[216:217]
	v_pk_fma_f32 v[216:217], v[214:215], v[216:217], v[214:215]
	v_pk_mul_f32 v[216:217], v[216:217], s[96:97]
	v_pk_mul_f32 v[216:217], v[216:217], s[28:29]
	v_exp_f32_e32 v216, v216
	v_exp_f32_e32 v217, v217
	s_nop 0
	v_add_f32_e32 v216, 1.0, v216
	v_add_f32_e32 v217, 1.0, v217
	v_rcp_f32_e32 v216, v216
	v_rcp_f32_e32 v217, v217
	s_nop 0
	v_pk_mul_f32 v[214:215], v[214:215], v[216:217]
	v_pk_mul_f32 v[214:215], v[48:49], v[214:215]
	v_cvt_pk_bf16_f32 v45, v214, v215
	s_add_i32 s26, s66, -32
	v_cmp_gt_i32_e64 s[24:25], s26, v227
	s_nop 1
	s_and_saveexec_b64 s[26:27], s[24:25]
	global_store_dwordx4 v242, v[42:45], s[18:19] offset:2048
	s_mov_b64 exec, s[26:27]
	s_nop 4
	v_mov_b32_dpp v210, v2 row_ror:1 row_mask:0xf bank_mask:0xf
	v_mov_b32_dpp v212, v2 row_ror:2 row_mask:0xf bank_mask:0xf
	v_mov_b32_dpp v211, v3 row_ror:1 row_mask:0xf bank_mask:0xf
	v_mov_b32_dpp v213, v3 row_ror:2 row_mask:0xf bank_mask:0xf
	s_nop 1
	v_mov_b32_dpp v210, v18 row_shr:1 row_mask:0xf bank_mask:0xf
	v_mov_b32_dpp v212, v18 row_shr:2 row_mask:0xf bank_mask:0xf
	v_mov_b32_dpp v211, v19 row_shr:1 row_mask:0xf bank_mask:0xf
	v_mov_b32_dpp v213, v19 row_shr:2 row_mask:0xf bank_mask:0xf
	s_nop 1
	v_pk_mul_f32 v[210:211], v[186:187], v[210:211]
	v_pk_fma_f32 v[214:215], v[194:195], v[18:19], v[210:211]
	v_pk_fma_f32 v[214:215], v[178:179], v[212:213], v[214:215]
	v_pk_add_f32 v[214:215], v[202:203], v[214:215]
	v_pk_mul_f32 v[216:217], v[214:215], s[92:93]
	v_pk_mul_f32 v[216:217], v[214:215], v[216:217]
	v_pk_fma_f32 v[216:217], v[214:215], v[216:217], v[214:215]
	v_pk_mul_f32 v[216:217], v[216:217], s[96:97]
	v_pk_mul_f32 v[216:217], v[216:217], s[28:29]
	v_exp_f32_e32 v216, v216
	v_exp_f32_e32 v217, v217
	s_nop 0
	v_add_f32_e32 v216, 1.0, v216
	v_add_f32_e32 v217, 1.0, v217
	v_rcp_f32_e32 v216, v216
	v_rcp_f32_e32 v217, v217
	s_nop 0
	v_pk_mul_f32 v[214:215], v[214:215], v[216:217]
	v_pk_mul_f32 v[214:215], v[26:27], v[214:215]
	v_cvt_pk_bf16_f32 v26, v214, v215
	v_mov_b32_dpp v210, v4 row_ror:1 row_mask:0xf bank_mask:0xf
	v_mov_b32_dpp v212, v4 row_ror:2 row_mask:0xf bank_mask:0xf
	v_mov_b32_dpp v211, v5 row_ror:1 row_mask:0xf bank_mask:0xf
	v_mov_b32_dpp v213, v5 row_ror:2 row_mask:0xf bank_mask:0xf
	s_nop 1
	v_mov_b32_dpp v210, v20 row_shr:1 row_mask:0xf bank_mask:0xf
	v_mov_b32_dpp v212, v20 row_shr:2 row_mask:0xf bank_mask:0xf
	v_mov_b32_dpp v211, v21 row_shr:1 row_mask:0xf bank_mask:0xf
	v_mov_b32_dpp v213, v21 row_shr:2 row_mask:0xf bank_mask:0xf
	s_nop 1
	v_pk_mul_f32 v[210:211], v[188:189], v[210:211]
	v_pk_fma_f32 v[214:215], v[196:197], v[20:21], v[210:211]
	v_pk_fma_f32 v[214:215], v[180:181], v[212:213], v[214:215]
	v_pk_add_f32 v[214:215], v[204:205], v[214:215]
	v_pk_mul_f32 v[216:217], v[214:215], s[92:93]
	v_pk_mul_f32 v[216:217], v[214:215], v[216:217]
	v_pk_fma_f32 v[216:217], v[214:215], v[216:217], v[214:215]
	v_pk_mul_f32 v[216:217], v[216:217], s[96:97]
	v_pk_mul_f32 v[216:217], v[216:217], s[28:29]
	v_exp_f32_e32 v216, v216
	v_exp_f32_e32 v217, v217
	s_nop 0
	v_add_f32_e32 v216, 1.0, v216
	v_add_f32_e32 v217, 1.0, v217
	v_rcp_f32_e32 v216, v216
	v_rcp_f32_e32 v217, v217
	s_nop 0
	v_pk_mul_f32 v[214:215], v[214:215], v[216:217]
	v_pk_mul_f32 v[214:215], v[28:29], v[214:215]
	v_cvt_pk_bf16_f32 v27, v214, v215
	v_mov_b32_dpp v210, v6 row_ror:1 row_mask:0xf bank_mask:0xf
	v_mov_b32_dpp v212, v6 row_ror:2 row_mask:0xf bank_mask:0xf
	v_mov_b32_dpp v211, v7 row_ror:1 row_mask:0xf bank_mask:0xf
	v_mov_b32_dpp v213, v7 row_ror:2 row_mask:0xf bank_mask:0xf
	s_nop 1
	v_mov_b32_dpp v210, v22 row_shr:1 row_mask:0xf bank_mask:0xf
	v_mov_b32_dpp v212, v22 row_shr:2 row_mask:0xf bank_mask:0xf
	v_mov_b32_dpp v211, v23 row_shr:1 row_mask:0xf bank_mask:0xf
	v_mov_b32_dpp v213, v23 row_shr:2 row_mask:0xf bank_mask:0xf
	s_nop 1
	v_pk_mul_f32 v[210:211], v[190:191], v[210:211]
	v_pk_fma_f32 v[214:215], v[198:199], v[22:23], v[210:211]
	v_pk_fma_f32 v[214:215], v[182:183], v[212:213], v[214:215]
	v_pk_add_f32 v[214:215], v[206:207], v[214:215]
	v_pk_mul_f32 v[216:217], v[214:215], s[92:93]
	v_pk_mul_f32 v[216:217], v[214:215], v[216:217]
	v_pk_fma_f32 v[216:217], v[214:215], v[216:217], v[214:215]
	v_pk_mul_f32 v[216:217], v[216:217], s[96:97]
	v_pk_mul_f32 v[216:217], v[216:217], s[28:29]
	v_exp_f32_e32 v216, v216
	v_exp_f32_e32 v217, v217
	s_nop 0
	v_add_f32_e32 v216, 1.0, v216
	v_add_f32_e32 v217, 1.0, v217
	v_rcp_f32_e32 v216, v216
	v_rcp_f32_e32 v217, v217
	s_nop 0
	v_pk_mul_f32 v[214:215], v[214:215], v[216:217]
	v_pk_mul_f32 v[214:215], v[30:31], v[214:215]
	v_cvt_pk_bf16_f32 v28, v214, v215
	v_mov_b32_dpp v210, v8 row_ror:1 row_mask:0xf bank_mask:0xf
	v_mov_b32_dpp v212, v8 row_ror:2 row_mask:0xf bank_mask:0xf
	v_mov_b32_dpp v211, v9 row_ror:1 row_mask:0xf bank_mask:0xf
	v_mov_b32_dpp v213, v9 row_ror:2 row_mask:0xf bank_mask:0xf
	s_nop 1
	v_mov_b32_dpp v210, v24 row_shr:1 row_mask:0xf bank_mask:0xf
	v_mov_b32_dpp v212, v24 row_shr:2 row_mask:0xf bank_mask:0xf
	v_mov_b32_dpp v211, v25 row_shr:1 row_mask:0xf bank_mask:0xf
	v_mov_b32_dpp v213, v25 row_shr:2 row_mask:0xf bank_mask:0xf
	s_nop 1
	v_pk_mul_f32 v[210:211], v[192:193], v[210:211]
	v_pk_fma_f32 v[214:215], v[200:201], v[24:25], v[210:211]
	v_pk_fma_f32 v[214:215], v[184:185], v[212:213], v[214:215]
	v_pk_add_f32 v[214:215], v[208:209], v[214:215]
	v_pk_mul_f32 v[216:217], v[214:215], s[92:93]
	v_pk_mul_f32 v[216:217], v[214:215], v[216:217]
	v_pk_fma_f32 v[216:217], v[214:215], v[216:217], v[214:215]
	v_pk_mul_f32 v[216:217], v[216:217], s[96:97]
	v_pk_mul_f32 v[216:217], v[216:217], s[28:29]
	v_exp_f32_e32 v216, v216
	v_exp_f32_e32 v217, v217
	s_nop 0
	v_add_f32_e32 v216, 1.0, v216
	v_add_f32_e32 v217, 1.0, v217
	v_rcp_f32_e32 v216, v216
	v_rcp_f32_e32 v217, v217
	s_nop 0
	v_pk_mul_f32 v[214:215], v[214:215], v[216:217]
	v_pk_mul_f32 v[214:215], v[32:33], v[214:215]
	v_cvt_pk_bf16_f32 v29, v214, v215
	s_add_i32 s26, s66, -16
	v_cmp_gt_i32_e64 s[24:25], s26, v227
	s_nop 1
	s_and_saveexec_b64 s[26:27], s[24:25]
	global_store_dwordx4 v242, v[26:29], s[18:19] offset:1024
	s_mov_b64 exec, s[26:27]
	s_nop 4
	v_mov_b32_dpp v210, v218 row_ror:1 row_mask:0xf bank_mask:0xf
	v_mov_b32_dpp v212, v218 row_ror:2 row_mask:0xf bank_mask:0xf
	v_mov_b32_dpp v211, v219 row_ror:1 row_mask:0xf bank_mask:0xf
	v_mov_b32_dpp v213, v219 row_ror:2 row_mask:0xf bank_mask:0xf
	s_nop 1
	v_mov_b32_dpp v210, v2 row_shr:1 row_mask:0xf bank_mask:0xf
	v_mov_b32_dpp v212, v2 row_shr:2 row_mask:0xf bank_mask:0xf
	v_mov_b32_dpp v211, v3 row_shr:1 row_mask:0xf bank_mask:0xf
	v_mov_b32_dpp v213, v3 row_shr:2 row_mask:0xf bank_mask:0xf
	s_nop 1
	v_pk_mul_f32 v[210:211], v[186:187], v[210:211]
	v_pk_fma_f32 v[214:215], v[194:195], v[2:3], v[210:211]
	v_pk_fma_f32 v[214:215], v[178:179], v[212:213], v[214:215]
	v_pk_add_f32 v[214:215], v[202:203], v[214:215]
	v_pk_mul_f32 v[216:217], v[214:215], s[92:93]
	v_pk_mul_f32 v[216:217], v[214:215], v[216:217]
	v_pk_fma_f32 v[216:217], v[214:215], v[216:217], v[214:215]
	v_pk_mul_f32 v[216:217], v[216:217], s[96:97]
	v_pk_mul_f32 v[216:217], v[216:217], s[28:29]
	v_exp_f32_e32 v216, v216
	v_exp_f32_e32 v217, v217
	s_nop 0
	v_add_f32_e32 v216, 1.0, v216
	v_add_f32_e32 v217, 1.0, v217
	v_rcp_f32_e32 v216, v216
	v_rcp_f32_e32 v217, v217
	s_nop 0
	v_pk_mul_f32 v[214:215], v[214:215], v[216:217]
	v_pk_mul_f32 v[214:215], v[10:11], v[214:215]
	v_cvt_pk_bf16_f32 v10, v214, v215
	v_mov_b32_dpp v210, v220 row_ror:1 row_mask:0xf bank_mask:0xf
	v_mov_b32_dpp v212, v220 row_ror:2 row_mask:0xf bank_mask:0xf
	v_mov_b32_dpp v211, v221 row_ror:1 row_mask:0xf bank_mask:0xf
	v_mov_b32_dpp v213, v221 row_ror:2 row_mask:0xf bank_mask:0xf
	s_nop 1
	v_mov_b32_dpp v210, v4 row_shr:1 row_mask:0xf bank_mask:0xf
	v_mov_b32_dpp v212, v4 row_shr:2 row_mask:0xf bank_mask:0xf
	v_mov_b32_dpp v211, v5 row_shr:1 row_mask:0xf bank_mask:0xf
	v_mov_b32_dpp v213, v5 row_shr:2 row_mask:0xf bank_mask:0xf
	s_nop 1
	v_pk_mul_f32 v[210:211], v[188:189], v[210:211]
	v_pk_fma_f32 v[214:215], v[196:197], v[4:5], v[210:211]
	v_pk_fma_f32 v[214:215], v[180:181], v[212:213], v[214:215]
	v_pk_add_f32 v[214:215], v[204:205], v[214:215]
	v_pk_mul_f32 v[216:217], v[214:215], s[92:93]
	v_pk_mul_f32 v[216:217], v[214:215], v[216:217]
	v_pk_fma_f32 v[216:217], v[214:215], v[216:217], v[214:215]
	v_pk_mul_f32 v[216:217], v[216:217], s[96:97]
	v_pk_mul_f32 v[216:217], v[216:217], s[28:29]
	v_exp_f32_e32 v216, v216
	v_exp_f32_e32 v217, v217
	s_nop 0
	v_add_f32_e32 v216, 1.0, v216
	v_add_f32_e32 v217, 1.0, v217
	v_rcp_f32_e32 v216, v216
	v_rcp_f32_e32 v217, v217
	s_nop 0
	v_pk_mul_f32 v[214:215], v[214:215], v[216:217]
	v_pk_mul_f32 v[214:215], v[12:13], v[214:215]
	v_cvt_pk_bf16_f32 v11, v214, v215
	v_mov_b32_dpp v210, v222 row_ror:1 row_mask:0xf bank_mask:0xf
	v_mov_b32_dpp v212, v222 row_ror:2 row_mask:0xf bank_mask:0xf
	v_mov_b32_dpp v211, v223 row_ror:1 row_mask:0xf bank_mask:0xf
	v_mov_b32_dpp v213, v223 row_ror:2 row_mask:0xf bank_mask:0xf
	s_nop 1
	v_mov_b32_dpp v210, v6 row_shr:1 row_mask:0xf bank_mask:0xf
	v_mov_b32_dpp v212, v6 row_shr:2 row_mask:0xf bank_mask:0xf
	v_mov_b32_dpp v211, v7 row_shr:1 row_mask:0xf bank_mask:0xf
	v_mov_b32_dpp v213, v7 row_shr:2 row_mask:0xf bank_mask:0xf
	s_nop 1
	v_pk_mul_f32 v[210:211], v[190:191], v[210:211]
	v_pk_fma_f32 v[214:215], v[198:199], v[6:7], v[210:211]
	v_pk_fma_f32 v[214:215], v[182:183], v[212:213], v[214:215]
	v_pk_add_f32 v[214:215], v[206:207], v[214:215]
	v_pk_mul_f32 v[216:217], v[214:215], s[92:93]
	v_pk_mul_f32 v[216:217], v[214:215], v[216:217]
	v_pk_fma_f32 v[216:217], v[214:215], v[216:217], v[214:215]
	v_pk_mul_f32 v[216:217], v[216:217], s[96:97]
	v_pk_mul_f32 v[216:217], v[216:217], s[28:29]
	v_exp_f32_e32 v216, v216
	v_exp_f32_e32 v217, v217
	s_nop 0
	v_add_f32_e32 v216, 1.0, v216
	v_add_f32_e32 v217, 1.0, v217
	v_rcp_f32_e32 v216, v216
	v_rcp_f32_e32 v217, v217
	s_nop 0
	v_pk_mul_f32 v[214:215], v[214:215], v[216:217]
	v_pk_mul_f32 v[214:215], v[14:15], v[214:215]
	v_cvt_pk_bf16_f32 v12, v214, v215
	v_mov_b32_dpp v210, v224 row_ror:1 row_mask:0xf bank_mask:0xf
	v_mov_b32_dpp v212, v224 row_ror:2 row_mask:0xf bank_mask:0xf
	v_mov_b32_dpp v211, v225 row_ror:1 row_mask:0xf bank_mask:0xf
	v_mov_b32_dpp v213, v225 row_ror:2 row_mask:0xf bank_mask:0xf
	s_nop 1
	v_mov_b32_dpp v210, v8 row_shr:1 row_mask:0xf bank_mask:0xf
	v_mov_b32_dpp v212, v8 row_shr:2 row_mask:0xf bank_mask:0xf
	v_mov_b32_dpp v211, v9 row_shr:1 row_mask:0xf bank_mask:0xf
	v_mov_b32_dpp v213, v9 row_shr:2 row_mask:0xf bank_mask:0xf
	s_nop 1
	v_pk_mul_f32 v[210:211], v[192:193], v[210:211]
	v_pk_fma_f32 v[214:215], v[200:201], v[8:9], v[210:211]
	v_pk_fma_f32 v[214:215], v[184:185], v[212:213], v[214:215]
	v_pk_add_f32 v[214:215], v[208:209], v[214:215]
	v_pk_mul_f32 v[216:217], v[214:215], s[92:93]
	v_pk_mul_f32 v[216:217], v[214:215], v[216:217]
	v_pk_fma_f32 v[216:217], v[214:215], v[216:217], v[214:215]
	v_pk_mul_f32 v[216:217], v[216:217], s[96:97]
	v_pk_mul_f32 v[216:217], v[216:217], s[28:29]
	v_exp_f32_e32 v216, v216
	v_exp_f32_e32 v217, v217
	s_nop 0
	v_add_f32_e32 v216, 1.0, v216
	v_add_f32_e32 v217, 1.0, v217
	v_rcp_f32_e32 v216, v216
	v_rcp_f32_e32 v217, v217
	s_nop 0
	v_pk_mul_f32 v[214:215], v[214:215], v[216:217]
	v_pk_mul_f32 v[214:215], v[16:17], v[214:215]
	v_cvt_pk_bf16_f32 v13, v214, v215
	s_add_i32 s26, s66, 0
	v_cmp_gt_i32_e64 s[24:25], s26, v227
	v_cmp_lt_u32_e32 vcc, 1, v227
	s_and_b64 s[24:25], s[24:25], vcc
	s_nop 1
	s_and_saveexec_b64 s[26:27], s[24:25]
	global_store_dwordx4 v242, v[10:13], s[18:19]
	s_mov_b64 exec, s[26:27]
	s_nop 4

.Lpj_nn_a:
	s_waitcnt vmcnt(6) lgkmcnt(0)
	s_barrier
	v_add_u32_e32 v240, s61, v238
	v_add_u32_e32 v241, s61, v239
	s_setprio 1
	s_add_i32 m0, s60, s62
	v_mfma_f32_16x16x32_bf16 v[2:5], v[162:165], v[130:133], 0
	global_load_lds_dwordx4 v226, s[54:55]
	v_mfma_f32_16x16x32_bf16 v[6:9], v[166:169], v[130:133], 0
	global_load_lds_dwordx4 v226, s[54:55] offset:1024
	v_mfma_f32_16x16x32_bf16 v[10:13], v[170:173], v[130:133], 0
	global_load_lds_dwordx4 v226, s[54:55] offset:2048
	v_mfma_f32_16x16x32_bf16 v[14:17], v[174:177], v[130:133], 0
	global_load_lds_dwordx4 v226, s[54:55] offset:3072
	s_add_i32 m0, s60, s63
	v_mfma_f32_16x16x32_bf16 v[18:21], v[162:165], v[134:137], 0
	global_load_lds_dwordx4 v230, s[56:57]
	v_mfma_f32_16x16x32_bf16 v[22:25], v[166:169], v[134:137], 0
	global_load_lds_dwordx4 v231, s[56:57] offset:1024
	v_mfma_f32_16x16x32_bf16 v[26:29], v[170:173], v[134:137], 0
	v_mfma_f32_16x16x32_bf16 v[30:33], v[174:177], v[134:137], 0
	v_mfma_f32_16x16x32_bf16 v[34:37], v[162:165], v[138:141], 0
	ds_read_b128 v[210:213], v241 offset:0
	v_mfma_f32_16x16x32_bf16 v[38:41], v[166:169], v[138:141], 0
	ds_read_b128 v[214:217], v241 offset:256
	v_mfma_f32_16x16x32_bf16 v[42:45], v[170:173], v[138:141], 0
	ds_read_b128 v[218:221], v241 offset:2048
	v_mfma_f32_16x16x32_bf16 v[46:49], v[174:177], v[138:141], 0
	ds_read_b128 v[222:225], v241 offset:2304
	v_mfma_f32_16x16x32_bf16 v[50:53], v[162:165], v[142:145], 0
	ds_read_b128 v[178:181], v240 offset:0
	v_mfma_f32_16x16x32_bf16 v[54:57], v[166:169], v[142:145], 0
	ds_read_b128 v[182:185], v240 offset:1024
	v_mfma_f32_16x16x32_bf16 v[58:61], v[170:173], v[142:145], 0
	ds_read_b128 v[186:189], v240 offset:2048
	v_mfma_f32_16x16x32_bf16 v[62:65], v[174:177], v[142:145], 0
	ds_read_b128 v[190:193], v240 offset:3072
	v_mfma_f32_16x16x32_bf16 v[66:69], v[162:165], v[146:149], 0
	ds_read_b128 v[194:197], v240 offset:4096
	v_mfma_f32_16x16x32_bf16 v[70:73], v[166:169], v[146:149], 0
	ds_read_b128 v[198:201], v240 offset:5120
	v_mfma_f32_16x16x32_bf16 v[74:77], v[170:173], v[146:149], 0
	ds_read_b128 v[202:205], v240 offset:6144
	v_mfma_f32_16x16x32_bf16 v[78:81], v[174:177], v[146:149], 0
	ds_read_b128 v[206:209], v240 offset:7168
	v_mfma_f32_16x16x32_bf16 v[82:85], v[162:165], v[150:153], 0
	v_mfma_f32_16x16x32_bf16 v[86:89], v[166:169], v[150:153], 0
	v_mfma_f32_16x16x32_bf16 v[90:93], v[170:173], v[150:153], 0
	v_mfma_f32_16x16x32_bf16 v[94:97], v[174:177], v[150:153], 0
	v_mfma_f32_16x16x32_bf16 v[98:101], v[162:165], v[154:157], 0
	v_mfma_f32_16x16x32_bf16 v[102:105], v[166:169], v[154:157], 0
	v_mfma_f32_16x16x32_bf16 v[106:109], v[170:173], v[154:157], 0
	v_mfma_f32_16x16x32_bf16 v[110:113], v[174:177], v[154:157], 0
	v_mfma_f32_16x16x32_bf16 v[114:117], v[162:165], v[158:161], 0
	v_mfma_f32_16x16x32_bf16 v[118:121], v[166:169], v[158:161], 0
	v_mfma_f32_16x16x32_bf16 v[122:125], v[170:173], v[158:161], 0
	v_mfma_f32_16x16x32_bf16 v[126:129], v[174:177], v[158:161], 0
	s_setprio 0
	s_add_i32 s60, s60, 0x6000
	s_cmp_eq_u32 s60, 0x12000
	s_cselect_b32 s60, 0, s60
	s_add_u32 s54, s54, s72
	s_addc_u32 s55, s55, 0
	s_add_u32 s56, s56, s73
	s_addc_u32 s57, s57, 0
	s_add_i32 s61, s61, 0x6000
	s_cmp_eq_u32 s61, 0x12000
	s_cselect_b32 s61, 0, s61
	s_waitcnt vmcnt(6) lgkmcnt(0)
	s_barrier
	v_add_u32_e32 v240, s61, v238
	v_add_u32_e32 v241, s61, v239
	s_setprio 1
	s_add_i32 m0, s60, s62
	v_mfma_f32_16x16x32_bf16 v[2:5], v[210:213], v[178:181], v[2:5]
	global_load_lds_dwordx4 v226, s[54:55]
	v_mfma_f32_16x16x32_bf16 v[6:9], v[214:217], v[178:181], v[6:9]
	global_load_lds_dwordx4 v226, s[54:55] offset:1024
	v_mfma_f32_16x16x32_bf16 v[10:13], v[218:221], v[178:181], v[10:13]
	global_load_lds_dwordx4 v226, s[54:55] offset:2048
	v_mfma_f32_16x16x32_bf16 v[14:17], v[222:225], v[178:181], v[14:17]
	global_load_lds_dwordx4 v226, s[54:55] offset:3072
	s_add_i32 m0, s60, s63
	v_mfma_f32_16x16x32_bf16 v[18:21], v[210:213], v[182:185], v[18:21]
	global_load_lds_dwordx4 v230, s[56:57]
	v_mfma_f32_16x16x32_bf16 v[22:25], v[214:217], v[182:185], v[22:25]
	global_load_lds_dwordx4 v231, s[56:57] offset:1024
	v_mfma_f32_16x16x32_bf16 v[26:29], v[218:221], v[182:185], v[26:29]
	v_mfma_f32_16x16x32_bf16 v[30:33], v[222:225], v[182:185], v[30:33]
	v_mfma_f32_16x16x32_bf16 v[34:37], v[210:213], v[186:189], v[34:37]
	ds_read_b128 v[162:165], v241 offset:0
	v_mfma_f32_16x16x32_bf16 v[38:41], v[214:217], v[186:189], v[38:41]
	ds_read_b128 v[166:169], v241 offset:256
	v_mfma_f32_16x16x32_bf16 v[42:45], v[218:221], v[186:189], v[42:45]
	ds_read_b128 v[170:173], v241 offset:2048
	v_mfma_f32_16x16x32_bf16 v[46:49], v[222:225], v[186:189], v[46:49]
	ds_read_b128 v[174:177], v241 offset:2304
	v_mfma_f32_16x16x32_bf16 v[50:53], v[210:213], v[190:193], v[50:53]
	ds_read_b128 v[130:133], v240 offset:0
	v_mfma_f32_16x16x32_bf16 v[54:57], v[214:217], v[190:193], v[54:57]
	ds_read_b128 v[134:137], v240 offset:1024
	v_mfma_f32_16x16x32_bf16 v[58:61], v[218:221], v[190:193], v[58:61]
	ds_read_b128 v[138:141], v240 offset:2048
	v_mfma_f32_16x16x32_bf16 v[62:65], v[222:225], v[190:193], v[62:65]
	ds_read_b128 v[142:145], v240 offset:3072
	v_mfma_f32_16x16x32_bf16 v[66:69], v[210:213], v[194:197], v[66:69]
	ds_read_b128 v[146:149], v240 offset:4096
	v_mfma_f32_16x16x32_bf16 v[70:73], v[214:217], v[194:197], v[70:73]
	ds_read_b128 v[150:153], v240 offset:5120
	v_mfma_f32_16x16x32_bf16 v[74:77], v[218:221], v[194:197], v[74:77]
	ds_read_b128 v[154:157], v240 offset:6144
	v_mfma_f32_16x16x32_bf16 v[78:81], v[222:225], v[194:197], v[78:81]
	ds_read_b128 v[158:161], v240 offset:7168
	v_mfma_f32_16x16x32_bf16 v[82:85], v[210:213], v[198:201], v[82:85]
	v_mfma_f32_16x16x32_bf16 v[86:89], v[214:217], v[198:201], v[86:89]
	v_mfma_f32_16x16x32_bf16 v[90:93], v[218:221], v[198:201], v[90:93]
	v_mfma_f32_16x16x32_bf16 v[94:97], v[222:225], v[198:201], v[94:97]
	v_mfma_f32_16x16x32_bf16 v[98:101], v[210:213], v[202:205], v[98:101]
	v_mfma_f32_16x16x32_bf16 v[102:105], v[214:217], v[202:205], v[102:105]
	v_mfma_f32_16x16x32_bf16 v[106:109], v[218:221], v[202:205], v[106:109]
	v_mfma_f32_16x16x32_bf16 v[110:113], v[222:225], v[202:205], v[110:113]
	v_mfma_f32_16x16x32_bf16 v[114:117], v[210:213], v[206:209], v[114:117]
	v_mfma_f32_16x16x32_bf16 v[118:121], v[214:217], v[206:209], v[118:121]
	v_mfma_f32_16x16x32_bf16 v[122:125], v[218:221], v[206:209], v[122:125]
	v_mfma_f32_16x16x32_bf16 v[126:129], v[222:225], v[206:209], v[126:129]
	s_setprio 0
	s_add_i32 s60, s60, 0x6000
	s_cmp_eq_u32 s60, 0x12000
	s_cselect_b32 s60, 0, s60
	s_add_u32 s54, s54, s72
	s_addc_u32 s55, s55, 0
	s_add_u32 s56, s56, s73
	s_addc_u32 s57, s57, 0
	s_add_i32 s61, s61, 0x6000
	s_cmp_eq_u32 s61, 0x12000
	s_cselect_b32 s61, 0, s61
	s_branch .Lpj_main

.Lpj_nn_b:
	s_waitcnt vmcnt(63) lgkmcnt(0)
	s_barrier
	v_add_u32_e32 v240, s61, v238
	v_add_u32_e32 v241, s61, v239
	s_setprio 1
	s_add_i32 m0, s60, s62
	v_mfma_f32_16x16x32_bf16 v[2:5], v[162:165], v[130:133], 0
	global_load_lds_dwordx4 v226, s[54:55]
	v_mfma_f32_16x16x32_bf16 v[6:9], v[166:169], v[130:133], 0
	global_load_lds_dwordx4 v226, s[54:55] offset:1024
	v_mfma_f32_16x16x32_bf16 v[10:13], v[170:173], v[130:133], 0
	global_load_lds_dwordx4 v226, s[54:55] offset:2048
	v_mfma_f32_16x16x32_bf16 v[14:17], v[174:177], v[130:133], 0
	global_load_lds_dwordx4 v226, s[54:55] offset:3072
	s_add_i32 m0, s60, s63
	v_mfma_f32_16x16x32_bf16 v[18:21], v[162:165], v[134:137], 0
	global_load_lds_dwordx4 v230, s[56:57]
	v_mfma_f32_16x16x32_bf16 v[22:25], v[166:169], v[134:137], 0
	global_load_lds_dwordx4 v231, s[56:57] offset:1024
	v_mfma_f32_16x16x32_bf16 v[26:29], v[170:173], v[134:137], 0
	v_mfma_f32_16x16x32_bf16 v[30:33], v[174:177], v[134:137], 0
	v_mfma_f32_16x16x32_bf16 v[34:37], v[162:165], v[138:141], 0
	ds_read_b128 v[210:213], v241 offset:0
	v_mfma_f32_16x16x32_bf16 v[38:41], v[166:169], v[138:141], 0
	ds_read_b128 v[214:217], v241 offset:256
	v_mfma_f32_16x16x32_bf16 v[42:45], v[170:173], v[138:141], 0
	ds_read_b128 v[218:221], v241 offset:2048
	v_mfma_f32_16x16x32_bf16 v[46:49], v[174:177], v[138:141], 0
	ds_read_b128 v[222:225], v241 offset:2304
	v_mfma_f32_16x16x32_bf16 v[50:53], v[162:165], v[142:145], 0
	ds_read_b128 v[178:181], v240 offset:0
	v_mfma_f32_16x16x32_bf16 v[54:57], v[166:169], v[142:145], 0
	ds_read_b128 v[182:185], v240 offset:1024
	v_mfma_f32_16x16x32_bf16 v[58:61], v[170:173], v[142:145], 0
	ds_read_b128 v[186:189], v240 offset:2048
	v_mfma_f32_16x16x32_bf16 v[62:65], v[174:177], v[142:145], 0
	ds_read_b128 v[190:193], v240 offset:3072
	v_mfma_f32_16x16x32_bf16 v[66:69], v[162:165], v[146:149], 0
	ds_read_b128 v[194:197], v240 offset:4096
	v_mfma_f32_16x16x32_bf16 v[70:73], v[166:169], v[146:149], 0
	ds_read_b128 v[198:201], v240 offset:5120
	v_mfma_f32_16x16x32_bf16 v[74:77], v[170:173], v[146:149], 0
	ds_read_b128 v[202:205], v240 offset:6144
	v_mfma_f32_16x16x32_bf16 v[78:81], v[174:177], v[146:149], 0
	ds_read_b128 v[206:209], v240 offset:7168
	v_mfma_f32_16x16x32_bf16 v[82:85], v[162:165], v[150:153], 0
	v_mfma_f32_16x16x32_bf16 v[86:89], v[166:169], v[150:153], 0
	v_mfma_f32_16x16x32_bf16 v[90:93], v[170:173], v[150:153], 0
	v_mfma_f32_16x16x32_bf16 v[94:97], v[174:177], v[150:153], 0
	v_mfma_f32_16x16x32_bf16 v[98:101], v[162:165], v[154:157], 0
	v_mfma_f32_16x16x32_bf16 v[102:105], v[166:169], v[154:157], 0
	v_mfma_f32_16x16x32_bf16 v[106:109], v[170:173], v[154:157], 0
	v_mfma_f32_16x16x32_bf16 v[110:113], v[174:177], v[154:157], 0
	v_mfma_f32_16x16x32_bf16 v[114:117], v[162:165], v[158:161], 0
	v_mfma_f32_16x16x32_bf16 v[118:121], v[166:169], v[158:161], 0
	v_mfma_f32_16x16x32_bf16 v[122:125], v[170:173], v[158:161], 0
	v_mfma_f32_16x16x32_bf16 v[126:129], v[174:177], v[158:161], 0
	s_setprio 0
	s_add_i32 s60, s60, 0x6000
	s_cmp_eq_u32 s60, 0x12000
	s_cselect_b32 s60, 0, s60
	s_add_u32 s54, s54, s72
	s_addc_u32 s55, s55, 0
	s_add_u32 s56, s56, s73
	s_addc_u32 s57, s57, 0
	s_add_i32 s61, s61, 0x6000
	s_cmp_eq_u32 s61, 0x12000
	s_cselect_b32 s61, 0, s61
	s_waitcnt vmcnt(63) lgkmcnt(0)
	s_barrier
	v_add_u32_e32 v240, s61, v238
	v_add_u32_e32 v241, s61, v239
	s_setprio 1
	s_add_i32 m0, s60, s62
	v_mfma_f32_16x16x32_bf16 v[2:5], v[210:213], v[178:181], v[2:5]
	global_load_lds_dwordx4 v226, s[54:55]
	v_mfma_f32_16x16x32_bf16 v[6:9], v[214:217], v[178:181], v[6:9]
	global_load_lds_dwordx4 v226, s[54:55] offset:1024
	v_mfma_f32_16x16x32_bf16 v[10:13], v[218:221], v[178:181], v[10:13]
	global_load_lds_dwordx4 v226, s[54:55] offset:2048
	v_mfma_f32_16x16x32_bf16 v[14:17], v[222:225], v[178:181], v[14:17]
	global_load_lds_dwordx4 v226, s[54:55] offset:3072
	s_add_i32 m0, s60, s63
	v_mfma_f32_16x16x32_bf16 v[18:21], v[210:213], v[182:185], v[18:21]
	global_load_lds_dwordx4 v230, s[56:57]
	v_mfma_f32_16x16x32_bf16 v[22:25], v[214:217], v[182:185], v[22:25]
	global_load_lds_dwordx4 v231, s[56:57] offset:1024
	v_mfma_f32_16x16x32_bf16 v[26:29], v[218:221], v[182:185], v[26:29]
	v_mfma_f32_16x16x32_bf16 v[30:33], v[222:225], v[182:185], v[30:33]
	v_mfma_f32_16x16x32_bf16 v[34:37], v[210:213], v[186:189], v[34:37]
	ds_read_b128 v[162:165], v241 offset:0
	v_mfma_f32_16x16x32_bf16 v[38:41], v[214:217], v[186:189], v[38:41]
	ds_read_b128 v[166:169], v241 offset:256
	v_mfma_f32_16x16x32_bf16 v[42:45], v[218:221], v[186:189], v[42:45]
	ds_read_b128 v[170:173], v241 offset:2048
	v_mfma_f32_16x16x32_bf16 v[46:49], v[222:225], v[186:189], v[46:49]
	ds_read_b128 v[174:177], v241 offset:2304
	v_mfma_f32_16x16x32_bf16 v[50:53], v[210:213], v[190:193], v[50:53]
	ds_read_b128 v[130:133], v240 offset:0
	v_mfma_f32_16x16x32_bf16 v[54:57], v[214:217], v[190:193], v[54:57]
	ds_read_b128 v[134:137], v240 offset:1024
	v_mfma_f32_16x16x32_bf16 v[58:61], v[218:221], v[190:193], v[58:61]
	ds_read_b128 v[138:141], v240 offset:2048
	v_mfma_f32_16x16x32_bf16 v[62:65], v[222:225], v[190:193], v[62:65]
	ds_read_b128 v[142:145], v240 offset:3072
	v_mfma_f32_16x16x32_bf16 v[66:69], v[210:213], v[194:197], v[66:69]
	ds_read_b128 v[146:149], v240 offset:4096
	v_mfma_f32_16x16x32_bf16 v[70:73], v[214:217], v[194:197], v[70:73]
	ds_read_b128 v[150:153], v240 offset:5120
	v_mfma_f32_16x16x32_bf16 v[74:77], v[218:221], v[194:197], v[74:77]
	ds_read_b128 v[154:157], v240 offset:6144
	v_mfma_f32_16x16x32_bf16 v[78:81], v[222:225], v[194:197], v[78:81]
	ds_read_b128 v[158:161], v240 offset:7168
	v_mfma_f32_16x16x32_bf16 v[82:85], v[210:213], v[198:201], v[82:85]
	v_mfma_f32_16x16x32_bf16 v[86:89], v[214:217], v[198:201], v[86:89]
	v_mfma_f32_16x16x32_bf16 v[90:93], v[218:221], v[198:201], v[90:93]
	v_mfma_f32_16x16x32_bf16 v[94:97], v[222:225], v[198:201], v[94:97]
	v_mfma_f32_16x16x32_bf16 v[98:101], v[210:213], v[202:205], v[98:101]
	v_mfma_f32_16x16x32_bf16 v[102:105], v[214:217], v[202:205], v[102:105]
	v_mfma_f32_16x16x32_bf16 v[106:109], v[218:221], v[202:205], v[106:109]
	v_mfma_f32_16x16x32_bf16 v[110:113], v[222:225], v[202:205], v[110:113]
	v_mfma_f32_16x16x32_bf16 v[114:117], v[210:213], v[206:209], v[114:117]
	v_mfma_f32_16x16x32_bf16 v[118:121], v[214:217], v[206:209], v[118:121]
	v_mfma_f32_16x16x32_bf16 v[122:125], v[218:221], v[206:209], v[122:125]
	v_mfma_f32_16x16x32_bf16 v[126:129], v[222:225], v[206:209], v[126:129]
	s_setprio 0
	s_add_i32 s60, s60, 0x6000
	s_cmp_eq_u32 s60, 0x12000
	s_cselect_b32 s60, 0, s60
	s_add_u32 s54, s54, s72
	s_addc_u32 s55, s55, 0
	s_add_u32 s56, s56, s73
	s_addc_u32 s57, s57, 0
	s_add_i32 s61, s61, 0x6000
	s_cmp_eq_u32 s61, 0x12000
	s_cselect_b32 s61, 0, s61

.Lpj_kloop:
	s_waitcnt vmcnt(6) lgkmcnt(0)
	s_barrier
	v_add_u32_e32 v240, s61, v238
	v_add_u32_e32 v241, s61, v239
	s_setprio 1
	s_add_i32 m0, s60, s62
	v_mfma_f32_16x16x32_bf16 v[2:5], v[162:165], v[130:133], v[2:5]
	global_load_lds_dwordx4 v226, s[54:55]
	v_mfma_f32_16x16x32_bf16 v[6:9], v[166:169], v[130:133], v[6:9]
	global_load_lds_dwordx4 v226, s[54:55] offset:1024
	v_mfma_f32_16x16x32_bf16 v[10:13], v[170:173], v[130:133], v[10:13]
	global_load_lds_dwordx4 v226, s[54:55] offset:2048
	v_mfma_f32_16x16x32_bf16 v[14:17], v[174:177], v[130:133], v[14:17]
	global_load_lds_dwordx4 v226, s[54:55] offset:3072
	s_add_i32 m0, s60, s63
	v_mfma_f32_16x16x32_bf16 v[18:21], v[162:165], v[134:137], v[18:21]
	global_load_lds_dwordx4 v230, s[56:57]
	v_mfma_f32_16x16x32_bf16 v[22:25], v[166:169], v[134:137], v[22:25]
	global_load_lds_dwordx4 v231, s[56:57] offset:1024
	v_mfma_f32_16x16x32_bf16 v[26:29], v[170:173], v[134:137], v[26:29]
	v_mfma_f32_16x16x32_bf16 v[30:33], v[174:177], v[134:137], v[30:33]
	v_mfma_f32_16x16x32_bf16 v[34:37], v[162:165], v[138:141], v[34:37]
	ds_read_b128 v[210:213], v241 offset:0
	v_mfma_f32_16x16x32_bf16 v[38:41], v[166:169], v[138:141], v[38:41]
	ds_read_b128 v[214:217], v241 offset:256
	v_mfma_f32_16x16x32_bf16 v[42:45], v[170:173], v[138:141], v[42:45]
	ds_read_b128 v[218:221], v241 offset:2048
	v_mfma_f32_16x16x32_bf16 v[46:49], v[174:177], v[138:141], v[46:49]
	ds_read_b128 v[222:225], v241 offset:2304
	v_mfma_f32_16x16x32_bf16 v[50:53], v[162:165], v[142:145], v[50:53]
	ds_read_b128 v[178:181], v240 offset:0
	v_mfma_f32_16x16x32_bf16 v[54:57], v[166:169], v[142:145], v[54:57]
	ds_read_b128 v[182:185], v240 offset:1024
	v_mfma_f32_16x16x32_bf16 v[58:61], v[170:173], v[142:145], v[58:61]
	ds_read_b128 v[186:189], v240 offset:2048
	v_mfma_f32_16x16x32_bf16 v[62:65], v[174:177], v[142:145], v[62:65]
	ds_read_b128 v[190:193], v240 offset:3072
	v_mfma_f32_16x16x32_bf16 v[66:69], v[162:165], v[146:149], v[66:69]
	ds_read_b128 v[194:197], v240 offset:4096
	v_mfma_f32_16x16x32_bf16 v[70:73], v[166:169], v[146:149], v[70:73]
	ds_read_b128 v[198:201], v240 offset:5120
	v_mfma_f32_16x16x32_bf16 v[74:77], v[170:173], v[146:149], v[74:77]
	ds_read_b128 v[202:205], v240 offset:6144
	v_mfma_f32_16x16x32_bf16 v[78:81], v[174:177], v[146:149], v[78:81]
	ds_read_b128 v[206:209], v240 offset:7168
	v_mfma_f32_16x16x32_bf16 v[82:85], v[162:165], v[150:153], v[82:85]
	v_mfma_f32_16x16x32_bf16 v[86:89], v[166:169], v[150:153], v[86:89]
	v_mfma_f32_16x16x32_bf16 v[90:93], v[170:173], v[150:153], v[90:93]
	v_mfma_f32_16x16x32_bf16 v[94:97], v[174:177], v[150:153], v[94:97]
	v_mfma_f32_16x16x32_bf16 v[98:101], v[162:165], v[154:157], v[98:101]
	v_mfma_f32_16x16x32_bf16 v[102:105], v[166:169], v[154:157], v[102:105]
	v_mfma_f32_16x16x32_bf16 v[106:109], v[170:173], v[154:157], v[106:109]
	v_mfma_f32_16x16x32_bf16 v[110:113], v[174:177], v[154:157], v[110:113]
	v_mfma_f32_16x16x32_bf16 v[114:117], v[162:165], v[158:161], v[114:117]
	v_mfma_f32_16x16x32_bf16 v[118:121], v[166:169], v[158:161], v[118:121]
	v_mfma_f32_16x16x32_bf16 v[122:125], v[170:173], v[158:161], v[122:125]
	v_mfma_f32_16x16x32_bf16 v[126:129], v[174:177], v[158:161], v[126:129]
	s_setprio 0
	s_add_i32 s60, s60, 0x6000
	s_cmp_eq_u32 s60, 0x12000
	s_cselect_b32 s60, 0, s60
	s_add_u32 s54, s54, s72
	s_addc_u32 s55, s55, 0
	s_add_u32 s56, s56, s73
	s_addc_u32 s57, s57, 0
	s_add_i32 s61, s61, 0x6000
	s_cmp_eq_u32 s61, 0x12000
	s_cselect_b32 s61, 0, s61
	s_waitcnt vmcnt(6) lgkmcnt(0)
	s_barrier
	v_add_u32_e32 v240, s61, v238
	v_add_u32_e32 v241, s61, v239
	s_setprio 1
	s_add_i32 m0, s60, s62
	v_mfma_f32_16x16x32_bf16 v[2:5], v[210:213], v[178:181], v[2:5]
	global_load_lds_dwordx4 v226, s[54:55]
	v_mfma_f32_16x16x32_bf16 v[6:9], v[214:217], v[178:181], v[6:9]
	global_load_lds_dwordx4 v226, s[54:55] offset:1024
	v_mfma_f32_16x16x32_bf16 v[10:13], v[218:221], v[178:181], v[10:13]
	global_load_lds_dwordx4 v226, s[54:55] offset:2048
	v_mfma_f32_16x16x32_bf16 v[14:17], v[222:225], v[178:181], v[14:17]
	global_load_lds_dwordx4 v226, s[54:55] offset:3072
	s_add_i32 m0, s60, s63
	v_mfma_f32_16x16x32_bf16 v[18:21], v[210:213], v[182:185], v[18:21]
	global_load_lds_dwordx4 v230, s[56:57]
	v_mfma_f32_16x16x32_bf16 v[22:25], v[214:217], v[182:185], v[22:25]
	global_load_lds_dwordx4 v231, s[56:57] offset:1024
	v_mfma_f32_16x16x32_bf16 v[26:29], v[218:221], v[182:185], v[26:29]
	v_mfma_f32_16x16x32_bf16 v[30:33], v[222:225], v[182:185], v[30:33]
	v_mfma_f32_16x16x32_bf16 v[34:37], v[210:213], v[186:189], v[34:37]
	ds_read_b128 v[162:165], v241 offset:0
	v_mfma_f32_16x16x32_bf16 v[38:41], v[214:217], v[186:189], v[38:41]
	ds_read_b128 v[166:169], v241 offset:256
	v_mfma_f32_16x16x32_bf16 v[42:45], v[218:221], v[186:189], v[42:45]
	ds_read_b128 v[170:173], v241 offset:2048
	v_mfma_f32_16x16x32_bf16 v[46:49], v[222:225], v[186:189], v[46:49]
	ds_read_b128 v[174:177], v241 offset:2304
	v_mfma_f32_16x16x32_bf16 v[50:53], v[210:213], v[190:193], v[50:53]
	ds_read_b128 v[130:133], v240 offset:0
	v_mfma_f32_16x16x32_bf16 v[54:57], v[214:217], v[190:193], v[54:57]
	ds_read_b128 v[134:137], v240 offset:1024
	v_mfma_f32_16x16x32_bf16 v[58:61], v[218:221], v[190:193], v[58:61]
	ds_read_b128 v[138:141], v240 offset:2048
	v_mfma_f32_16x16x32_bf16 v[62:65], v[222:225], v[190:193], v[62:65]
	ds_read_b128 v[142:145], v240 offset:3072
	v_mfma_f32_16x16x32_bf16 v[66:69], v[210:213], v[194:197], v[66:69]
	ds_read_b128 v[146:149], v240 offset:4096
	v_mfma_f32_16x16x32_bf16 v[70:73], v[214:217], v[194:197], v[70:73]
	ds_read_b128 v[150:153], v240 offset:5120
	v_mfma_f32_16x16x32_bf16 v[74:77], v[218:221], v[194:197], v[74:77]
	ds_read_b128 v[154:157], v240 offset:6144
	v_mfma_f32_16x16x32_bf16 v[78:81], v[222:225], v[194:197], v[78:81]
	ds_read_b128 v[158:161], v240 offset:7168
	v_mfma_f32_16x16x32_bf16 v[82:85], v[210:213], v[198:201], v[82:85]
	v_mfma_f32_16x16x32_bf16 v[86:89], v[214:217], v[198:201], v[86:89]
	v_mfma_f32_16x16x32_bf16 v[90:93], v[218:221], v[198:201], v[90:93]
	v_mfma_f32_16x16x32_bf16 v[94:97], v[222:225], v[198:201], v[94:97]
	v_mfma_f32_16x16x32_bf16 v[98:101], v[210:213], v[202:205], v[98:101]
	v_mfma_f32_16x16x32_bf16 v[102:105], v[214:217], v[202:205], v[102:105]
	v_mfma_f32_16x16x32_bf16 v[106:109], v[218:221], v[202:205], v[106:109]
	v_mfma_f32_16x16x32_bf16 v[110:113], v[222:225], v[202:205], v[110:113]
	v_mfma_f32_16x16x32_bf16 v[114:117], v[210:213], v[206:209], v[114:117]
	v_mfma_f32_16x16x32_bf16 v[118:121], v[214:217], v[206:209], v[118:121]
	v_mfma_f32_16x16x32_bf16 v[122:125], v[218:221], v[206:209], v[122:125]
	v_mfma_f32_16x16x32_bf16 v[126:129], v[222:225], v[206:209], v[126:129]
	s_setprio 0
	s_add_i32 s60, s60, 0x6000
	s_cmp_eq_u32 s60, 0x12000
	s_cselect_b32 s60, 0, s60
	s_add_u32 s54, s54, s72
	s_addc_u32 s55, s55, 0
	s_add_u32 s56, s56, s73
	s_addc_u32 s57, s57, 0
	s_add_i32 s61, s61, 0x6000
	s_cmp_eq_u32 s61, 0x12000
	s_cselect_b32 s61, 0, s61
	s_add_i32 s40, s40, -1
	s_cmp_lg_u32 s40, 0
	s_cbranch_scc1 .Lpj_kloop
	s_cmp_eq_u32 s37, 0
	s_cbranch_scc1 .Lpj_tail_last
	s_waitcnt vmcnt(6) lgkmcnt(0)
	s_barrier
	v_add_u32_e32 v240, s61, v238
	v_add_u32_e32 v241, s61, v239
	s_setprio 1
	s_add_i32 m0, s60, s62
	v_mfma_f32_16x16x32_bf16 v[2:5], v[162:165], v[130:133], v[2:5]
	global_load_lds_dwordx4 v226, s[54:55]
	v_mfma_f32_16x16x32_bf16 v[6:9], v[166:169], v[130:133], v[6:9]
	global_load_lds_dwordx4 v226, s[54:55] offset:1024
	v_mfma_f32_16x16x32_bf16 v[10:13], v[170:173], v[130:133], v[10:13]
	global_load_lds_dwordx4 v226, s[54:55] offset:2048
	v_mfma_f32_16x16x32_bf16 v[14:17], v[174:177], v[130:133], v[14:17]
	global_load_lds_dwordx4 v226, s[54:55] offset:3072
	s_add_i32 m0, s60, s63
	v_mfma_f32_16x16x32_bf16 v[18:21], v[162:165], v[134:137], v[18:21]
	global_load_lds_dwordx4 v230, s[56:57]
	v_mfma_f32_16x16x32_bf16 v[22:25], v[166:169], v[134:137], v[22:25]
	global_load_lds_dwordx4 v231, s[56:57] offset:1024
	v_mfma_f32_16x16x32_bf16 v[26:29], v[170:173], v[134:137], v[26:29]
	v_mfma_f32_16x16x32_bf16 v[30:33], v[174:177], v[134:137], v[30:33]
	v_mfma_f32_16x16x32_bf16 v[34:37], v[162:165], v[138:141], v[34:37]
	ds_read_b128 v[210:213], v241 offset:0
	v_mfma_f32_16x16x32_bf16 v[38:41], v[166:169], v[138:141], v[38:41]
	ds_read_b128 v[214:217], v241 offset:256
	v_mfma_f32_16x16x32_bf16 v[42:45], v[170:173], v[138:141], v[42:45]
	ds_read_b128 v[218:221], v241 offset:2048
	v_mfma_f32_16x16x32_bf16 v[46:49], v[174:177], v[138:141], v[46:49]
	ds_read_b128 v[222:225], v241 offset:2304
	v_mfma_f32_16x16x32_bf16 v[50:53], v[162:165], v[142:145], v[50:53]
	ds_read_b128 v[178:181], v240 offset:0
	v_mfma_f32_16x16x32_bf16 v[54:57], v[166:169], v[142:145], v[54:57]
	ds_read_b128 v[182:185], v240 offset:1024
	v_mfma_f32_16x16x32_bf16 v[58:61], v[170:173], v[142:145], v[58:61]
	ds_read_b128 v[186:189], v240 offset:2048
	v_mfma_f32_16x16x32_bf16 v[62:65], v[174:177], v[142:145], v[62:65]
	ds_read_b128 v[190:193], v240 offset:3072
	v_mfma_f32_16x16x32_bf16 v[66:69], v[162:165], v[146:149], v[66:69]
	ds_read_b128 v[194:197], v240 offset:4096
	v_mfma_f32_16x16x32_bf16 v[70:73], v[166:169], v[146:149], v[70:73]
	ds_read_b128 v[198:201], v240 offset:5120
	v_mfma_f32_16x16x32_bf16 v[74:77], v[170:173], v[146:149], v[74:77]
	ds_read_b128 v[202:205], v240 offset:6144
	v_mfma_f32_16x16x32_bf16 v[78:81], v[174:177], v[146:149], v[78:81]
	ds_read_b128 v[206:209], v240 offset:7168
	v_mfma_f32_16x16x32_bf16 v[82:85], v[162:165], v[150:153], v[82:85]
	v_mfma_f32_16x16x32_bf16 v[86:89], v[166:169], v[150:153], v[86:89]
	v_mfma_f32_16x16x32_bf16 v[90:93], v[170:173], v[150:153], v[90:93]
	v_mfma_f32_16x16x32_bf16 v[94:97], v[174:177], v[150:153], v[94:97]
	v_mfma_f32_16x16x32_bf16 v[98:101], v[162:165], v[154:157], v[98:101]
	v_mfma_f32_16x16x32_bf16 v[102:105], v[166:169], v[154:157], v[102:105]
	v_mfma_f32_16x16x32_bf16 v[106:109], v[170:173], v[154:157], v[106:109]
	v_mfma_f32_16x16x32_bf16 v[110:113], v[174:177], v[154:157], v[110:113]
	v_mfma_f32_16x16x32_bf16 v[114:117], v[162:165], v[158:161], v[114:117]
	v_mfma_f32_16x16x32_bf16 v[118:121], v[166:169], v[158:161], v[118:121]
	v_mfma_f32_16x16x32_bf16 v[122:125], v[170:173], v[158:161], v[122:125]
	v_mfma_f32_16x16x32_bf16 v[126:129], v[174:177], v[158:161], v[126:129]
	s_setprio 0
	s_add_i32 s60, s60, 0x6000
	s_cmp_eq_u32 s60, 0x12000
	s_cselect_b32 s60, 0, s60
	s_add_u32 s54, s54, s72
	s_addc_u32 s55, s55, 0
	s_add_u32 s56, s56, s73
	s_addc_u32 s57, s57, 0
	s_add_i32 s61, s61, 0x6000
	s_cmp_eq_u32 s61, 0x12000
	s_cselect_b32 s61, 0, s61
	v_mov_b32_e32 v226, v232
	v_mov_b32_e32 v230, v236
	v_mov_b32_e32 v231, v237
	s_mov_b64 s[54:55], s[48:49]
	s_mov_b64 s[56:57], s[50:51]
	s_waitcnt vmcnt(6) lgkmcnt(0)
	s_barrier
	v_add_u32_e32 v240, s61, v238
	v_add_u32_e32 v241, s61, v239
	s_setprio 1
	s_add_i32 m0, s60, s62
	v_mfma_f32_16x16x32_bf16 v[2:5], v[210:213], v[178:181], v[2:5]
	global_load_lds_dwordx4 v226, s[54:55]
	v_mfma_f32_16x16x32_bf16 v[6:9], v[214:217], v[178:181], v[6:9]
	global_load_lds_dwordx4 v226, s[54:55] offset:1024
	v_mfma_f32_16x16x32_bf16 v[10:13], v[218:221], v[178:181], v[10:13]
	global_load_lds_dwordx4 v226, s[54:55] offset:2048
	v_mfma_f32_16x16x32_bf16 v[14:17], v[222:225], v[178:181], v[14:17]
	global_load_lds_dwordx4 v226, s[54:55] offset:3072
	s_add_i32 m0, s60, s63
	v_mfma_f32_16x16x32_bf16 v[18:21], v[210:213], v[182:185], v[18:21]
	global_load_lds_dwordx4 v230, s[56:57]
	v_mfma_f32_16x16x32_bf16 v[22:25], v[214:217], v[182:185], v[22:25]
	global_load_lds_dwordx4 v231, s[56:57] offset:1024
	v_mfma_f32_16x16x32_bf16 v[26:29], v[218:221], v[182:185], v[26:29]
	v_mfma_f32_16x16x32_bf16 v[30:33], v[222:225], v[182:185], v[30:33]
	v_mfma_f32_16x16x32_bf16 v[34:37], v[210:213], v[186:189], v[34:37]
	ds_read_b128 v[162:165], v241 offset:0
	v_mfma_f32_16x16x32_bf16 v[38:41], v[214:217], v[186:189], v[38:41]
	ds_read_b128 v[166:169], v241 offset:256
	v_mfma_f32_16x16x32_bf16 v[42:45], v[218:221], v[186:189], v[42:45]
	ds_read_b128 v[170:173], v241 offset:2048
	v_mfma_f32_16x16x32_bf16 v[46:49], v[222:225], v[186:189], v[46:49]
	ds_read_b128 v[174:177], v241 offset:2304
	v_mfma_f32_16x16x32_bf16 v[50:53], v[210:213], v[190:193], v[50:53]
	ds_read_b128 v[130:133], v240 offset:0
	v_mfma_f32_16x16x32_bf16 v[54:57], v[214:217], v[190:193], v[54:57]
	ds_read_b128 v[134:137], v240 offset:1024
	v_mfma_f32_16x16x32_bf16 v[58:61], v[218:221], v[190:193], v[58:61]
	ds_read_b128 v[138:141], v240 offset:2048
	v_mfma_f32_16x16x32_bf16 v[62:65], v[222:225], v[190:193], v[62:65]
	ds_read_b128 v[142:145], v240 offset:3072
	v_mfma_f32_16x16x32_bf16 v[66:69], v[210:213], v[194:197], v[66:69]
	ds_read_b128 v[146:149], v240 offset:4096
	v_mfma_f32_16x16x32_bf16 v[70:73], v[214:217], v[194:197], v[70:73]
	ds_read_b128 v[150:153], v240 offset:5120
	v_mfma_f32_16x16x32_bf16 v[74:77], v[218:221], v[194:197], v[74:77]
	ds_read_b128 v[154:157], v240 offset:6144
	v_mfma_f32_16x16x32_bf16 v[78:81], v[222:225], v[194:197], v[78:81]
	ds_read_b128 v[158:161], v240 offset:7168
	v_mfma_f32_16x16x32_bf16 v[82:85], v[210:213], v[198:201], v[82:85]
	v_mfma_f32_16x16x32_bf16 v[86:89], v[214:217], v[198:201], v[86:89]
	v_mfma_f32_16x16x32_bf16 v[90:93], v[218:221], v[198:201], v[90:93]
	v_mfma_f32_16x16x32_bf16 v[94:97], v[222:225], v[198:201], v[94:97]
	v_mfma_f32_16x16x32_bf16 v[98:101], v[210:213], v[202:205], v[98:101]
	v_mfma_f32_16x16x32_bf16 v[102:105], v[214:217], v[202:205], v[102:105]
	v_mfma_f32_16x16x32_bf16 v[106:109], v[218:221], v[202:205], v[106:109]
	v_mfma_f32_16x16x32_bf16 v[110:113], v[222:225], v[202:205], v[110:113]
	v_mfma_f32_16x16x32_bf16 v[114:117], v[210:213], v[206:209], v[114:117]
	v_mfma_f32_16x16x32_bf16 v[118:121], v[214:217], v[206:209], v[118:121]
	v_mfma_f32_16x16x32_bf16 v[122:125], v[218:221], v[206:209], v[122:125]
	v_mfma_f32_16x16x32_bf16 v[126:129], v[222:225], v[206:209], v[126:129]
	s_setprio 0
	s_add_i32 s60, s60, 0x6000
	s_cmp_eq_u32 s60, 0x12000
	s_cselect_b32 s60, 0, s60
	s_add_u32 s54, s54, s72
	s_addc_u32 s55, s55, 0
	s_add_u32 s56, s56, s73
	s_addc_u32 s57, s57, 0
	s_add_i32 s61, s61, 0x6000
	s_cmp_eq_u32 s61, 0x12000
	s_cselect_b32 s61, 0, s61
	s_waitcnt vmcnt(6) lgkmcnt(0)
	s_barrier
	v_add_u32_e32 v240, s61, v238
	v_add_u32_e32 v241, s61, v239
	s_setprio 1
	s_add_i32 m0, s60, s62
	v_mfma_f32_16x16x32_bf16 v[2:5], v[162:165], v[130:133], v[2:5]
	global_load_lds_dwordx4 v226, s[54:55]
	v_mfma_f32_16x16x32_bf16 v[6:9], v[166:169], v[130:133], v[6:9]
	global_load_lds_dwordx4 v226, s[54:55] offset:1024
	v_mfma_f32_16x16x32_bf16 v[10:13], v[170:173], v[130:133], v[10:13]
	global_load_lds_dwordx4 v226, s[54:55] offset:2048
	v_mfma_f32_16x16x32_bf16 v[14:17], v[174:177], v[130:133], v[14:17]
	global_load_lds_dwordx4 v226, s[54:55] offset:3072
	s_add_i32 m0, s60, s63
	v_mfma_f32_16x16x32_bf16 v[18:21], v[162:165], v[134:137], v[18:21]
	global_load_lds_dwordx4 v230, s[56:57]
	v_mfma_f32_16x16x32_bf16 v[22:25], v[166:169], v[134:137], v[22:25]
	global_load_lds_dwordx4 v231, s[56:57] offset:1024
	v_mfma_f32_16x16x32_bf16 v[26:29], v[170:173], v[134:137], v[26:29]
	v_mfma_f32_16x16x32_bf16 v[30:33], v[174:177], v[134:137], v[30:33]
	v_mfma_f32_16x16x32_bf16 v[34:37], v[162:165], v[138:141], v[34:37]
	ds_read_b128 v[210:213], v241 offset:0
	v_mfma_f32_16x16x32_bf16 v[38:41], v[166:169], v[138:141], v[38:41]
	ds_read_b128 v[214:217], v241 offset:256
	v_mfma_f32_16x16x32_bf16 v[42:45], v[170:173], v[138:141], v[42:45]
	ds_read_b128 v[218:221], v241 offset:2048
	v_mfma_f32_16x16x32_bf16 v[46:49], v[174:177], v[138:141], v[46:49]
	ds_read_b128 v[222:225], v241 offset:2304
	v_mfma_f32_16x16x32_bf16 v[50:53], v[162:165], v[142:145], v[50:53]
	ds_read_b128 v[178:181], v240 offset:0
	v_mfma_f32_16x16x32_bf16 v[54:57], v[166:169], v[142:145], v[54:57]
	ds_read_b128 v[182:185], v240 offset:1024
	v_mfma_f32_16x16x32_bf16 v[58:61], v[170:173], v[142:145], v[58:61]
	ds_read_b128 v[186:189], v240 offset:2048
	v_mfma_f32_16x16x32_bf16 v[62:65], v[174:177], v[142:145], v[62:65]
	ds_read_b128 v[190:193], v240 offset:3072
	v_mfma_f32_16x16x32_bf16 v[66:69], v[162:165], v[146:149], v[66:69]
	ds_read_b128 v[194:197], v240 offset:4096
	v_mfma_f32_16x16x32_bf16 v[70:73], v[166:169], v[146:149], v[70:73]
	ds_read_b128 v[198:201], v240 offset:5120
	v_mfma_f32_16x16x32_bf16 v[74:77], v[170:173], v[146:149], v[74:77]
	ds_read_b128 v[202:205], v240 offset:6144
	v_mfma_f32_16x16x32_bf16 v[78:81], v[174:177], v[146:149], v[78:81]
	ds_read_b128 v[206:209], v240 offset:7168
	v_mfma_f32_16x16x32_bf16 v[82:85], v[162:165], v[150:153], v[82:85]
	v_mfma_f32_16x16x32_bf16 v[86:89], v[166:169], v[150:153], v[86:89]
	v_mfma_f32_16x16x32_bf16 v[90:93], v[170:173], v[150:153], v[90:93]
	v_mfma_f32_16x16x32_bf16 v[94:97], v[174:177], v[150:153], v[94:97]
	v_mfma_f32_16x16x32_bf16 v[98:101], v[162:165], v[154:157], v[98:101]
	v_mfma_f32_16x16x32_bf16 v[102:105], v[166:169], v[154:157], v[102:105]
	v_mfma_f32_16x16x32_bf16 v[106:109], v[170:173], v[154:157], v[106:109]
	v_mfma_f32_16x16x32_bf16 v[110:113], v[174:177], v[154:157], v[110:113]
	v_mfma_f32_16x16x32_bf16 v[114:117], v[162:165], v[158:161], v[114:117]
	v_mfma_f32_16x16x32_bf16 v[118:121], v[166:169], v[158:161], v[118:121]
	v_mfma_f32_16x16x32_bf16 v[122:125], v[170:173], v[158:161], v[122:125]
	v_mfma_f32_16x16x32_bf16 v[126:129], v[174:177], v[158:161], v[126:129]
	s_setprio 0
	s_add_i32 s60, s60, 0x6000
	s_cmp_eq_u32 s60, 0x12000
	s_cselect_b32 s60, 0, s60
	s_add_u32 s54, s54, s72
	s_addc_u32 s55, s55, 0
	s_add_u32 s56, s56, s73
	s_addc_u32 s57, s57, 0
	s_add_i32 s61, s61, 0x6000
	s_cmp_eq_u32 s61, 0x12000
	s_cselect_b32 s61, 0, s61
	s_waitcnt vmcnt(6) lgkmcnt(0)
	s_barrier
	v_add_u32_e32 v240, s61, v238
	v_add_u32_e32 v241, s61, v239
	s_setprio 1
	s_add_i32 m0, s60, s62
	v_mfma_f32_16x16x32_bf16 v[2:5], v[210:213], v[178:181], v[2:5]
	global_load_lds_dwordx4 v226, s[54:55]
	v_mfma_f32_16x16x32_bf16 v[6:9], v[214:217], v[178:181], v[6:9]
	global_load_lds_dwordx4 v226, s[54:55] offset:1024
	v_mfma_f32_16x16x32_bf16 v[10:13], v[218:221], v[178:181], v[10:13]
	global_load_lds_dwordx4 v226, s[54:55] offset:2048
	v_mfma_f32_16x16x32_bf16 v[14:17], v[222:225], v[178:181], v[14:17]
	global_load_lds_dwordx4 v226, s[54:55] offset:3072
	s_add_i32 m0, s60, s63
	v_mfma_f32_16x16x32_bf16 v[18:21], v[210:213], v[182:185], v[18:21]
	global_load_lds_dwordx4 v230, s[56:57]
	v_mfma_f32_16x16x32_bf16 v[22:25], v[214:217], v[182:185], v[22:25]
	global_load_lds_dwordx4 v231, s[56:57] offset:1024
	v_mfma_f32_16x16x32_bf16 v[26:29], v[218:221], v[182:185], v[26:29]
	v_mfma_f32_16x16x32_bf16 v[30:33], v[222:225], v[182:185], v[30:33]
	v_mfma_f32_16x16x32_bf16 v[34:37], v[210:213], v[186:189], v[34:37]
	ds_read_b128 v[162:165], v241 offset:0
	v_mfma_f32_16x16x32_bf16 v[38:41], v[214:217], v[186:189], v[38:41]
	ds_read_b128 v[166:169], v241 offset:256
	v_mfma_f32_16x16x32_bf16 v[42:45], v[218:221], v[186:189], v[42:45]
	ds_read_b128 v[170:173], v241 offset:2048
	v_mfma_f32_16x16x32_bf16 v[46:49], v[222:225], v[186:189], v[46:49]
	ds_read_b128 v[174:177], v241 offset:2304
	v_mfma_f32_16x16x32_bf16 v[50:53], v[210:213], v[190:193], v[50:53]
	ds_read_b128 v[130:133], v240 offset:0
	v_mfma_f32_16x16x32_bf16 v[54:57], v[214:217], v[190:193], v[54:57]
	ds_read_b128 v[134:137], v240 offset:1024
	v_mfma_f32_16x16x32_bf16 v[58:61], v[218:221], v[190:193], v[58:61]
	ds_read_b128 v[138:141], v240 offset:2048
	v_mfma_f32_16x16x32_bf16 v[62:65], v[222:225], v[190:193], v[62:65]
	ds_read_b128 v[142:145], v240 offset:3072
	v_mfma_f32_16x16x32_bf16 v[66:69], v[210:213], v[194:197], v[66:69]
	ds_read_b128 v[146:149], v240 offset:4096
	v_mfma_f32_16x16x32_bf16 v[70:73], v[214:217], v[194:197], v[70:73]
	ds_read_b128 v[150:153], v240 offset:5120
	v_mfma_f32_16x16x32_bf16 v[74:77], v[218:221], v[194:197], v[74:77]
	ds_read_b128 v[154:157], v240 offset:6144
	v_mfma_f32_16x16x32_bf16 v[78:81], v[222:225], v[194:197], v[78:81]
	ds_read_b128 v[158:161], v240 offset:7168
	v_mfma_f32_16x16x32_bf16 v[82:85], v[210:213], v[198:201], v[82:85]
	v_mfma_f32_16x16x32_bf16 v[86:89], v[214:217], v[198:201], v[86:89]
	v_mfma_f32_16x16x32_bf16 v[90:93], v[218:221], v[198:201], v[90:93]
	v_mfma_f32_16x16x32_bf16 v[94:97], v[222:225], v[198:201], v[94:97]
	v_mfma_f32_16x16x32_bf16 v[98:101], v[210:213], v[202:205], v[98:101]
	v_mfma_f32_16x16x32_bf16 v[102:105], v[214:217], v[202:205], v[102:105]
	v_mfma_f32_16x16x32_bf16 v[106:109], v[218:221], v[202:205], v[106:109]
	v_mfma_f32_16x16x32_bf16 v[110:113], v[222:225], v[202:205], v[110:113]
	v_mfma_f32_16x16x32_bf16 v[114:117], v[210:213], v[206:209], v[114:117]
	v_mfma_f32_16x16x32_bf16 v[118:121], v[214:217], v[206:209], v[118:121]
	v_mfma_f32_16x16x32_bf16 v[122:125], v[218:221], v[206:209], v[122:125]
	v_mfma_f32_16x16x32_bf16 v[126:129], v[222:225], v[206:209], v[126:129]
	s_setprio 0
	s_add_i32 s60, s60, 0x6000
	s_cmp_eq_u32 s60, 0x12000
	s_cselect_b32 s60, 0, s60
	s_add_u32 s54, s54, s72
	s_addc_u32 s55, s55, 0
	s_add_u32 s56, s56, s73
	s_addc_u32 s57, s57, 0
	s_add_i32 s61, s61, 0x6000
	s_cmp_eq_u32 s61, 0x12000
	s_cselect_b32 s61, 0, s61
	s_branch .Lpj_epi

.Lpj_tail_last:
	s_waitcnt vmcnt(6) lgkmcnt(0)
	s_barrier
	v_add_u32_e32 v240, s61, v238
	v_add_u32_e32 v241, s61, v239
	s_setprio 1
	s_add_i32 m0, s60, s62
	v_mfma_f32_16x16x32_bf16 v[2:5], v[162:165], v[130:133], v[2:5]
	global_load_lds_dwordx4 v226, s[54:55]
	v_mfma_f32_16x16x32_bf16 v[6:9], v[166:169], v[130:133], v[6:9]
	global_load_lds_dwordx4 v226, s[54:55] offset:1024
	v_mfma_f32_16x16x32_bf16 v[10:13], v[170:173], v[130:133], v[10:13]
	global_load_lds_dwordx4 v226, s[54:55] offset:2048
	v_mfma_f32_16x16x32_bf16 v[14:17], v[174:177], v[130:133], v[14:17]
	global_load_lds_dwordx4 v226, s[54:55] offset:3072
	s_add_i32 m0, s60, s63
	v_mfma_f32_16x16x32_bf16 v[18:21], v[162:165], v[134:137], v[18:21]
	global_load_lds_dwordx4 v230, s[56:57]
	v_mfma_f32_16x16x32_bf16 v[22:25], v[166:169], v[134:137], v[22:25]
	global_load_lds_dwordx4 v231, s[56:57] offset:1024
	v_mfma_f32_16x16x32_bf16 v[26:29], v[170:173], v[134:137], v[26:29]
	v_mfma_f32_16x16x32_bf16 v[30:33], v[174:177], v[134:137], v[30:33]
	v_mfma_f32_16x16x32_bf16 v[34:37], v[162:165], v[138:141], v[34:37]
	ds_read_b128 v[210:213], v241 offset:0
	v_mfma_f32_16x16x32_bf16 v[38:41], v[166:169], v[138:141], v[38:41]
	ds_read_b128 v[214:217], v241 offset:256
	v_mfma_f32_16x16x32_bf16 v[42:45], v[170:173], v[138:141], v[42:45]
	ds_read_b128 v[218:221], v241 offset:2048
	v_mfma_f32_16x16x32_bf16 v[46:49], v[174:177], v[138:141], v[46:49]
	ds_read_b128 v[222:225], v241 offset:2304
	v_mfma_f32_16x16x32_bf16 v[50:53], v[162:165], v[142:145], v[50:53]
	ds_read_b128 v[178:181], v240 offset:0
	v_mfma_f32_16x16x32_bf16 v[54:57], v[166:169], v[142:145], v[54:57]
	ds_read_b128 v[182:185], v240 offset:1024
	v_mfma_f32_16x16x32_bf16 v[58:61], v[170:173], v[142:145], v[58:61]
	ds_read_b128 v[186:189], v240 offset:2048
	v_mfma_f32_16x16x32_bf16 v[62:65], v[174:177], v[142:145], v[62:65]
	ds_read_b128 v[190:193], v240 offset:3072
	v_mfma_f32_16x16x32_bf16 v[66:69], v[162:165], v[146:149], v[66:69]
	ds_read_b128 v[194:197], v240 offset:4096
	v_mfma_f32_16x16x32_bf16 v[70:73], v[166:169], v[146:149], v[70:73]
	ds_read_b128 v[198:201], v240 offset:5120
	v_mfma_f32_16x16x32_bf16 v[74:77], v[170:173], v[146:149], v[74:77]
	ds_read_b128 v[202:205], v240 offset:6144
	v_mfma_f32_16x16x32_bf16 v[78:81], v[174:177], v[146:149], v[78:81]
	ds_read_b128 v[206:209], v240 offset:7168
	v_mfma_f32_16x16x32_bf16 v[82:85], v[162:165], v[150:153], v[82:85]
	v_mfma_f32_16x16x32_bf16 v[86:89], v[166:169], v[150:153], v[86:89]
	v_mfma_f32_16x16x32_bf16 v[90:93], v[170:173], v[150:153], v[90:93]
	v_mfma_f32_16x16x32_bf16 v[94:97], v[174:177], v[150:153], v[94:97]
	v_mfma_f32_16x16x32_bf16 v[98:101], v[162:165], v[154:157], v[98:101]
	v_mfma_f32_16x16x32_bf16 v[102:105], v[166:169], v[154:157], v[102:105]
	v_mfma_f32_16x16x32_bf16 v[106:109], v[170:173], v[154:157], v[106:109]
	v_mfma_f32_16x16x32_bf16 v[110:113], v[174:177], v[154:157], v[110:113]
	v_mfma_f32_16x16x32_bf16 v[114:117], v[162:165], v[158:161], v[114:117]
	v_mfma_f32_16x16x32_bf16 v[118:121], v[166:169], v[158:161], v[118:121]
	v_mfma_f32_16x16x32_bf16 v[122:125], v[170:173], v[158:161], v[122:125]
	v_mfma_f32_16x16x32_bf16 v[126:129], v[174:177], v[158:161], v[126:129]
	s_setprio 0
	s_add_i32 s60, s60, 0x6000
	s_cmp_eq_u32 s60, 0x12000
	s_cselect_b32 s60, 0, s60
	s_add_u32 s54, s54, s72
	s_addc_u32 s55, s55, 0
	s_add_u32 s56, s56, s73
	s_addc_u32 s57, s57, 0
	s_add_i32 s61, s61, 0x6000
	s_cmp_eq_u32 s61, 0x12000
	s_cselect_b32 s61, 0, s61
	s_waitcnt vmcnt(6) lgkmcnt(0)
	s_barrier
	v_add_u32_e32 v240, s61, v238
	v_add_u32_e32 v241, s61, v239
	s_setprio 1
	v_mfma_f32_16x16x32_bf16 v[2:5], v[210:213], v[178:181], v[2:5]
	v_mfma_f32_16x16x32_bf16 v[6:9], v[214:217], v[178:181], v[6:9]
	v_mfma_f32_16x16x32_bf16 v[10:13], v[218:221], v[178:181], v[10:13]
	v_mfma_f32_16x16x32_bf16 v[14:17], v[222:225], v[178:181], v[14:17]
	v_mfma_f32_16x16x32_bf16 v[18:21], v[210:213], v[182:185], v[18:21]
	v_mfma_f32_16x16x32_bf16 v[22:25], v[214:217], v[182:185], v[22:25]
	v_mfma_f32_16x16x32_bf16 v[26:29], v[218:221], v[182:185], v[26:29]
	v_mfma_f32_16x16x32_bf16 v[30:33], v[222:225], v[182:185], v[30:33]
	v_mfma_f32_16x16x32_bf16 v[34:37], v[210:213], v[186:189], v[34:37]
	ds_read_b128 v[162:165], v241 offset:0
	v_mfma_f32_16x16x32_bf16 v[38:41], v[214:217], v[186:189], v[38:41]
	ds_read_b128 v[166:169], v241 offset:256
	v_mfma_f32_16x16x32_bf16 v[42:45], v[218:221], v[186:189], v[42:45]
	ds_read_b128 v[170:173], v241 offset:2048
	v_mfma_f32_16x16x32_bf16 v[46:49], v[222:225], v[186:189], v[46:49]
	ds_read_b128 v[174:177], v241 offset:2304
	v_mfma_f32_16x16x32_bf16 v[50:53], v[210:213], v[190:193], v[50:53]
	ds_read_b128 v[130:133], v240 offset:0
	v_mfma_f32_16x16x32_bf16 v[54:57], v[214:217], v[190:193], v[54:57]
	ds_read_b128 v[134:137], v240 offset:1024
	v_mfma_f32_16x16x32_bf16 v[58:61], v[218:221], v[190:193], v[58:61]
	ds_read_b128 v[138:141], v240 offset:2048
	v_mfma_f32_16x16x32_bf16 v[62:65], v[222:225], v[190:193], v[62:65]
	ds_read_b128 v[142:145], v240 offset:3072
	v_mfma_f32_16x16x32_bf16 v[66:69], v[210:213], v[194:197], v[66:69]
	ds_read_b128 v[146:149], v240 offset:4096
	v_mfma_f32_16x16x32_bf16 v[70:73], v[214:217], v[194:197], v[70:73]
	ds_read_b128 v[150:153], v240 offset:5120
	v_mfma_f32_16x16x32_bf16 v[74:77], v[218:221], v[194:197], v[74:77]
	ds_read_b128 v[154:157], v240 offset:6144
	v_mfma_f32_16x16x32_bf16 v[78:81], v[222:225], v[194:197], v[78:81]
	ds_read_b128 v[158:161], v240 offset:7168
	v_mfma_f32_16x16x32_bf16 v[82:85], v[210:213], v[198:201], v[82:85]
	v_mfma_f32_16x16x32_bf16 v[86:89], v[214:217], v[198:201], v[86:89]
	v_mfma_f32_16x16x32_bf16 v[90:93], v[218:221], v[198:201], v[90:93]
	v_mfma_f32_16x16x32_bf16 v[94:97], v[222:225], v[198:201], v[94:97]
	v_mfma_f32_16x16x32_bf16 v[98:101], v[210:213], v[202:205], v[98:101]
	v_mfma_f32_16x16x32_bf16 v[102:105], v[214:217], v[202:205], v[102:105]
	v_mfma_f32_16x16x32_bf16 v[106:109], v[218:221], v[202:205], v[106:109]
	v_mfma_f32_16x16x32_bf16 v[110:113], v[222:225], v[202:205], v[110:113]
	v_mfma_f32_16x16x32_bf16 v[114:117], v[210:213], v[206:209], v[114:117]
	v_mfma_f32_16x16x32_bf16 v[118:121], v[214:217], v[206:209], v[118:121]
	v_mfma_f32_16x16x32_bf16 v[122:125], v[218:221], v[206:209], v[122:125]
	v_mfma_f32_16x16x32_bf16 v[126:129], v[222:225], v[206:209], v[126:129]
	s_setprio 0
	s_add_i32 s61, s61, 0x6000
	s_cmp_eq_u32 s61, 0x12000
	s_cselect_b32 s61, 0, s61
	s_waitcnt vmcnt(0) lgkmcnt(0)
	s_barrier
	v_add_u32_e32 v240, s61, v238
	v_add_u32_e32 v241, s61, v239
	s_setprio 1
	v_mfma_f32_16x16x32_bf16 v[2:5], v[162:165], v[130:133], v[2:5]
	v_mfma_f32_16x16x32_bf16 v[6:9], v[166:169], v[130:133], v[6:9]
	v_mfma_f32_16x16x32_bf16 v[10:13], v[170:173], v[130:133], v[10:13]
	v_mfma_f32_16x16x32_bf16 v[14:17], v[174:177], v[130:133], v[14:17]
	v_mfma_f32_16x16x32_bf16 v[18:21], v[162:165], v[134:137], v[18:21]
	v_mfma_f32_16x16x32_bf16 v[22:25], v[166:169], v[134:137], v[22:25]
	v_mfma_f32_16x16x32_bf16 v[26:29], v[170:173], v[134:137], v[26:29]
	v_mfma_f32_16x16x32_bf16 v[30:33], v[174:177], v[134:137], v[30:33]
	v_mfma_f32_16x16x32_bf16 v[34:37], v[162:165], v[138:141], v[34:37]
	ds_read_b128 v[210:213], v241 offset:0
	v_mfma_f32_16x16x32_bf16 v[38:41], v[166:169], v[138:141], v[38:41]
	ds_read_b128 v[214:217], v241 offset:256
	v_mfma_f32_16x16x32_bf16 v[42:45], v[170:173], v[138:141], v[42:45]
	ds_read_b128 v[218:221], v241 offset:2048
	v_mfma_f32_16x16x32_bf16 v[46:49], v[174:177], v[138:141], v[46:49]
	ds_read_b128 v[222:225], v241 offset:2304
	v_mfma_f32_16x16x32_bf16 v[50:53], v[162:165], v[142:145], v[50:53]
	ds_read_b128 v[178:181], v240 offset:0
	v_mfma_f32_16x16x32_bf16 v[54:57], v[166:169], v[142:145], v[54:57]
	ds_read_b128 v[182:185], v240 offset:1024
	v_mfma_f32_16x16x32_bf16 v[58:61], v[170:173], v[142:145], v[58:61]
	ds_read_b128 v[186:189], v240 offset:2048
	v_mfma_f32_16x16x32_bf16 v[62:65], v[174:177], v[142:145], v[62:65]
	ds_read_b128 v[190:193], v240 offset:3072
	v_mfma_f32_16x16x32_bf16 v[66:69], v[162:165], v[146:149], v[66:69]
	ds_read_b128 v[194:197], v240 offset:4096
	v_mfma_f32_16x16x32_bf16 v[70:73], v[166:169], v[146:149], v[70:73]
	ds_read_b128 v[198:201], v240 offset:5120
	v_mfma_f32_16x16x32_bf16 v[74:77], v[170:173], v[146:149], v[74:77]
	ds_read_b128 v[202:205], v240 offset:6144
	v_mfma_f32_16x16x32_bf16 v[78:81], v[174:177], v[146:149], v[78:81]
	ds_read_b128 v[206:209], v240 offset:7168
	v_mfma_f32_16x16x32_bf16 v[82:85], v[162:165], v[150:153], v[82:85]
	v_mfma_f32_16x16x32_bf16 v[86:89], v[166:169], v[150:153], v[86:89]
	v_mfma_f32_16x16x32_bf16 v[90:93], v[170:173], v[150:153], v[90:93]
	v_mfma_f32_16x16x32_bf16 v[94:97], v[174:177], v[150:153], v[94:97]
	v_mfma_f32_16x16x32_bf16 v[98:101], v[162:165], v[154:157], v[98:101]
	v_mfma_f32_16x16x32_bf16 v[102:105], v[166:169], v[154:157], v[102:105]
	v_mfma_f32_16x16x32_bf16 v[106:109], v[170:173], v[154:157], v[106:109]
	v_mfma_f32_16x16x32_bf16 v[110:113], v[174:177], v[154:157], v[110:113]
	v_mfma_f32_16x16x32_bf16 v[114:117], v[162:165], v[158:161], v[114:117]
	v_mfma_f32_16x16x32_bf16 v[118:121], v[166:169], v[158:161], v[118:121]
	v_mfma_f32_16x16x32_bf16 v[122:125], v[170:173], v[158:161], v[122:125]
	v_mfma_f32_16x16x32_bf16 v[126:129], v[174:177], v[158:161], v[126:129]
	s_setprio 0
	s_add_i32 s61, s61, 0x6000
	s_cmp_eq_u32 s61, 0x12000
	s_cselect_b32 s61, 0, s61
	s_waitcnt lgkmcnt(0)
	s_barrier
	s_setprio 1
	v_mfma_f32_16x16x32_bf16 v[2:5], v[210:213], v[178:181], v[2:5]
	v_mfma_f32_16x16x32_bf16 v[6:9], v[214:217], v[178:181], v[6:9]
	v_mfma_f32_16x16x32_bf16 v[10:13], v[218:221], v[178:181], v[10:13]
	v_mfma_f32_16x16x32_bf16 v[14:17], v[222:225], v[178:181], v[14:17]
	v_mfma_f32_16x16x32_bf16 v[18:21], v[210:213], v[182:185], v[18:21]
	v_mfma_f32_16x16x32_bf16 v[22:25], v[214:217], v[182:185], v[22:25]
	v_mfma_f32_16x16x32_bf16 v[26:29], v[218:221], v[182:185], v[26:29]
	v_mfma_f32_16x16x32_bf16 v[30:33], v[222:225], v[182:185], v[30:33]
	v_mfma_f32_16x16x32_bf16 v[34:37], v[210:213], v[186:189], v[34:37]
	v_mfma_f32_16x16x32_bf16 v[38:41], v[214:217], v[186:189], v[38:41]
	v_mfma_f32_16x16x32_bf16 v[42:45], v[218:221], v[186:189], v[42:45]
	v_mfma_f32_16x16x32_bf16 v[46:49], v[222:225], v[186:189], v[46:49]
	v_mfma_f32_16x16x32_bf16 v[50:53], v[210:213], v[190:193], v[50:53]
	v_mfma_f32_16x16x32_bf16 v[54:57], v[214:217], v[190:193], v[54:57]
	v_mfma_f32_16x16x32_bf16 v[58:61], v[218:221], v[190:193], v[58:61]
	v_mfma_f32_16x16x32_bf16 v[62:65], v[222:225], v[190:193], v[62:65]
	v_mfma_f32_16x16x32_bf16 v[66:69], v[210:213], v[194:197], v[66:69]
	v_mfma_f32_16x16x32_bf16 v[70:73], v[214:217], v[194:197], v[70:73]
	v_mfma_f32_16x16x32_bf16 v[74:77], v[218:221], v[194:197], v[74:77]
	v_mfma_f32_16x16x32_bf16 v[78:81], v[222:225], v[194:197], v[78:81]
	v_mfma_f32_16x16x32_bf16 v[82:85], v[210:213], v[198:201], v[82:85]
	v_mfma_f32_16x16x32_bf16 v[86:89], v[214:217], v[198:201], v[86:89]
	v_mfma_f32_16x16x32_bf16 v[90:93], v[218:221], v[198:201], v[90:93]
	v_mfma_f32_16x16x32_bf16 v[94:97], v[222:225], v[198:201], v[94:97]
	v_mfma_f32_16x16x32_bf16 v[98:101], v[210:213], v[202:205], v[98:101]
	v_mfma_f32_16x16x32_bf16 v[102:105], v[214:217], v[202:205], v[102:105]
	v_mfma_f32_16x16x32_bf16 v[106:109], v[218:221], v[202:205], v[106:109]
	v_mfma_f32_16x16x32_bf16 v[110:113], v[222:225], v[202:205], v[110:113]
	v_mfma_f32_16x16x32_bf16 v[114:117], v[210:213], v[206:209], v[114:117]
	v_mfma_f32_16x16x32_bf16 v[118:121], v[214:217], v[206:209], v[118:121]
	v_mfma_f32_16x16x32_bf16 v[122:125], v[218:221], v[206:209], v[122:125]
	v_mfma_f32_16x16x32_bf16 v[126:129], v[222:225], v[206:209], v[126:129]
	s_setprio 0

	.amdhsa_kernel _Z11mega_kernel6Params
		.amdhsa_group_segment_fixed_size 78864
		.amdhsa_private_segment_fixed_size 0
		.amdhsa_kernarg_size 568
		.amdhsa_user_sgpr_count 2
		.amdhsa_user_sgpr_dispatch_ptr 0
		.amdhsa_user_sgpr_queue_ptr 0
		.amdhsa_user_sgpr_kernarg_segment_ptr 1
		.amdhsa_user_sgpr_dispatch_id 0
		.amdhsa_user_sgpr_kernarg_preload_length 0
		.amdhsa_user_sgpr_kernarg_preload_offset 0
		.amdhsa_user_sgpr_private_segment_size 0
		.amdhsa_uses_dynamic_stack 0
		.amdhsa_enable_private_segment 0
		.amdhsa_system_sgpr_workgroup_id_x 1
		.amdhsa_system_sgpr_workgroup_id_y 0
		.amdhsa_system_sgpr_workgroup_id_z 0
		.amdhsa_system_sgpr_workgroup_info 0
		.amdhsa_system_vgpr_workitem_id 2
		.amdhsa_next_free_vgpr 248
		.amdhsa_next_free_sgpr 100
		.amdhsa_accum_offset 248
		.amdhsa_reserve_vcc 1
		.amdhsa_float_round_mode_32 0
		.amdhsa_float_round_mode_16_64 0
		.amdhsa_float_denorm_mode_32 3
		.amdhsa_float_denorm_mode_16_64 3
		.amdhsa_dx10_clamp 1
		.amdhsa_ieee_mode 1
		.amdhsa_fp16_overflow 0
		.amdhsa_tg_split 0
		.amdhsa_exception_fp_ieee_invalid_op 0
		.amdhsa_exception_fp_denorm_src 0
		.amdhsa_exception_fp_ieee_div_zero 0
		.amdhsa_exception_fp_ieee_overflow 0
		.amdhsa_exception_fp_ieee_underflow 0
		.amdhsa_exception_fp_ieee_inexact 0
		.amdhsa_exception_int_div_zero 0
	.end_amdhsa_kernel

amdhsa.kernels:
  - .agpr_count:     0
    .args:
      - .offset:         0
        .size:           312
        .value_kind:     by_value
      - .offset:         312
        .size:           4
        .value_kind:     hidden_block_count_x
      - .offset:         316
        .size:           4
        .value_kind:     hidden_block_count_y
      - .offset:         320
        .size:           4
        .value_kind:     hidden_block_count_z
      - .offset:         324
        .size:           2
        .value_kind:     hidden_group_size_x
      - .offset:         326
        .size:           2
        .value_kind:     hidden_group_size_y
      - .offset:         328
        .size:           2
        .value_kind:     hidden_group_size_z
      - .offset:         330
        .size:           2
        .value_kind:     hidden_remainder_x
      - .offset:         332
        .size:           2
        .value_kind:     hidden_remainder_y
      - .offset:         334
        .size:           2
        .value_kind:     hidden_remainder_z
      - .offset:         352
        .size:           8
        .value_kind:     hidden_global_offset_x
      - .offset:         360
        .size:           8
        .value_kind:     hidden_global_offset_y
      - .offset:         368
        .size:           8
        .value_kind:     hidden_global_offset_z
      - .offset:         376
        .size:           2
        .value_kind:     hidden_grid_dims
      - .offset:         400
        .size:           8
        .value_kind:     hidden_multigrid_sync_arg
    .group_segment_fixed_size: 78864
    .kernarg_segment_align: 8
    .kernarg_segment_size: 568
    .language:       OpenCL C
    .language_version:
      - 2
      - 0
    .max_flat_workgroup_size: 256
    .name:           _Z11mega_kernel6Params
    .private_segment_fixed_size: 0
    .sgpr_count:     106
    .sgpr_spill_count: 74
    .symbol:         _Z11mega_kernel6Params.kd
    .uniform_work_group_size: 1
    .uses_dynamic_stack: false
    .vgpr_count:     248
    .vgpr_spill_count: 0
    .wavefront_size: 64
